# gemm mainloop rewrite + out-proj epilogue gate-load hoist + MLA attention tile body pipelined (QK/softmax overlap, permlane32 max, DMA interleaved)
# speedup vs baseline: 1.0595x; 1.0282x over previous
.LBB0_77:
	s_or_b64 exec, exec, s[6:7]
	v_mov_b32_e32 v2, 0x2000
	v_mov_b32_e32 v3, 1
	s_waitcnt vmcnt(0)
	global_atomic_add v2, v3, s[8:9] offset:1024
	buffer_inv sc1
	s_waitcnt vmcnt(0)

.LBB0_141:
	s_or_b64 exec, exec, s[10:11]
	v_mov_b32_e32 v3, 0x2000
	v_mov_b32_e32 v5, 1
	s_waitcnt vmcnt(0)
	global_atomic_add v3, v5, s[6:7] offset:1024
	buffer_inv sc1
	s_waitcnt vmcnt(0)

.LBB0_150:
	s_ashr_i32 s4, s35, 31
	s_lshr_b32 s4, s4, 26
	s_add_i32 s4, s35, s4
	s_ashr_i32 s6, s4, 6
	s_and_b32 s4, s4, 0x3ffffc0
	s_sub_i32 s4, s35, s4
	s_mulk_i32 s4, 0xc0
	v_add_u32_e32 v2, s4, v1
	s_lshr_b32 s7, s4, 6
	s_lshl_b32 s5, s6, 7
	v_ashrrev_i32_e32 v3, 31, v2
	s_add_i32 s7, s7, s6
	v_lshlrev_b64 v[2:3], 11, v[2:3]
	v_or_b32_e32 v4, s5, v1
	s_lshl_b32 s6, s7, 6
	s_lshl_b32 s7, s7, 7
	v_ashrrev_i32_e32 v5, 31, v4
	v_lshl_add_u64 v[104:105], v[100:101], 0, v[2:3]
	s_and_b32 s14, s7, 0x780
	v_readfirstlane_b32 s7, v112
	v_lshlrev_b64 v[4:5], 11, v[4:5]
	v_lshl_add_u64 v[2:3], v[104:105], 0, s[14:15]
	s_mov_b32 m0, s7
	v_readfirstlane_b32 s7, v124
	v_lshl_add_u64 v[106:107], v[102:103], 0, v[4:5]
	s_waitcnt vmcnt(0)
	s_barrier
	s_load_dwordx2 s[66:67], s[0:1], 0x90
	s_load_dwordx2 s[68:69], s[0:1], 0xc0
	v_and_b32_e32 v201, 0x3ff, v0
	v_readfirstlane_b32 s80, v0
	v_and_b32_e32 v200, 31, v201
	v_bfe_u32 v214, v201, 1, 3
	v_bfe_u32 v213, v201, 5, 1
	v_xor_b32_e32 v214, v214, v213
	v_lshlrev_b32_e32 v214, 4, v214
	s_and_b32 s80, s80, 0x3ff
	s_lshr_b32 s83, s80, 6
	s_lshl_b32 s80, s80, 4
	s_lshr_b32 s84, s83, 1
	s_and_b32 s83, s83, 1
	s_mul_i32 s84, s84, 0x3000
	s_lshl_b32 s83, s83, 13
	s_add_u32 s83, s83, 0xc000
	v_lshlrev_b32_e32 v200, 7, v200
	v_or_b32_e32 v200, v200, v214
	v_add_u32_e32 v215, s84, v200
	v_add_u32_e32 v211, s83, v200
	v_xor_b32_e32 v214, 0x20, v215
	v_xor_b32_e32 v210, 0x20, v211
	v_xor_b32_e32 v213, 0x40, v215
	v_xor_b32_e32 v209, 0x40, v211
	v_xor_b32_e32 v212, 0x60, v215
	v_xor_b32_e32 v208, 0x60, v211
	v_bfe_u32 v200, v201, 4, 3
	v_and_b32_e32 v206, 7, v201
	v_xor_b32_e32 v200, v200, v206
	v_lshlrev_b32_e32 v200, 4, v200
	v_lshrrev_b32_e32 v206, 3, v201
	v_lshl_or_b32 v207, v206, 11, v200
	v_add_u32_e32 v206, 0x10000, v207
	v_add_u32_e32 v205, 0x20000, v207
	v_add_u32_e32 v204, 0x30000, v207
	v_add_u32_e32 v203, 0x40000, v207
	v_add_u32_e32 v202, 0x50000, v207
	s_lshr_b32 s83, s35, 6
	s_and_b32 s84, s35, 63
	s_mov_b32 s79, 0
	s_mul_i32 s84, s84, 0x60000
	s_lshl_b32 s83, s83, 18
	s_waitcnt lgkmcnt(0)
	s_add_u32 s66, s66, s84
	s_addc_u32 s67, s67, 0
	s_add_u32 s68, s68, s83
	s_addc_u32 s69, s69, 0
	s_add_u32 s83, s79, 0
	s_and_b32 s83, s83, 15
	s_lshl_b32 s83, s83, 7
	s_add_u32 s70, s66, s83
	s_addc_u32 s71, s67, 0
	s_add_u32 s72, s68, s83
	s_addc_u32 s73, s69, 0
	s_add_u32 s81, s80, 0x0
	s_add_u32 s82, s80, 0xc000
	s_add_u32 m0, s81, 0x0
	s_nop 0
	global_load_lds_dwordx4 v207, s[70:71]
	s_add_u32 m0, s81, 0x1000
	s_nop 0
	global_load_lds_dwordx4 v206, s[70:71]
	s_add_u32 m0, s81, 0x2000
	s_nop 0
	global_load_lds_dwordx4 v205, s[70:71]
	s_add_u32 m0, s81, 0x3000
	s_nop 0
	global_load_lds_dwordx4 v204, s[70:71]
	s_add_u32 m0, s81, 0x4000
	s_nop 0
	global_load_lds_dwordx4 v203, s[70:71]
	s_add_u32 m0, s81, 0x5000
	s_nop 0
	global_load_lds_dwordx4 v202, s[70:71]
	s_add_u32 m0, s82, 0x0
	s_nop 0
	global_load_lds_dwordx4 v207, s[72:73]
	s_add_u32 m0, s82, 0x1000
	s_nop 0
	global_load_lds_dwordx4 v206, s[72:73]
	s_add_u32 m0, s82, 0x2000
	s_nop 0
	global_load_lds_dwordx4 v205, s[72:73]
	s_add_u32 m0, s82, 0x3000
	s_nop 0
	global_load_lds_dwordx4 v204, s[72:73]
	s_add_u32 s83, s79, 1
	s_and_b32 s83, s83, 15
	s_lshl_b32 s83, s83, 7
	s_add_u32 s70, s66, s83
	s_addc_u32 s71, s67, 0
	s_add_u32 s72, s68, s83
	s_addc_u32 s73, s69, 0
	s_add_u32 s81, s80, 0x6000
	s_add_u32 s82, s80, 0x10000
	s_add_u32 m0, s81, 0x0
	s_nop 0
	global_load_lds_dwordx4 v207, s[70:71]
	s_add_u32 m0, s81, 0x1000
	s_nop 0
	global_load_lds_dwordx4 v206, s[70:71]
	s_add_u32 m0, s81, 0x2000
	s_nop 0
	global_load_lds_dwordx4 v205, s[70:71]
	s_add_u32 m0, s81, 0x3000
	s_nop 0
	global_load_lds_dwordx4 v204, s[70:71]
	s_add_u32 m0, s81, 0x4000
	s_nop 0
	global_load_lds_dwordx4 v203, s[70:71]
	s_add_u32 m0, s81, 0x5000
	s_nop 0
	global_load_lds_dwordx4 v202, s[70:71]
	s_add_u32 m0, s82, 0x0
	s_nop 0
	global_load_lds_dwordx4 v207, s[72:73]
	s_add_u32 m0, s82, 0x1000
	s_nop 0
	global_load_lds_dwordx4 v206, s[72:73]
	s_add_u32 m0, s82, 0x2000
	s_nop 0
	global_load_lds_dwordx4 v205, s[72:73]
	s_add_u32 m0, s82, 0x3000
	s_nop 0
	global_load_lds_dwordx4 v204, s[72:73]
	v_mov_b32_e32 v2, 0
	v_mov_b32_e32 v3, 0
	v_mov_b32_e32 v4, 0
	v_mov_b32_e32 v5, 0
	v_mov_b32_e32 v6, 0
	v_mov_b32_e32 v7, 0
	v_mov_b32_e32 v8, 0
	v_mov_b32_e32 v9, 0
	v_mov_b32_e32 v10, 0
	v_mov_b32_e32 v11, 0
	v_mov_b32_e32 v12, 0
	v_mov_b32_e32 v13, 0
	v_mov_b32_e32 v14, 0
	v_mov_b32_e32 v15, 0
	v_mov_b32_e32 v16, 0
	v_mov_b32_e32 v17, 0
	v_mov_b32_e32 v18, 0
	v_mov_b32_e32 v19, 0
	v_mov_b32_e32 v20, 0
	v_mov_b32_e32 v21, 0
	v_mov_b32_e32 v22, 0
	v_mov_b32_e32 v23, 0
	v_mov_b32_e32 v24, 0
	v_mov_b32_e32 v25, 0
	v_mov_b32_e32 v26, 0
	v_mov_b32_e32 v27, 0
	v_mov_b32_e32 v28, 0
	v_mov_b32_e32 v29, 0
	v_mov_b32_e32 v30, 0
	v_mov_b32_e32 v31, 0
	v_mov_b32_e32 v32, 0
	v_mov_b32_e32 v33, 0
	v_mov_b32_e32 v34, 0
	v_mov_b32_e32 v35, 0
	v_mov_b32_e32 v36, 0
	v_mov_b32_e32 v37, 0
	v_mov_b32_e32 v38, 0
	v_mov_b32_e32 v39, 0
	v_mov_b32_e32 v40, 0
	v_mov_b32_e32 v41, 0
	v_mov_b32_e32 v42, 0
	v_mov_b32_e32 v43, 0
	v_mov_b32_e32 v44, 0
	v_mov_b32_e32 v45, 0
	v_mov_b32_e32 v46, 0
	v_mov_b32_e32 v47, 0
	v_mov_b32_e32 v48, 0
	v_mov_b32_e32 v49, 0
	v_mov_b32_e32 v50, 0
	v_mov_b32_e32 v51, 0
	v_mov_b32_e32 v52, 0
	v_mov_b32_e32 v53, 0
	v_mov_b32_e32 v54, 0
	v_mov_b32_e32 v55, 0
	v_mov_b32_e32 v56, 0
	v_mov_b32_e32 v57, 0
	v_mov_b32_e32 v58, 0
	v_mov_b32_e32 v59, 0
	v_mov_b32_e32 v60, 0
	v_mov_b32_e32 v61, 0
	v_mov_b32_e32 v62, 0
	v_mov_b32_e32 v63, 0
	v_mov_b32_e32 v64, 0
	v_mov_b32_e32 v65, 0
	v_mov_b32_e32 v66, 0
	v_mov_b32_e32 v67, 0
	v_mov_b32_e32 v68, 0
	v_mov_b32_e32 v69, 0
	v_mov_b32_e32 v70, 0
	v_mov_b32_e32 v71, 0
	v_mov_b32_e32 v72, 0
	v_mov_b32_e32 v73, 0
	v_mov_b32_e32 v74, 0
	v_mov_b32_e32 v75, 0
	v_mov_b32_e32 v76, 0
	v_mov_b32_e32 v77, 0
	v_mov_b32_e32 v78, 0
	v_mov_b32_e32 v79, 0
	v_mov_b32_e32 v80, 0
	v_mov_b32_e32 v81, 0
	v_mov_b32_e32 v82, 0
	v_mov_b32_e32 v83, 0
	v_mov_b32_e32 v84, 0
	v_mov_b32_e32 v85, 0
	v_mov_b32_e32 v86, 0
	v_mov_b32_e32 v87, 0
	v_mov_b32_e32 v88, 0
	v_mov_b32_e32 v89, 0
	v_mov_b32_e32 v90, 0
	v_mov_b32_e32 v91, 0
	v_mov_b32_e32 v92, 0
	v_mov_b32_e32 v93, 0
	v_mov_b32_e32 v94, 0
	v_mov_b32_e32 v95, 0
	v_mov_b32_e32 v96, 0
	v_mov_b32_e32 v97, 0
	s_waitcnt vmcnt(10)
	s_barrier
	ds_read_b128 v[240:243], v211 offset:0
	ds_read_b128 v[252:255], v215 offset:0
	ds_read_b128 v[236:239], v211 offset:4096
	ds_read_b128 v[248:251], v215 offset:4096
	ds_read_b128 v[244:247], v215 offset:8192
	s_mov_b32 s78, 0
.Lgm_ph2_loop:
	s_waitcnt lgkmcnt(1)
	v_mfma_f32_32x32x16_bf16 v[82:97], v[240:243], v[252:255], v[82:97]
	ds_read_b128 v[220:223], v210 offset:0
	v_mfma_f32_32x32x16_bf16 v[66:81], v[236:239], v[252:255], v[66:81]
	ds_read_b128 v[232:235], v214 offset:0
	v_mfma_f32_32x32x16_bf16 v[50:65], v[240:243], v[248:251], v[50:65]
	ds_read_b128 v[216:219], v210 offset:4096
	v_mfma_f32_32x32x16_bf16 v[34:49], v[236:239], v[248:251], v[34:49]
	ds_read_b128 v[228:231], v214 offset:4096
	s_waitcnt lgkmcnt(4)
	v_mfma_f32_32x32x16_bf16 v[18:33], v[240:243], v[244:247], v[18:33]
	ds_read_b128 v[224:227], v214 offset:8192
	v_mfma_f32_32x32x16_bf16 v[2:17], v[236:239], v[244:247], v[2:17]
	s_waitcnt lgkmcnt(1)
	v_mfma_f32_32x32x16_bf16 v[82:97], v[220:223], v[232:235], v[82:97]
	ds_read_b128 v[240:243], v209 offset:0
	v_mfma_f32_32x32x16_bf16 v[66:81], v[216:219], v[232:235], v[66:81]
	ds_read_b128 v[252:255], v213 offset:0
	v_mfma_f32_32x32x16_bf16 v[50:65], v[220:223], v[228:231], v[50:65]
	ds_read_b128 v[236:239], v209 offset:4096
	v_mfma_f32_32x32x16_bf16 v[34:49], v[216:219], v[228:231], v[34:49]
	ds_read_b128 v[248:251], v213 offset:4096
	s_waitcnt lgkmcnt(4)
	v_mfma_f32_32x32x16_bf16 v[18:33], v[220:223], v[224:227], v[18:33]
	ds_read_b128 v[244:247], v213 offset:8192
	v_mfma_f32_32x32x16_bf16 v[2:17], v[216:219], v[224:227], v[2:17]
	s_waitcnt lgkmcnt(1)
	v_mfma_f32_32x32x16_bf16 v[82:97], v[240:243], v[252:255], v[82:97]
	ds_read_b128 v[220:223], v208 offset:0
	s_add_u32 s83, s79, s78
	s_add_u32 s83, s83, 2
	s_and_b32 s83, s83, 15
	v_mfma_f32_32x32x16_bf16 v[66:81], v[236:239], v[252:255], v[66:81]
	ds_read_b128 v[232:235], v212 offset:0
	s_lshl_b32 s83, s83, 7
	s_add_u32 s70, s66, s83
	v_mfma_f32_32x32x16_bf16 v[50:65], v[240:243], v[248:251], v[50:65]
	ds_read_b128 v[216:219], v208 offset:4096
	s_addc_u32 s71, s67, 0
	s_add_u32 s72, s68, s83
	v_mfma_f32_32x32x16_bf16 v[34:49], v[236:239], v[248:251], v[34:49]
	ds_read_b128 v[228:231], v212 offset:4096
	s_addc_u32 s73, s69, 0
	s_add_u32 s81, s80, 0x0
	s_add_u32 s82, s80, 0xc000
	s_waitcnt lgkmcnt(4)
	v_mfma_f32_32x32x16_bf16 v[18:33], v[240:243], v[244:247], v[18:33]
	ds_read_b128 v[224:227], v212 offset:8192
	v_mfma_f32_32x32x16_bf16 v[2:17], v[236:239], v[244:247], v[2:17]
	s_waitcnt vmcnt(0) lgkmcnt(0)
	s_barrier
	v_mfma_f32_32x32x16_bf16 v[82:97], v[220:223], v[232:235], v[82:97]
	s_add_u32 m0, s81, 0x0
	ds_read_b128 v[240:243], v211 offset:16384
	global_load_lds_dwordx4 v207, s[70:71]
	s_add_u32 m0, s81, 0x1000
	s_nop 0
	global_load_lds_dwordx4 v206, s[70:71]
	v_mfma_f32_32x32x16_bf16 v[66:81], v[216:219], v[232:235], v[66:81]
	s_add_u32 m0, s81, 0x2000
	ds_read_b128 v[252:255], v215 offset:24576
	global_load_lds_dwordx4 v205, s[70:71]
	s_add_u32 m0, s81, 0x3000
	s_nop 0
	global_load_lds_dwordx4 v204, s[70:71]
	v_mfma_f32_32x32x16_bf16 v[50:65], v[220:223], v[228:231], v[50:65]
	s_add_u32 m0, s81, 0x4000
	ds_read_b128 v[236:239], v211 offset:20480
	global_load_lds_dwordx4 v203, s[70:71]
	s_add_u32 m0, s81, 0x5000
	s_nop 0
	global_load_lds_dwordx4 v202, s[70:71]
	v_mfma_f32_32x32x16_bf16 v[34:49], v[216:219], v[228:231], v[34:49]
	s_add_u32 m0, s82, 0x0
	ds_read_b128 v[248:251], v215 offset:28672
	global_load_lds_dwordx4 v207, s[72:73]
	s_add_u32 m0, s82, 0x1000
	s_nop 0
	global_load_lds_dwordx4 v206, s[72:73]
	v_mfma_f32_32x32x16_bf16 v[18:33], v[220:223], v[224:227], v[18:33]
	s_add_u32 m0, s82, 0x2000
	ds_read_b128 v[244:247], v215 offset:32768
	global_load_lds_dwordx4 v205, s[72:73]
	s_add_u32 m0, s82, 0x3000
	s_nop 0
	global_load_lds_dwordx4 v204, s[72:73]
	v_mfma_f32_32x32x16_bf16 v[2:17], v[216:219], v[224:227], v[2:17]
	s_waitcnt lgkmcnt(1)
	v_mfma_f32_32x32x16_bf16 v[82:97], v[240:243], v[252:255], v[82:97]
	ds_read_b128 v[220:223], v210 offset:16384
	v_mfma_f32_32x32x16_bf16 v[66:81], v[236:239], v[252:255], v[66:81]
	ds_read_b128 v[232:235], v214 offset:24576
	v_mfma_f32_32x32x16_bf16 v[50:65], v[240:243], v[248:251], v[50:65]
	ds_read_b128 v[216:219], v210 offset:20480
	v_mfma_f32_32x32x16_bf16 v[34:49], v[236:239], v[248:251], v[34:49]
	ds_read_b128 v[228:231], v214 offset:28672
	s_waitcnt lgkmcnt(4)
	v_mfma_f32_32x32x16_bf16 v[18:33], v[240:243], v[244:247], v[18:33]
	ds_read_b128 v[224:227], v214 offset:32768
	v_mfma_f32_32x32x16_bf16 v[2:17], v[236:239], v[244:247], v[2:17]
	s_waitcnt lgkmcnt(1)
	v_mfma_f32_32x32x16_bf16 v[82:97], v[220:223], v[232:235], v[82:97]
	ds_read_b128 v[240:243], v209 offset:16384
	v_mfma_f32_32x32x16_bf16 v[66:81], v[216:219], v[232:235], v[66:81]
	ds_read_b128 v[252:255], v213 offset:24576
	v_mfma_f32_32x32x16_bf16 v[50:65], v[220:223], v[228:231], v[50:65]
	ds_read_b128 v[236:239], v209 offset:20480
	v_mfma_f32_32x32x16_bf16 v[34:49], v[216:219], v[228:231], v[34:49]
	ds_read_b128 v[248:251], v213 offset:28672
	s_waitcnt lgkmcnt(4)
	v_mfma_f32_32x32x16_bf16 v[18:33], v[220:223], v[224:227], v[18:33]
	ds_read_b128 v[244:247], v213 offset:32768
	v_mfma_f32_32x32x16_bf16 v[2:17], v[216:219], v[224:227], v[2:17]
	s_waitcnt lgkmcnt(1)
	v_mfma_f32_32x32x16_bf16 v[82:97], v[240:243], v[252:255], v[82:97]
	ds_read_b128 v[220:223], v208 offset:16384
	s_add_u32 s83, s79, s78
	s_add_u32 s83, s83, 3
	s_and_b32 s83, s83, 15
	v_mfma_f32_32x32x16_bf16 v[66:81], v[236:239], v[252:255], v[66:81]
	ds_read_b128 v[232:235], v212 offset:24576
	s_lshl_b32 s83, s83, 7
	s_add_u32 s70, s66, s83
	v_mfma_f32_32x32x16_bf16 v[50:65], v[240:243], v[248:251], v[50:65]
	ds_read_b128 v[216:219], v208 offset:20480
	s_addc_u32 s71, s67, 0
	s_add_u32 s72, s68, s83
	v_mfma_f32_32x32x16_bf16 v[34:49], v[236:239], v[248:251], v[34:49]
	ds_read_b128 v[228:231], v212 offset:28672
	s_addc_u32 s73, s69, 0
	s_add_u32 s81, s80, 0x6000
	s_add_u32 s82, s80, 0x10000
	s_waitcnt lgkmcnt(4)
	v_mfma_f32_32x32x16_bf16 v[18:33], v[240:243], v[244:247], v[18:33]
	ds_read_b128 v[224:227], v212 offset:32768
	v_mfma_f32_32x32x16_bf16 v[2:17], v[236:239], v[244:247], v[2:17]
	s_waitcnt vmcnt(0) lgkmcnt(0)
	s_barrier
	v_mfma_f32_32x32x16_bf16 v[82:97], v[220:223], v[232:235], v[82:97]
	s_add_u32 m0, s81, 0x0
	ds_read_b128 v[240:243], v211 offset:0
	global_load_lds_dwordx4 v207, s[70:71]
	s_add_u32 m0, s81, 0x1000
	s_nop 0
	global_load_lds_dwordx4 v206, s[70:71]
	v_mfma_f32_32x32x16_bf16 v[66:81], v[216:219], v[232:235], v[66:81]
	s_add_u32 m0, s81, 0x2000
	ds_read_b128 v[252:255], v215 offset:0
	global_load_lds_dwordx4 v205, s[70:71]
	s_add_u32 m0, s81, 0x3000
	s_nop 0
	global_load_lds_dwordx4 v204, s[70:71]
	v_mfma_f32_32x32x16_bf16 v[50:65], v[220:223], v[228:231], v[50:65]
	s_add_u32 m0, s81, 0x4000
	ds_read_b128 v[236:239], v211 offset:4096
	global_load_lds_dwordx4 v203, s[70:71]
	s_add_u32 m0, s81, 0x5000
	s_nop 0
	global_load_lds_dwordx4 v202, s[70:71]
	v_mfma_f32_32x32x16_bf16 v[34:49], v[216:219], v[228:231], v[34:49]
	s_add_u32 m0, s82, 0x0
	ds_read_b128 v[248:251], v215 offset:4096
	global_load_lds_dwordx4 v207, s[72:73]
	s_add_u32 m0, s82, 0x1000
	s_nop 0
	global_load_lds_dwordx4 v206, s[72:73]
	v_mfma_f32_32x32x16_bf16 v[18:33], v[220:223], v[224:227], v[18:33]
	s_add_u32 m0, s82, 0x2000
	ds_read_b128 v[244:247], v215 offset:8192
	global_load_lds_dwordx4 v205, s[72:73]
	s_add_u32 m0, s82, 0x3000
	s_nop 0
	global_load_lds_dwordx4 v204, s[72:73]
	v_mfma_f32_32x32x16_bf16 v[2:17], v[216:219], v[224:227], v[2:17]
	s_add_u32 s78, s78, 2
	s_cmp_lt_u32 s78, 14
	s_cbranch_scc1 .Lgm_ph2_loop
	s_waitcnt lgkmcnt(1)
	v_mfma_f32_32x32x16_bf16 v[82:97], v[240:243], v[252:255], v[82:97]
	ds_read_b128 v[220:223], v210 offset:0
	v_mfma_f32_32x32x16_bf16 v[66:81], v[236:239], v[252:255], v[66:81]
	ds_read_b128 v[232:235], v214 offset:0
	v_mfma_f32_32x32x16_bf16 v[50:65], v[240:243], v[248:251], v[50:65]
	ds_read_b128 v[216:219], v210 offset:4096
	v_mfma_f32_32x32x16_bf16 v[34:49], v[236:239], v[248:251], v[34:49]
	ds_read_b128 v[228:231], v214 offset:4096
	s_waitcnt lgkmcnt(4)
	v_mfma_f32_32x32x16_bf16 v[18:33], v[240:243], v[244:247], v[18:33]
	ds_read_b128 v[224:227], v214 offset:8192
	v_mfma_f32_32x32x16_bf16 v[2:17], v[236:239], v[244:247], v[2:17]
	s_waitcnt lgkmcnt(1)
	v_mfma_f32_32x32x16_bf16 v[82:97], v[220:223], v[232:235], v[82:97]
	ds_read_b128 v[240:243], v209 offset:0
	v_mfma_f32_32x32x16_bf16 v[66:81], v[216:219], v[232:235], v[66:81]
	ds_read_b128 v[252:255], v213 offset:0
	v_mfma_f32_32x32x16_bf16 v[50:65], v[220:223], v[228:231], v[50:65]
	ds_read_b128 v[236:239], v209 offset:4096
	v_mfma_f32_32x32x16_bf16 v[34:49], v[216:219], v[228:231], v[34:49]
	ds_read_b128 v[248:251], v213 offset:4096
	s_waitcnt lgkmcnt(4)
	v_mfma_f32_32x32x16_bf16 v[18:33], v[220:223], v[224:227], v[18:33]
	ds_read_b128 v[244:247], v213 offset:8192
	v_mfma_f32_32x32x16_bf16 v[2:17], v[216:219], v[224:227], v[2:17]
	s_waitcnt lgkmcnt(1)
	v_mfma_f32_32x32x16_bf16 v[82:97], v[240:243], v[252:255], v[82:97]
	ds_read_b128 v[220:223], v208 offset:0
	v_mfma_f32_32x32x16_bf16 v[66:81], v[236:239], v[252:255], v[66:81]
	ds_read_b128 v[232:235], v212 offset:0
	v_mfma_f32_32x32x16_bf16 v[50:65], v[240:243], v[248:251], v[50:65]
	ds_read_b128 v[216:219], v208 offset:4096
	v_mfma_f32_32x32x16_bf16 v[34:49], v[236:239], v[248:251], v[34:49]
	ds_read_b128 v[228:231], v212 offset:4096
	s_waitcnt lgkmcnt(4)
	v_mfma_f32_32x32x16_bf16 v[18:33], v[240:243], v[244:247], v[18:33]
	ds_read_b128 v[224:227], v212 offset:8192
	v_mfma_f32_32x32x16_bf16 v[2:17], v[236:239], v[244:247], v[2:17]
	s_waitcnt vmcnt(0) lgkmcnt(0)
	s_barrier
	v_mfma_f32_32x32x16_bf16 v[82:97], v[220:223], v[232:235], v[82:97]
	ds_read_b128 v[240:243], v211 offset:16384
	v_mfma_f32_32x32x16_bf16 v[66:81], v[216:219], v[232:235], v[66:81]
	ds_read_b128 v[252:255], v215 offset:24576
	v_mfma_f32_32x32x16_bf16 v[50:65], v[220:223], v[228:231], v[50:65]
	ds_read_b128 v[236:239], v211 offset:20480
	v_mfma_f32_32x32x16_bf16 v[34:49], v[216:219], v[228:231], v[34:49]
	ds_read_b128 v[248:251], v215 offset:28672
	v_mfma_f32_32x32x16_bf16 v[18:33], v[220:223], v[224:227], v[18:33]
	ds_read_b128 v[244:247], v215 offset:32768
	v_mfma_f32_32x32x16_bf16 v[2:17], v[216:219], v[224:227], v[2:17]
	s_waitcnt lgkmcnt(1)
	v_mfma_f32_32x32x16_bf16 v[82:97], v[240:243], v[252:255], v[82:97]
	ds_read_b128 v[220:223], v210 offset:16384
	v_mfma_f32_32x32x16_bf16 v[66:81], v[236:239], v[252:255], v[66:81]
	ds_read_b128 v[232:235], v214 offset:24576
	v_mfma_f32_32x32x16_bf16 v[50:65], v[240:243], v[248:251], v[50:65]
	ds_read_b128 v[216:219], v210 offset:20480
	v_mfma_f32_32x32x16_bf16 v[34:49], v[236:239], v[248:251], v[34:49]
	ds_read_b128 v[228:231], v214 offset:28672
	s_waitcnt lgkmcnt(4)
	v_mfma_f32_32x32x16_bf16 v[18:33], v[240:243], v[244:247], v[18:33]
	ds_read_b128 v[224:227], v214 offset:32768
	v_mfma_f32_32x32x16_bf16 v[2:17], v[236:239], v[244:247], v[2:17]
	s_waitcnt lgkmcnt(1)
	v_mfma_f32_32x32x16_bf16 v[82:97], v[220:223], v[232:235], v[82:97]
	ds_read_b128 v[240:243], v209 offset:16384
	v_mfma_f32_32x32x16_bf16 v[66:81], v[216:219], v[232:235], v[66:81]
	ds_read_b128 v[252:255], v213 offset:24576
	v_mfma_f32_32x32x16_bf16 v[50:65], v[220:223], v[228:231], v[50:65]
	ds_read_b128 v[236:239], v209 offset:20480
	v_mfma_f32_32x32x16_bf16 v[34:49], v[216:219], v[228:231], v[34:49]
	ds_read_b128 v[248:251], v213 offset:28672
	s_waitcnt lgkmcnt(4)
	v_mfma_f32_32x32x16_bf16 v[18:33], v[220:223], v[224:227], v[18:33]
	ds_read_b128 v[244:247], v213 offset:32768
	v_mfma_f32_32x32x16_bf16 v[2:17], v[216:219], v[224:227], v[2:17]
	s_waitcnt lgkmcnt(1)
	v_mfma_f32_32x32x16_bf16 v[82:97], v[240:243], v[252:255], v[82:97]
	ds_read_b128 v[220:223], v208 offset:16384
	v_mfma_f32_32x32x16_bf16 v[66:81], v[236:239], v[252:255], v[66:81]
	ds_read_b128 v[232:235], v212 offset:24576
	v_mfma_f32_32x32x16_bf16 v[50:65], v[240:243], v[248:251], v[50:65]
	ds_read_b128 v[216:219], v208 offset:20480
	v_mfma_f32_32x32x16_bf16 v[34:49], v[236:239], v[248:251], v[34:49]
	ds_read_b128 v[228:231], v212 offset:28672
	s_waitcnt lgkmcnt(4)
	v_mfma_f32_32x32x16_bf16 v[18:33], v[240:243], v[244:247], v[18:33]
	ds_read_b128 v[224:227], v212 offset:32768
	v_mfma_f32_32x32x16_bf16 v[2:17], v[236:239], v[244:247], v[2:17]
	s_waitcnt vmcnt(0) lgkmcnt(0)
	s_barrier
	v_mfma_f32_32x32x16_bf16 v[82:97], v[220:223], v[232:235], v[82:97]
	v_mfma_f32_32x32x16_bf16 v[66:81], v[216:219], v[232:235], v[66:81]
	v_mfma_f32_32x32x16_bf16 v[50:65], v[220:223], v[228:231], v[50:65]
	v_mfma_f32_32x32x16_bf16 v[34:49], v[216:219], v[228:231], v[34:49]
	v_mfma_f32_32x32x16_bf16 v[18:33], v[220:223], v[224:227], v[18:33]
	v_mfma_f32_32x32x16_bf16 v[2:17], v[216:219], v[224:227], v[2:17]
	s_nop 7
	s_nop 7
	v_add_u32_e32 v147, v115, v118
	s_nop 4
	v_add_u32_e32 v98, v117, v121
	s_nop 4
	s_waitcnt lgkmcnt(0)
	v_or_b32_e32 v142, s5, v122
	v_cmp_lt_i32_e64 s[6:7], s3, v142
	v_add_u32_e32 v106, s4, v114
	v_ashrrev_i32_e32 v107, 31, v106
	v_lshlrev_b64 v[110:111], 11, v[106:107]
	v_or_b32_e32 v104, v142, v123
	v_lshl_add_u64 v[108:109], s[10:11], 0, v[110:111]
	s_and_saveexec_b64 s[4:5], s[6:7]
	s_xor_b64 s[4:5], exec, s[4:5]
	s_cbranch_execz .LBB0_154
	v_mul_f32_e32 v98, 0xbfb8aa3b, v82
	v_exp_f32_e32 v144, v98
	v_mul_f32_e32 v98, 0xbfb8aa3b, v83
	v_exp_f32_e32 v145, v98
	s_nop 0
	v_pk_add_f32 v[144:145], v[144:145], 1.0 op_sel_hi:[1,0]
	s_nop 0
	v_div_scale_f32 v98, s[30:31], v145, v145, v83
	v_rcp_f32_e32 v105, v98
	v_div_scale_f32 v107, vcc, v83, v145, v83
	v_fma_f32 v143, -v98, v105, 1.0
	v_fmac_f32_e32 v105, v143, v105
	v_mul_f32_e32 v143, v107, v105
	v_fma_f32 v147, -v98, v143, v107
	v_fmac_f32_e32 v143, v147, v105
	v_fma_f32 v98, -v98, v143, v107
	v_div_scale_f32 v107, s[30:31], v144, v144, v82
	v_rcp_f32_e32 v147, v107
	v_div_fmas_f32 v98, v98, v105, v143
	v_div_fixup_f32 v98, v98, v145, v83
	v_mul_f32_e32 v145, 0xbfb8aa3b, v84
	v_exp_f32_e32 v150, v145
	v_mul_f32_e32 v145, 0xbfb8aa3b, v85
	v_fma_f32 v105, -v107, v147, 1.0
	v_exp_f32_e32 v151, v145
	v_fmac_f32_e32 v147, v105, v147
	v_div_scale_f32 v105, vcc, v82, v144, v82
	v_mul_f32_e32 v143, v105, v147
	v_fma_f32 v145, -v107, v143, v105
	v_fmac_f32_e32 v143, v145, v147
	v_pk_add_f32 v[150:151], v[150:151], 1.0 op_sel_hi:[1,0]
	v_fma_f32 v105, -v107, v143, v105
	v_div_scale_f32 v107, s[30:31], v151, v151, v85
	v_rcp_f32_e32 v145, v107
	v_div_fmas_f32 v105, v105, v147, v143
	v_div_fixup_f32 v105, v105, v144, v82
	v_cvt_pk_bf16_f32 v144, v105, v98
	v_fma_f32 v98, -v107, v145, 1.0
	v_fmac_f32_e32 v145, v98, v145
	v_div_scale_f32 v98, vcc, v85, v151, v85
	v_mul_f32_e32 v105, v98, v145
	v_fma_f32 v143, -v107, v105, v98
	v_fmac_f32_e32 v105, v143, v145
	v_fma_f32 v98, -v107, v105, v98
	v_div_scale_f32 v107, s[30:31], v150, v150, v84
	v_rcp_f32_e32 v143, v107
	v_div_fmas_f32 v98, v98, v145, v105
	v_div_fixup_f32 v98, v98, v151, v85
	v_fma_f32 v105, -v107, v143, 1.0
	v_fmac_f32_e32 v143, v105, v143
	v_div_scale_f32 v105, vcc, v84, v150, v84
	v_mul_f32_e32 v145, v105, v143
	v_fma_f32 v147, -v107, v145, v105
	v_fmac_f32_e32 v145, v147, v143
	v_fma_f32 v105, -v107, v145, v105
	v_div_fmas_f32 v105, v105, v143, v145
	v_div_fixup_f32 v105, v105, v150, v84
	v_cvt_pk_bf16_f32 v145, v105, v98
	v_mov_b32_e32 v105, v99
	v_lshl_add_u64 v[150:151], v[104:105], 1, v[108:109]
	global_store_dwordx2 v[150:151], v[144:145], off offset:-2048

.LBB0_489:
	s_ashr_i32 s10, s28, 31
	s_lshr_b32 s10, s10, 26
	s_add_i32 s10, s28, s10
	s_ashr_i32 s31, s10, 6
	s_and_b32 s10, s10, 0x3ffffc0
	s_sub_i32 s29, s28, s10
	s_mulk_i32 s29, 0xc0
	v_add_u32_e32 v2, s29, v108
	s_lshr_b32 s10, s29, 6
	s_lshl_b32 s30, s31, 7
	v_ashrrev_i32_e32 v3, 31, v2
	s_add_i32 s10, s10, s31
	v_lshlrev_b64 v[2:3], 11, v[2:3]
	v_or_b32_e32 v4, s30, v108
	s_lshl_b32 s31, s10, 6
	s_lshl_b32 s10, s10, 7
	v_ashrrev_i32_e32 v5, 31, v4
	v_lshl_add_u64 v[104:105], v[100:101], 0, v[2:3]
	s_and_b32 s10, s10, 0x780
	v_readfirstlane_b32 s34, v109
	v_lshlrev_b64 v[4:5], 11, v[4:5]
	v_lshl_add_u64 v[2:3], v[104:105], 0, s[10:11]
	s_mov_b32 m0, s34
	v_readfirstlane_b32 s34, v128
	v_lshl_add_u64 v[106:107], v[102:103], 0, v[4:5]
	s_waitcnt vmcnt(0)
	s_barrier
	s_load_dwordx2 s[66:67], s[0:1], 0x118
	s_load_dwordx2 s[68:69], s[0:1], 0xd0
	v_and_b32_e32 v201, 0x3ff, v0
	v_readfirstlane_b32 s80, v0
	v_and_b32_e32 v200, 31, v201
	v_bfe_u32 v214, v201, 1, 3
	v_bfe_u32 v213, v201, 5, 1
	v_xor_b32_e32 v214, v214, v213
	v_lshlrev_b32_e32 v214, 4, v214
	s_and_b32 s80, s80, 0x3ff
	s_lshr_b32 s83, s80, 6
	s_lshl_b32 s80, s80, 4
	s_lshr_b32 s84, s83, 1
	s_and_b32 s83, s83, 1
	s_mul_i32 s84, s84, 0x3000
	s_lshl_b32 s83, s83, 13
	s_add_u32 s83, s83, 0xc000
	v_lshlrev_b32_e32 v200, 7, v200
	v_or_b32_e32 v200, v200, v214
	v_add_u32_e32 v215, s84, v200
	v_add_u32_e32 v211, s83, v200
	v_xor_b32_e32 v214, 0x20, v215
	v_xor_b32_e32 v210, 0x20, v211
	v_xor_b32_e32 v213, 0x40, v215
	v_xor_b32_e32 v209, 0x40, v211
	v_xor_b32_e32 v212, 0x60, v215
	v_xor_b32_e32 v208, 0x60, v211
	v_bfe_u32 v200, v201, 4, 3
	v_and_b32_e32 v206, 7, v201
	v_xor_b32_e32 v200, v200, v206
	v_lshlrev_b32_e32 v200, 4, v200
	v_lshrrev_b32_e32 v206, 3, v201
	v_lshl_or_b32 v207, v206, 11, v200
	v_add_u32_e32 v206, 0x10000, v207
	v_add_u32_e32 v205, 0x20000, v207
	v_add_u32_e32 v204, 0x30000, v207
	v_add_u32_e32 v203, 0x40000, v207
	v_add_u32_e32 v202, 0x50000, v207
	s_lshr_b32 s83, s28, 6
	s_and_b32 s84, s28, 63
	s_mov_b32 s79, 0
	s_mul_i32 s84, s84, 0x60000
	s_lshl_b32 s83, s83, 18
	s_waitcnt lgkmcnt(0)
	s_add_u32 s66, s66, s84
	s_addc_u32 s67, s67, 0
	s_add_u32 s68, s68, s83
	s_addc_u32 s69, s69, 0
	s_add_u32 s83, s79, 0
	s_and_b32 s83, s83, 15
	s_lshl_b32 s83, s83, 7
	s_add_u32 s70, s66, s83
	s_addc_u32 s71, s67, 0
	s_add_u32 s72, s68, s83
	s_addc_u32 s73, s69, 0
	s_add_u32 s81, s80, 0x0
	s_add_u32 s82, s80, 0xc000
	s_add_u32 m0, s81, 0x0
	s_nop 0
	global_load_lds_dwordx4 v207, s[70:71]
	s_add_u32 m0, s81, 0x1000
	s_nop 0
	global_load_lds_dwordx4 v206, s[70:71]
	s_add_u32 m0, s81, 0x2000
	s_nop 0
	global_load_lds_dwordx4 v205, s[70:71]
	s_add_u32 m0, s81, 0x3000
	s_nop 0
	global_load_lds_dwordx4 v204, s[70:71]
	s_add_u32 m0, s81, 0x4000
	s_nop 0
	global_load_lds_dwordx4 v203, s[70:71]
	s_add_u32 m0, s81, 0x5000
	s_nop 0
	global_load_lds_dwordx4 v202, s[70:71]
	s_add_u32 m0, s82, 0x0
	s_nop 0
	global_load_lds_dwordx4 v207, s[72:73]
	s_add_u32 m0, s82, 0x1000
	s_nop 0
	global_load_lds_dwordx4 v206, s[72:73]
	s_add_u32 m0, s82, 0x2000
	s_nop 0
	global_load_lds_dwordx4 v205, s[72:73]
	s_add_u32 m0, s82, 0x3000
	s_nop 0
	global_load_lds_dwordx4 v204, s[72:73]
	s_add_u32 s83, s79, 1
	s_and_b32 s83, s83, 15
	s_lshl_b32 s83, s83, 7
	s_add_u32 s70, s66, s83
	s_addc_u32 s71, s67, 0
	s_add_u32 s72, s68, s83
	s_addc_u32 s73, s69, 0
	s_add_u32 s81, s80, 0x6000
	s_add_u32 s82, s80, 0x10000
	s_add_u32 m0, s81, 0x0
	s_nop 0
	global_load_lds_dwordx4 v207, s[70:71]
	s_add_u32 m0, s81, 0x1000
	s_nop 0
	global_load_lds_dwordx4 v206, s[70:71]
	s_add_u32 m0, s81, 0x2000
	s_nop 0
	global_load_lds_dwordx4 v205, s[70:71]
	s_add_u32 m0, s81, 0x3000
	s_nop 0
	global_load_lds_dwordx4 v204, s[70:71]
	s_add_u32 m0, s81, 0x4000
	s_nop 0
	global_load_lds_dwordx4 v203, s[70:71]
	s_add_u32 m0, s81, 0x5000
	s_nop 0
	global_load_lds_dwordx4 v202, s[70:71]
	s_add_u32 m0, s82, 0x0
	s_nop 0
	global_load_lds_dwordx4 v207, s[72:73]
	s_add_u32 m0, s82, 0x1000
	s_nop 0
	global_load_lds_dwordx4 v206, s[72:73]
	s_add_u32 m0, s82, 0x2000
	s_nop 0
	global_load_lds_dwordx4 v205, s[72:73]
	s_add_u32 m0, s82, 0x3000
	s_nop 0
	global_load_lds_dwordx4 v204, s[72:73]
	v_mov_b32_e32 v2, 0
	v_mov_b32_e32 v3, 0
	v_mov_b32_e32 v4, 0
	v_mov_b32_e32 v5, 0
	v_mov_b32_e32 v6, 0
	v_mov_b32_e32 v7, 0
	v_mov_b32_e32 v8, 0
	v_mov_b32_e32 v9, 0
	v_mov_b32_e32 v10, 0
	v_mov_b32_e32 v11, 0
	v_mov_b32_e32 v12, 0
	v_mov_b32_e32 v13, 0
	v_mov_b32_e32 v14, 0
	v_mov_b32_e32 v15, 0
	v_mov_b32_e32 v16, 0
	v_mov_b32_e32 v17, 0
	v_mov_b32_e32 v18, 0
	v_mov_b32_e32 v19, 0
	v_mov_b32_e32 v20, 0
	v_mov_b32_e32 v21, 0
	v_mov_b32_e32 v22, 0
	v_mov_b32_e32 v23, 0
	v_mov_b32_e32 v24, 0
	v_mov_b32_e32 v25, 0
	v_mov_b32_e32 v26, 0
	v_mov_b32_e32 v27, 0
	v_mov_b32_e32 v28, 0
	v_mov_b32_e32 v29, 0
	v_mov_b32_e32 v30, 0
	v_mov_b32_e32 v31, 0
	v_mov_b32_e32 v32, 0
	v_mov_b32_e32 v33, 0
	v_mov_b32_e32 v34, 0
	v_mov_b32_e32 v35, 0
	v_mov_b32_e32 v36, 0
	v_mov_b32_e32 v37, 0
	v_mov_b32_e32 v38, 0
	v_mov_b32_e32 v39, 0
	v_mov_b32_e32 v40, 0
	v_mov_b32_e32 v41, 0
	v_mov_b32_e32 v42, 0
	v_mov_b32_e32 v43, 0
	v_mov_b32_e32 v44, 0
	v_mov_b32_e32 v45, 0
	v_mov_b32_e32 v46, 0
	v_mov_b32_e32 v47, 0
	v_mov_b32_e32 v48, 0
	v_mov_b32_e32 v49, 0
	v_mov_b32_e32 v50, 0
	v_mov_b32_e32 v51, 0
	v_mov_b32_e32 v52, 0
	v_mov_b32_e32 v53, 0
	v_mov_b32_e32 v54, 0
	v_mov_b32_e32 v55, 0
	v_mov_b32_e32 v56, 0
	v_mov_b32_e32 v57, 0
	v_mov_b32_e32 v58, 0
	v_mov_b32_e32 v59, 0
	v_mov_b32_e32 v60, 0
	v_mov_b32_e32 v61, 0
	v_mov_b32_e32 v62, 0
	v_mov_b32_e32 v63, 0
	v_mov_b32_e32 v64, 0
	v_mov_b32_e32 v65, 0
	v_mov_b32_e32 v66, 0
	v_mov_b32_e32 v67, 0
	v_mov_b32_e32 v68, 0
	v_mov_b32_e32 v69, 0
	v_mov_b32_e32 v70, 0
	v_mov_b32_e32 v71, 0
	v_mov_b32_e32 v72, 0
	v_mov_b32_e32 v73, 0
	v_mov_b32_e32 v74, 0
	v_mov_b32_e32 v75, 0
	v_mov_b32_e32 v76, 0
	v_mov_b32_e32 v77, 0
	v_mov_b32_e32 v78, 0
	v_mov_b32_e32 v79, 0
	v_mov_b32_e32 v80, 0
	v_mov_b32_e32 v81, 0
	v_mov_b32_e32 v82, 0
	v_mov_b32_e32 v83, 0
	v_mov_b32_e32 v84, 0
	v_mov_b32_e32 v85, 0
	v_mov_b32_e32 v86, 0
	v_mov_b32_e32 v87, 0
	v_mov_b32_e32 v88, 0
	v_mov_b32_e32 v89, 0
	v_mov_b32_e32 v90, 0
	v_mov_b32_e32 v91, 0
	v_mov_b32_e32 v92, 0
	v_mov_b32_e32 v93, 0
	v_mov_b32_e32 v94, 0
	v_mov_b32_e32 v95, 0
	v_mov_b32_e32 v96, 0
	v_mov_b32_e32 v97, 0
	s_waitcnt vmcnt(10)
	s_barrier
	ds_read_b128 v[240:243], v211 offset:0
	ds_read_b128 v[252:255], v215 offset:0
	ds_read_b128 v[236:239], v211 offset:4096
	ds_read_b128 v[248:251], v215 offset:4096
	ds_read_b128 v[244:247], v215 offset:8192
	s_mov_b32 s78, 0
.Lgm_ph5_loop:
	s_waitcnt lgkmcnt(1)
	v_mfma_f32_32x32x16_bf16 v[82:97], v[240:243], v[252:255], v[82:97]
	ds_read_b128 v[220:223], v210 offset:0
	v_mfma_f32_32x32x16_bf16 v[66:81], v[236:239], v[252:255], v[66:81]
	ds_read_b128 v[232:235], v214 offset:0
	v_mfma_f32_32x32x16_bf16 v[50:65], v[240:243], v[248:251], v[50:65]
	ds_read_b128 v[216:219], v210 offset:4096
	v_mfma_f32_32x32x16_bf16 v[34:49], v[236:239], v[248:251], v[34:49]
	ds_read_b128 v[228:231], v214 offset:4096
	s_waitcnt lgkmcnt(4)
	v_mfma_f32_32x32x16_bf16 v[18:33], v[240:243], v[244:247], v[18:33]
	ds_read_b128 v[224:227], v214 offset:8192
	v_mfma_f32_32x32x16_bf16 v[2:17], v[236:239], v[244:247], v[2:17]
	s_waitcnt lgkmcnt(1)
	v_mfma_f32_32x32x16_bf16 v[82:97], v[220:223], v[232:235], v[82:97]
	ds_read_b128 v[240:243], v209 offset:0
	v_mfma_f32_32x32x16_bf16 v[66:81], v[216:219], v[232:235], v[66:81]
	ds_read_b128 v[252:255], v213 offset:0
	v_mfma_f32_32x32x16_bf16 v[50:65], v[220:223], v[228:231], v[50:65]
	ds_read_b128 v[236:239], v209 offset:4096
	v_mfma_f32_32x32x16_bf16 v[34:49], v[216:219], v[228:231], v[34:49]
	ds_read_b128 v[248:251], v213 offset:4096
	s_waitcnt lgkmcnt(4)
	v_mfma_f32_32x32x16_bf16 v[18:33], v[220:223], v[224:227], v[18:33]
	ds_read_b128 v[244:247], v213 offset:8192
	v_mfma_f32_32x32x16_bf16 v[2:17], v[216:219], v[224:227], v[2:17]
	s_waitcnt lgkmcnt(1)
	v_mfma_f32_32x32x16_bf16 v[82:97], v[240:243], v[252:255], v[82:97]
	ds_read_b128 v[220:223], v208 offset:0
	s_add_u32 s83, s79, s78
	s_add_u32 s83, s83, 2
	s_and_b32 s83, s83, 15
	v_mfma_f32_32x32x16_bf16 v[66:81], v[236:239], v[252:255], v[66:81]
	ds_read_b128 v[232:235], v212 offset:0
	s_lshl_b32 s83, s83, 7
	s_add_u32 s70, s66, s83
	v_mfma_f32_32x32x16_bf16 v[50:65], v[240:243], v[248:251], v[50:65]
	ds_read_b128 v[216:219], v208 offset:4096
	s_addc_u32 s71, s67, 0
	s_add_u32 s72, s68, s83
	v_mfma_f32_32x32x16_bf16 v[34:49], v[236:239], v[248:251], v[34:49]
	ds_read_b128 v[228:231], v212 offset:4096
	s_addc_u32 s73, s69, 0
	s_add_u32 s81, s80, 0x0
	s_add_u32 s82, s80, 0xc000
	s_waitcnt lgkmcnt(4)
	v_mfma_f32_32x32x16_bf16 v[18:33], v[240:243], v[244:247], v[18:33]
	ds_read_b128 v[224:227], v212 offset:8192
	v_mfma_f32_32x32x16_bf16 v[2:17], v[236:239], v[244:247], v[2:17]
	s_waitcnt vmcnt(0) lgkmcnt(0)
	s_barrier
	v_mfma_f32_32x32x16_bf16 v[82:97], v[220:223], v[232:235], v[82:97]
	s_add_u32 m0, s81, 0x0
	ds_read_b128 v[240:243], v211 offset:16384
	global_load_lds_dwordx4 v207, s[70:71]
	s_add_u32 m0, s81, 0x1000
	s_nop 0
	global_load_lds_dwordx4 v206, s[70:71]
	v_mfma_f32_32x32x16_bf16 v[66:81], v[216:219], v[232:235], v[66:81]
	s_add_u32 m0, s81, 0x2000
	ds_read_b128 v[252:255], v215 offset:24576
	global_load_lds_dwordx4 v205, s[70:71]
	s_add_u32 m0, s81, 0x3000
	s_nop 0
	global_load_lds_dwordx4 v204, s[70:71]
	v_mfma_f32_32x32x16_bf16 v[50:65], v[220:223], v[228:231], v[50:65]
	s_add_u32 m0, s81, 0x4000
	ds_read_b128 v[236:239], v211 offset:20480
	global_load_lds_dwordx4 v203, s[70:71]
	s_add_u32 m0, s81, 0x5000
	s_nop 0
	global_load_lds_dwordx4 v202, s[70:71]
	v_mfma_f32_32x32x16_bf16 v[34:49], v[216:219], v[228:231], v[34:49]
	s_add_u32 m0, s82, 0x0
	ds_read_b128 v[248:251], v215 offset:28672
	global_load_lds_dwordx4 v207, s[72:73]
	s_add_u32 m0, s82, 0x1000
	s_nop 0
	global_load_lds_dwordx4 v206, s[72:73]
	v_mfma_f32_32x32x16_bf16 v[18:33], v[220:223], v[224:227], v[18:33]
	s_add_u32 m0, s82, 0x2000
	ds_read_b128 v[244:247], v215 offset:32768
	global_load_lds_dwordx4 v205, s[72:73]
	s_add_u32 m0, s82, 0x3000
	s_nop 0
	global_load_lds_dwordx4 v204, s[72:73]
	v_mfma_f32_32x32x16_bf16 v[2:17], v[216:219], v[224:227], v[2:17]
	s_waitcnt lgkmcnt(1)
	v_mfma_f32_32x32x16_bf16 v[82:97], v[240:243], v[252:255], v[82:97]
	ds_read_b128 v[220:223], v210 offset:16384
	v_mfma_f32_32x32x16_bf16 v[66:81], v[236:239], v[252:255], v[66:81]
	ds_read_b128 v[232:235], v214 offset:24576
	v_mfma_f32_32x32x16_bf16 v[50:65], v[240:243], v[248:251], v[50:65]
	ds_read_b128 v[216:219], v210 offset:20480
	v_mfma_f32_32x32x16_bf16 v[34:49], v[236:239], v[248:251], v[34:49]
	ds_read_b128 v[228:231], v214 offset:28672
	s_waitcnt lgkmcnt(4)
	v_mfma_f32_32x32x16_bf16 v[18:33], v[240:243], v[244:247], v[18:33]
	ds_read_b128 v[224:227], v214 offset:32768
	v_mfma_f32_32x32x16_bf16 v[2:17], v[236:239], v[244:247], v[2:17]
	s_waitcnt lgkmcnt(1)
	v_mfma_f32_32x32x16_bf16 v[82:97], v[220:223], v[232:235], v[82:97]
	ds_read_b128 v[240:243], v209 offset:16384
	v_mfma_f32_32x32x16_bf16 v[66:81], v[216:219], v[232:235], v[66:81]
	ds_read_b128 v[252:255], v213 offset:24576
	v_mfma_f32_32x32x16_bf16 v[50:65], v[220:223], v[228:231], v[50:65]
	ds_read_b128 v[236:239], v209 offset:20480
	v_mfma_f32_32x32x16_bf16 v[34:49], v[216:219], v[228:231], v[34:49]
	ds_read_b128 v[248:251], v213 offset:28672
	s_waitcnt lgkmcnt(4)
	v_mfma_f32_32x32x16_bf16 v[18:33], v[220:223], v[224:227], v[18:33]
	ds_read_b128 v[244:247], v213 offset:32768
	v_mfma_f32_32x32x16_bf16 v[2:17], v[216:219], v[224:227], v[2:17]
	s_waitcnt lgkmcnt(1)
	v_mfma_f32_32x32x16_bf16 v[82:97], v[240:243], v[252:255], v[82:97]
	ds_read_b128 v[220:223], v208 offset:16384
	s_add_u32 s83, s79, s78
	s_add_u32 s83, s83, 3
	s_and_b32 s83, s83, 15
	v_mfma_f32_32x32x16_bf16 v[66:81], v[236:239], v[252:255], v[66:81]
	ds_read_b128 v[232:235], v212 offset:24576
	s_lshl_b32 s83, s83, 7
	s_add_u32 s70, s66, s83
	v_mfma_f32_32x32x16_bf16 v[50:65], v[240:243], v[248:251], v[50:65]
	ds_read_b128 v[216:219], v208 offset:20480
	s_addc_u32 s71, s67, 0
	s_add_u32 s72, s68, s83
	v_mfma_f32_32x32x16_bf16 v[34:49], v[236:239], v[248:251], v[34:49]
	ds_read_b128 v[228:231], v212 offset:28672
	s_addc_u32 s73, s69, 0
	s_add_u32 s81, s80, 0x6000
	s_add_u32 s82, s80, 0x10000
	s_waitcnt lgkmcnt(4)
	v_mfma_f32_32x32x16_bf16 v[18:33], v[240:243], v[244:247], v[18:33]
	ds_read_b128 v[224:227], v212 offset:32768
	v_mfma_f32_32x32x16_bf16 v[2:17], v[236:239], v[244:247], v[2:17]
	s_waitcnt vmcnt(0) lgkmcnt(0)
	s_barrier
	v_mfma_f32_32x32x16_bf16 v[82:97], v[220:223], v[232:235], v[82:97]
	s_add_u32 m0, s81, 0x0
	ds_read_b128 v[240:243], v211 offset:0
	global_load_lds_dwordx4 v207, s[70:71]
	s_add_u32 m0, s81, 0x1000
	s_nop 0
	global_load_lds_dwordx4 v206, s[70:71]
	v_mfma_f32_32x32x16_bf16 v[66:81], v[216:219], v[232:235], v[66:81]
	s_add_u32 m0, s81, 0x2000
	ds_read_b128 v[252:255], v215 offset:0
	global_load_lds_dwordx4 v205, s[70:71]
	s_add_u32 m0, s81, 0x3000
	s_nop 0
	global_load_lds_dwordx4 v204, s[70:71]
	v_mfma_f32_32x32x16_bf16 v[50:65], v[220:223], v[228:231], v[50:65]
	s_add_u32 m0, s81, 0x4000
	ds_read_b128 v[236:239], v211 offset:4096
	global_load_lds_dwordx4 v203, s[70:71]
	s_add_u32 m0, s81, 0x5000
	s_nop 0
	global_load_lds_dwordx4 v202, s[70:71]
	v_mfma_f32_32x32x16_bf16 v[34:49], v[216:219], v[228:231], v[34:49]
	s_add_u32 m0, s82, 0x0
	ds_read_b128 v[248:251], v215 offset:4096
	global_load_lds_dwordx4 v207, s[72:73]
	s_add_u32 m0, s82, 0x1000
	s_nop 0
	global_load_lds_dwordx4 v206, s[72:73]
	v_mfma_f32_32x32x16_bf16 v[18:33], v[220:223], v[224:227], v[18:33]
	s_add_u32 m0, s82, 0x2000
	ds_read_b128 v[244:247], v215 offset:8192
	global_load_lds_dwordx4 v205, s[72:73]
	s_add_u32 m0, s82, 0x3000
	s_nop 0
	global_load_lds_dwordx4 v204, s[72:73]
	v_mfma_f32_32x32x16_bf16 v[2:17], v[216:219], v[224:227], v[2:17]
	s_add_u32 s78, s78, 2
	s_cmp_lt_u32 s78, 14
	s_cbranch_scc1 .Lgm_ph5_loop
	s_waitcnt lgkmcnt(1)
	v_mfma_f32_32x32x16_bf16 v[82:97], v[240:243], v[252:255], v[82:97]
	ds_read_b128 v[220:223], v210 offset:0
	v_mfma_f32_32x32x16_bf16 v[66:81], v[236:239], v[252:255], v[66:81]
	ds_read_b128 v[232:235], v214 offset:0
	v_mfma_f32_32x32x16_bf16 v[50:65], v[240:243], v[248:251], v[50:65]
	ds_read_b128 v[216:219], v210 offset:4096
	v_mfma_f32_32x32x16_bf16 v[34:49], v[236:239], v[248:251], v[34:49]
	ds_read_b128 v[228:231], v214 offset:4096
	s_waitcnt lgkmcnt(4)
	v_mfma_f32_32x32x16_bf16 v[18:33], v[240:243], v[244:247], v[18:33]
	ds_read_b128 v[224:227], v214 offset:8192
	v_mfma_f32_32x32x16_bf16 v[2:17], v[236:239], v[244:247], v[2:17]
	s_waitcnt lgkmcnt(1)
	v_mfma_f32_32x32x16_bf16 v[82:97], v[220:223], v[232:235], v[82:97]
	ds_read_b128 v[240:243], v209 offset:0
	v_mfma_f32_32x32x16_bf16 v[66:81], v[216:219], v[232:235], v[66:81]
	ds_read_b128 v[252:255], v213 offset:0
	v_mfma_f32_32x32x16_bf16 v[50:65], v[220:223], v[228:231], v[50:65]
	ds_read_b128 v[236:239], v209 offset:4096
	v_mfma_f32_32x32x16_bf16 v[34:49], v[216:219], v[228:231], v[34:49]
	ds_read_b128 v[248:251], v213 offset:4096
	s_waitcnt lgkmcnt(4)
	v_mfma_f32_32x32x16_bf16 v[18:33], v[220:223], v[224:227], v[18:33]
	ds_read_b128 v[244:247], v213 offset:8192
	v_mfma_f32_32x32x16_bf16 v[2:17], v[216:219], v[224:227], v[2:17]
	s_waitcnt lgkmcnt(1)
	v_mfma_f32_32x32x16_bf16 v[82:97], v[240:243], v[252:255], v[82:97]
	ds_read_b128 v[220:223], v208 offset:0
	v_mfma_f32_32x32x16_bf16 v[66:81], v[236:239], v[252:255], v[66:81]
	ds_read_b128 v[232:235], v212 offset:0
	v_mfma_f32_32x32x16_bf16 v[50:65], v[240:243], v[248:251], v[50:65]
	ds_read_b128 v[216:219], v208 offset:4096
	v_mfma_f32_32x32x16_bf16 v[34:49], v[236:239], v[248:251], v[34:49]
	ds_read_b128 v[228:231], v212 offset:4096
	s_waitcnt lgkmcnt(4)
	v_mfma_f32_32x32x16_bf16 v[18:33], v[240:243], v[244:247], v[18:33]
	ds_read_b128 v[224:227], v212 offset:8192
	v_mfma_f32_32x32x16_bf16 v[2:17], v[236:239], v[244:247], v[2:17]
	s_waitcnt vmcnt(0) lgkmcnt(0)
	s_barrier
	v_mfma_f32_32x32x16_bf16 v[82:97], v[220:223], v[232:235], v[82:97]
	ds_read_b128 v[240:243], v211 offset:16384
	v_mfma_f32_32x32x16_bf16 v[66:81], v[216:219], v[232:235], v[66:81]
	ds_read_b128 v[252:255], v215 offset:24576
	v_mfma_f32_32x32x16_bf16 v[50:65], v[220:223], v[228:231], v[50:65]
	ds_read_b128 v[236:239], v211 offset:20480
	v_mfma_f32_32x32x16_bf16 v[34:49], v[216:219], v[228:231], v[34:49]
	ds_read_b128 v[248:251], v215 offset:28672
	v_mfma_f32_32x32x16_bf16 v[18:33], v[220:223], v[224:227], v[18:33]
	ds_read_b128 v[244:247], v215 offset:32768
	v_mfma_f32_32x32x16_bf16 v[2:17], v[216:219], v[224:227], v[2:17]
	s_waitcnt lgkmcnt(1)
	v_mfma_f32_32x32x16_bf16 v[82:97], v[240:243], v[252:255], v[82:97]
	ds_read_b128 v[220:223], v210 offset:16384
	v_mfma_f32_32x32x16_bf16 v[66:81], v[236:239], v[252:255], v[66:81]
	ds_read_b128 v[232:235], v214 offset:24576
	v_mfma_f32_32x32x16_bf16 v[50:65], v[240:243], v[248:251], v[50:65]
	ds_read_b128 v[216:219], v210 offset:20480
	v_mfma_f32_32x32x16_bf16 v[34:49], v[236:239], v[248:251], v[34:49]
	ds_read_b128 v[228:231], v214 offset:28672
	s_waitcnt lgkmcnt(4)
	v_mfma_f32_32x32x16_bf16 v[18:33], v[240:243], v[244:247], v[18:33]
	ds_read_b128 v[224:227], v214 offset:32768
	v_mfma_f32_32x32x16_bf16 v[2:17], v[236:239], v[244:247], v[2:17]
	s_waitcnt lgkmcnt(1)
	v_mfma_f32_32x32x16_bf16 v[82:97], v[220:223], v[232:235], v[82:97]
	ds_read_b128 v[240:243], v209 offset:16384
	v_mfma_f32_32x32x16_bf16 v[66:81], v[216:219], v[232:235], v[66:81]
	ds_read_b128 v[252:255], v213 offset:24576
	v_mfma_f32_32x32x16_bf16 v[50:65], v[220:223], v[228:231], v[50:65]
	ds_read_b128 v[236:239], v209 offset:20480
	v_mfma_f32_32x32x16_bf16 v[34:49], v[216:219], v[228:231], v[34:49]
	ds_read_b128 v[248:251], v213 offset:28672
	s_waitcnt lgkmcnt(4)
	v_mfma_f32_32x32x16_bf16 v[18:33], v[220:223], v[224:227], v[18:33]
	ds_read_b128 v[244:247], v213 offset:32768
	v_mfma_f32_32x32x16_bf16 v[2:17], v[216:219], v[224:227], v[2:17]
	s_waitcnt lgkmcnt(1)
	v_mfma_f32_32x32x16_bf16 v[82:97], v[240:243], v[252:255], v[82:97]
	ds_read_b128 v[220:223], v208 offset:16384
	v_mfma_f32_32x32x16_bf16 v[66:81], v[236:239], v[252:255], v[66:81]
	ds_read_b128 v[232:235], v212 offset:24576
	v_mfma_f32_32x32x16_bf16 v[50:65], v[240:243], v[248:251], v[50:65]
	ds_read_b128 v[216:219], v208 offset:20480
	v_mfma_f32_32x32x16_bf16 v[34:49], v[236:239], v[248:251], v[34:49]
	ds_read_b128 v[228:231], v212 offset:28672
	s_waitcnt lgkmcnt(4)
	v_mfma_f32_32x32x16_bf16 v[18:33], v[240:243], v[244:247], v[18:33]
	ds_read_b128 v[224:227], v212 offset:32768
	v_mfma_f32_32x32x16_bf16 v[2:17], v[236:239], v[244:247], v[2:17]
	s_waitcnt vmcnt(0) lgkmcnt(0)
	s_barrier
	v_mfma_f32_32x32x16_bf16 v[82:97], v[220:223], v[232:235], v[82:97]
	v_mfma_f32_32x32x16_bf16 v[66:81], v[216:219], v[232:235], v[66:81]
	v_mfma_f32_32x32x16_bf16 v[50:65], v[220:223], v[228:231], v[50:65]
	v_mfma_f32_32x32x16_bf16 v[34:49], v[216:219], v[228:231], v[34:49]
	v_mfma_f32_32x32x16_bf16 v[18:33], v[220:223], v[224:227], v[18:33]
	v_mfma_f32_32x32x16_bf16 v[2:17], v[216:219], v[224:227], v[2:17]
	s_nop 7
	s_nop 7
	s_waitcnt lgkmcnt(0)
	s_nop 10
	ds_write_b128 v147, v[82:85]
	ds_write_b128 v147, v[86:89] offset:32
	ds_write_b128 v147, v[90:93] offset:64
	ds_write_b128 v147, v[94:97] offset:96
	ds_write_b128 v147, v[66:69] offset:128
	ds_write_b128 v147, v[70:73] offset:160
	ds_write_b128 v147, v[74:77] offset:192
	ds_write_b128 v147, v[78:81] offset:224
	s_waitcnt lgkmcnt(0)
	v_add_u32_e32 v104, s29, v111
	v_or_b32_e32 v244, s30, v120
	v_lshlrev_b32_e32 v242, 2, v244
	v_add_u32_e32 v242, s3, v242
	v_lshlrev_b32_e32 v243, 1, v244
	v_mov_b32_e32 v240, v104
	v_add_u32_e32 v241, 0xfffff000, v240
	v_lshrrev_b32_e32 v241, 11, v241
	v_mad_u32_u24 v241, v241, s26, s26
	v_lshlrev_b32_e32 v241, 2, v241
	v_or_b32_e32 v232, v240, v119
	v_or_b32_e32 v233, v240, v121
	v_or_b32_e32 v234, v240, v122
	v_or_b32_e32 v235, v240, v123
	v_or_b32_e32 v236, v240, v124
	v_or_b32_e32 v237, v240, v125
	v_or_b32_e32 v238, v240, v126
	v_or_b32_e32 v239, v240, v127
	v_cmp_lt_i32_e64 s[82:83], s27, v232
	v_cmp_lt_i32_e64 s[84:85], s27, v233
	v_cmp_lt_i32_e64 s[86:87], s27, v234
	v_cmp_lt_i32_e64 s[88:89], s27, v235
	v_cmp_lt_i32_e64 s[90:91], s27, v236
	v_cmp_lt_i32_e64 s[92:93], s27, v237
	v_cmp_lt_i32_e64 s[94:95], s27, v238
	v_cmp_lt_i32_e64 s[96:97], s27, v239
	s_waitcnt lgkmcnt(0)
	v_cndmask_b32_e64 v200, 0, v241, s[82:83]
	v_cndmask_b32_e64 v204, 0, v241, s[84:85]
	v_cndmask_b32_e64 v208, 0, v241, s[86:87]
	v_cndmask_b32_e64 v212, 0, v241, s[88:89]
	v_cndmask_b32_e64 v216, 0, v241, s[90:91]
	v_cndmask_b32_e64 v220, 0, v241, s[92:93]
	v_cndmask_b32_e64 v224, 0, v241, s[94:95]
	v_cndmask_b32_e64 v228, 0, v241, s[96:97]
	v_add_u32_e32 v200, v200, v242
	v_add_u32_e32 v204, v204, v242
	v_add_u32_e32 v208, v208, v242
	v_add_u32_e32 v212, v212, v242
	v_add_u32_e32 v216, v216, v242
	v_add_u32_e32 v220, v220, v242
	v_add_u32_e32 v224, v224, v242
	v_add_u32_e32 v228, v228, v242
	ds_read_b128 v[82:85], v149
	global_load_dwordx4 v[200:203], v200, s[4:5]
	ds_read_b128 v[86:89], v149 offset:1088
	global_load_dwordx4 v[204:207], v204, s[4:5]
	ds_read_b128 v[90:93], v149 offset:2176
	global_load_dwordx4 v[208:211], v208, s[4:5]
	ds_read_b128 v[94:97], v149 offset:3264
	global_load_dwordx4 v[212:215], v212, s[4:5]
	ds_read_b128 v[66:69], v149 offset:4352
	global_load_dwordx4 v[216:219], v216, s[4:5]
	ds_read_b128 v[70:73], v149 offset:5440
	global_load_dwordx4 v[220:223], v220, s[4:5]
	ds_read_b128 v[74:77], v149 offset:6528
	global_load_dwordx4 v[224:227], v224, s[4:5]
	ds_read_b128 v[78:81], v149 offset:7616
	global_load_dwordx4 v[228:231], v228, s[4:5]
	v_lshl_add_u32 v232, v232, 11, v243
	v_lshl_add_u32 v233, v233, 11, v243
	v_lshl_add_u32 v234, v234, 11, v243
	v_lshl_add_u32 v235, v235, 11, v243
	v_lshl_add_u32 v236, v236, 11, v243
	v_lshl_add_u32 v237, v237, 11, v243
	v_lshl_add_u32 v238, v238, 11, v243
	v_lshl_add_u32 v239, v239, 11, v243
	s_waitcnt vmcnt(7) lgkmcnt(7)
	v_mul_f32_e32 v82, v82, v200
	v_mul_f32_e32 v83, v83, v201
	v_mul_f32_e32 v84, v84, v202
	v_mul_f32_e32 v85, v85, v203
	v_cvt_pk_bf16_f32 v82, v82, v83
	v_cvt_pk_bf16_f32 v83, v84, v85
	global_store_dwordx2 v232, v[82:83], s[6:7]
	s_waitcnt vmcnt(7) lgkmcnt(6)
	v_mul_f32_e32 v86, v86, v204
	v_mul_f32_e32 v87, v87, v205
	v_mul_f32_e32 v88, v88, v206
	v_mul_f32_e32 v89, v89, v207
	v_cvt_pk_bf16_f32 v86, v86, v87
	v_cvt_pk_bf16_f32 v87, v88, v89
	global_store_dwordx2 v233, v[86:87], s[6:7]
	s_waitcnt vmcnt(7) lgkmcnt(5)
	v_mul_f32_e32 v90, v90, v208
	v_mul_f32_e32 v91, v91, v209
	v_mul_f32_e32 v92, v92, v210
	v_mul_f32_e32 v93, v93, v211
	v_cvt_pk_bf16_f32 v90, v90, v91
	v_cvt_pk_bf16_f32 v91, v92, v93
	global_store_dwordx2 v234, v[90:91], s[6:7]
	s_waitcnt vmcnt(7) lgkmcnt(4)
	v_mul_f32_e32 v94, v94, v212
	v_mul_f32_e32 v95, v95, v213
	v_mul_f32_e32 v96, v96, v214
	v_mul_f32_e32 v97, v97, v215
	v_cvt_pk_bf16_f32 v94, v94, v95
	v_cvt_pk_bf16_f32 v95, v96, v97
	global_store_dwordx2 v235, v[94:95], s[6:7]
	s_waitcnt vmcnt(7) lgkmcnt(3)
	v_mul_f32_e32 v66, v66, v216
	v_mul_f32_e32 v67, v67, v217
	v_mul_f32_e32 v68, v68, v218
	v_mul_f32_e32 v69, v69, v219
	v_cvt_pk_bf16_f32 v66, v66, v67
	v_cvt_pk_bf16_f32 v67, v68, v69
	global_store_dwordx2 v236, v[66:67], s[6:7]
	s_waitcnt vmcnt(7) lgkmcnt(2)
	v_mul_f32_e32 v70, v70, v220
	v_mul_f32_e32 v71, v71, v221
	v_mul_f32_e32 v72, v72, v222
	v_mul_f32_e32 v73, v73, v223
	v_cvt_pk_bf16_f32 v70, v70, v71
	v_cvt_pk_bf16_f32 v71, v72, v73
	global_store_dwordx2 v237, v[70:71], s[6:7]
	s_waitcnt vmcnt(7) lgkmcnt(1)
	v_mul_f32_e32 v74, v74, v224
	v_mul_f32_e32 v75, v75, v225
	v_mul_f32_e32 v76, v76, v226
	v_mul_f32_e32 v77, v77, v227
	v_cvt_pk_bf16_f32 v74, v74, v75
	v_cvt_pk_bf16_f32 v75, v76, v77
	global_store_dwordx2 v238, v[74:75], s[6:7]
	s_waitcnt vmcnt(7) lgkmcnt(0)
	v_mul_f32_e32 v78, v78, v228
	v_mul_f32_e32 v79, v79, v229
	v_mul_f32_e32 v80, v80, v230
	v_mul_f32_e32 v81, v81, v231
	v_cvt_pk_bf16_f32 v78, v78, v79
	v_cvt_pk_bf16_f32 v79, v80, v81
	global_store_dwordx2 v239, v[78:79], s[6:7]
	ds_write_b128 v147, v[50:53]
	ds_write_b128 v147, v[54:57] offset:32
	ds_write_b128 v147, v[58:61] offset:64
	ds_write_b128 v147, v[62:65] offset:96
	ds_write_b128 v147, v[34:37] offset:128
	ds_write_b128 v147, v[38:41] offset:160
	ds_write_b128 v147, v[42:45] offset:192
	ds_write_b128 v147, v[46:49] offset:224
	v_add_u32_e32 v240, 0x20, v104
	v_add_u32_e32 v241, 0xfffff000, v240
	v_lshrrev_b32_e32 v241, 11, v241
	v_mad_u32_u24 v241, v241, s26, s26
	v_lshlrev_b32_e32 v241, 2, v241
	v_or_b32_e32 v232, v240, v119
	v_or_b32_e32 v233, v240, v121
	v_or_b32_e32 v234, v240, v122
	v_or_b32_e32 v235, v240, v123
	v_or_b32_e32 v236, v240, v124
	v_or_b32_e32 v237, v240, v125
	v_or_b32_e32 v238, v240, v126
	v_or_b32_e32 v239, v240, v127
	v_cmp_lt_i32_e64 s[82:83], s27, v232
	v_cmp_lt_i32_e64 s[84:85], s27, v233
	v_cmp_lt_i32_e64 s[86:87], s27, v234
	v_cmp_lt_i32_e64 s[88:89], s27, v235
	v_cmp_lt_i32_e64 s[90:91], s27, v236
	v_cmp_lt_i32_e64 s[92:93], s27, v237
	v_cmp_lt_i32_e64 s[94:95], s27, v238
	v_cmp_lt_i32_e64 s[96:97], s27, v239
	s_waitcnt lgkmcnt(0)
	v_cndmask_b32_e64 v200, 0, v241, s[82:83]
	v_cndmask_b32_e64 v204, 0, v241, s[84:85]
	v_cndmask_b32_e64 v208, 0, v241, s[86:87]
	v_cndmask_b32_e64 v212, 0, v241, s[88:89]
	v_cndmask_b32_e64 v216, 0, v241, s[90:91]
	v_cndmask_b32_e64 v220, 0, v241, s[92:93]
	v_cndmask_b32_e64 v224, 0, v241, s[94:95]
	v_cndmask_b32_e64 v228, 0, v241, s[96:97]
	v_add_u32_e32 v200, v200, v242
	v_add_u32_e32 v204, v204, v242
	v_add_u32_e32 v208, v208, v242
	v_add_u32_e32 v212, v212, v242
	v_add_u32_e32 v216, v216, v242
	v_add_u32_e32 v220, v220, v242
	v_add_u32_e32 v224, v224, v242
	v_add_u32_e32 v228, v228, v242
	ds_read_b128 v[50:53], v149
	global_load_dwordx4 v[200:203], v200, s[4:5]
	ds_read_b128 v[54:57], v149 offset:1088
	global_load_dwordx4 v[204:207], v204, s[4:5]
	ds_read_b128 v[58:61], v149 offset:2176
	global_load_dwordx4 v[208:211], v208, s[4:5]
	ds_read_b128 v[62:65], v149 offset:3264
	global_load_dwordx4 v[212:215], v212, s[4:5]
	ds_read_b128 v[34:37], v149 offset:4352
	global_load_dwordx4 v[216:219], v216, s[4:5]
	ds_read_b128 v[38:41], v149 offset:5440
	global_load_dwordx4 v[220:223], v220, s[4:5]
	ds_read_b128 v[42:45], v149 offset:6528
	global_load_dwordx4 v[224:227], v224, s[4:5]
	ds_read_b128 v[46:49], v149 offset:7616
	global_load_dwordx4 v[228:231], v228, s[4:5]
	v_lshl_add_u32 v232, v232, 11, v243
	v_lshl_add_u32 v233, v233, 11, v243
	v_lshl_add_u32 v234, v234, 11, v243
	v_lshl_add_u32 v235, v235, 11, v243
	v_lshl_add_u32 v236, v236, 11, v243
	v_lshl_add_u32 v237, v237, 11, v243
	v_lshl_add_u32 v238, v238, 11, v243
	v_lshl_add_u32 v239, v239, 11, v243
	s_waitcnt vmcnt(7) lgkmcnt(7)
	v_mul_f32_e32 v50, v50, v200
	v_mul_f32_e32 v51, v51, v201
	v_mul_f32_e32 v52, v52, v202
	v_mul_f32_e32 v53, v53, v203
	v_cvt_pk_bf16_f32 v50, v50, v51
	v_cvt_pk_bf16_f32 v51, v52, v53
	global_store_dwordx2 v232, v[50:51], s[6:7]
	s_waitcnt vmcnt(7) lgkmcnt(6)
	v_mul_f32_e32 v54, v54, v204
	v_mul_f32_e32 v55, v55, v205
	v_mul_f32_e32 v56, v56, v206
	v_mul_f32_e32 v57, v57, v207
	v_cvt_pk_bf16_f32 v54, v54, v55
	v_cvt_pk_bf16_f32 v55, v56, v57
	global_store_dwordx2 v233, v[54:55], s[6:7]
	s_waitcnt vmcnt(7) lgkmcnt(5)
	v_mul_f32_e32 v58, v58, v208
	v_mul_f32_e32 v59, v59, v209
	v_mul_f32_e32 v60, v60, v210
	v_mul_f32_e32 v61, v61, v211
	v_cvt_pk_bf16_f32 v58, v58, v59
	v_cvt_pk_bf16_f32 v59, v60, v61
	global_store_dwordx2 v234, v[58:59], s[6:7]
	s_waitcnt vmcnt(7) lgkmcnt(4)
	v_mul_f32_e32 v62, v62, v212
	v_mul_f32_e32 v63, v63, v213
	v_mul_f32_e32 v64, v64, v214
	v_mul_f32_e32 v65, v65, v215
	v_cvt_pk_bf16_f32 v62, v62, v63
	v_cvt_pk_bf16_f32 v63, v64, v65
	global_store_dwordx2 v235, v[62:63], s[6:7]
	s_waitcnt vmcnt(7) lgkmcnt(3)
	v_mul_f32_e32 v34, v34, v216
	v_mul_f32_e32 v35, v35, v217
	v_mul_f32_e32 v36, v36, v218
	v_mul_f32_e32 v37, v37, v219
	v_cvt_pk_bf16_f32 v34, v34, v35
	v_cvt_pk_bf16_f32 v35, v36, v37
	global_store_dwordx2 v236, v[34:35], s[6:7]
	s_waitcnt vmcnt(7) lgkmcnt(2)
	v_mul_f32_e32 v38, v38, v220
	v_mul_f32_e32 v39, v39, v221
	v_mul_f32_e32 v40, v40, v222
	v_mul_f32_e32 v41, v41, v223
	v_cvt_pk_bf16_f32 v38, v38, v39
	v_cvt_pk_bf16_f32 v39, v40, v41
	global_store_dwordx2 v237, v[38:39], s[6:7]
	s_waitcnt vmcnt(7) lgkmcnt(1)
	v_mul_f32_e32 v42, v42, v224
	v_mul_f32_e32 v43, v43, v225
	v_mul_f32_e32 v44, v44, v226
	v_mul_f32_e32 v45, v45, v227
	v_cvt_pk_bf16_f32 v42, v42, v43
	v_cvt_pk_bf16_f32 v43, v44, v45
	global_store_dwordx2 v238, v[42:43], s[6:7]
	s_waitcnt vmcnt(7) lgkmcnt(0)
	v_mul_f32_e32 v46, v46, v228
	v_mul_f32_e32 v47, v47, v229
	v_mul_f32_e32 v48, v48, v230
	v_mul_f32_e32 v49, v49, v231
	v_cvt_pk_bf16_f32 v46, v46, v47
	v_cvt_pk_bf16_f32 v47, v48, v49
	global_store_dwordx2 v239, v[46:47], s[6:7]
	ds_write_b128 v147, v[18:21]
	ds_write_b128 v147, v[22:25] offset:32
	ds_write_b128 v147, v[26:29] offset:64
	ds_write_b128 v147, v[30:33] offset:96
	ds_write_b128 v147, v[2:5] offset:128
	ds_write_b128 v147, v[6:9] offset:160
	ds_write_b128 v147, v[10:13] offset:192
	ds_write_b128 v147, v[14:17] offset:224
	v_add_u32_e32 v240, 0x40, v104
	v_add_u32_e32 v241, 0xfffff000, v240
	v_lshrrev_b32_e32 v241, 11, v241
	v_mad_u32_u24 v241, v241, s26, s26
	v_lshlrev_b32_e32 v241, 2, v241
	v_or_b32_e32 v232, v240, v119
	v_or_b32_e32 v233, v240, v121
	v_or_b32_e32 v234, v240, v122
	v_or_b32_e32 v235, v240, v123
	v_or_b32_e32 v236, v240, v124
	v_or_b32_e32 v237, v240, v125
	v_or_b32_e32 v238, v240, v126
	v_or_b32_e32 v239, v240, v127
	v_cmp_lt_i32_e64 s[82:83], s27, v232
	v_cmp_lt_i32_e64 s[84:85], s27, v233
	v_cmp_lt_i32_e64 s[86:87], s27, v234
	v_cmp_lt_i32_e64 s[88:89], s27, v235
	v_cmp_lt_i32_e64 s[90:91], s27, v236
	v_cmp_lt_i32_e64 s[92:93], s27, v237
	v_cmp_lt_i32_e64 s[94:95], s27, v238
	v_cmp_lt_i32_e64 s[96:97], s27, v239
	s_waitcnt lgkmcnt(0)
	v_cndmask_b32_e64 v200, 0, v241, s[82:83]
	v_cndmask_b32_e64 v204, 0, v241, s[84:85]
	v_cndmask_b32_e64 v208, 0, v241, s[86:87]
	v_cndmask_b32_e64 v212, 0, v241, s[88:89]
	v_cndmask_b32_e64 v216, 0, v241, s[90:91]
	v_cndmask_b32_e64 v220, 0, v241, s[92:93]
	v_cndmask_b32_e64 v224, 0, v241, s[94:95]
	v_cndmask_b32_e64 v228, 0, v241, s[96:97]
	v_add_u32_e32 v200, v200, v242
	v_add_u32_e32 v204, v204, v242
	v_add_u32_e32 v208, v208, v242
	v_add_u32_e32 v212, v212, v242
	v_add_u32_e32 v216, v216, v242
	v_add_u32_e32 v220, v220, v242
	v_add_u32_e32 v224, v224, v242
	v_add_u32_e32 v228, v228, v242
	ds_read_b128 v[18:21], v149
	global_load_dwordx4 v[200:203], v200, s[4:5]
	ds_read_b128 v[22:25], v149 offset:1088
	global_load_dwordx4 v[204:207], v204, s[4:5]
	ds_read_b128 v[26:29], v149 offset:2176
	global_load_dwordx4 v[208:211], v208, s[4:5]
	ds_read_b128 v[30:33], v149 offset:3264
	global_load_dwordx4 v[212:215], v212, s[4:5]
	ds_read_b128 v[2:5], v149 offset:4352
	global_load_dwordx4 v[216:219], v216, s[4:5]
	ds_read_b128 v[6:9], v149 offset:5440
	global_load_dwordx4 v[220:223], v220, s[4:5]
	ds_read_b128 v[10:13], v149 offset:6528
	global_load_dwordx4 v[224:227], v224, s[4:5]
	ds_read_b128 v[14:17], v149 offset:7616
	global_load_dwordx4 v[228:231], v228, s[4:5]
	v_lshl_add_u32 v232, v232, 11, v243
	v_lshl_add_u32 v233, v233, 11, v243
	v_lshl_add_u32 v234, v234, 11, v243
	v_lshl_add_u32 v235, v235, 11, v243
	v_lshl_add_u32 v236, v236, 11, v243
	v_lshl_add_u32 v237, v237, 11, v243
	v_lshl_add_u32 v238, v238, 11, v243
	v_lshl_add_u32 v239, v239, 11, v243
	s_waitcnt vmcnt(7) lgkmcnt(7)
	v_mul_f32_e32 v18, v18, v200
	v_mul_f32_e32 v19, v19, v201
	v_mul_f32_e32 v20, v20, v202
	v_mul_f32_e32 v21, v21, v203
	v_cvt_pk_bf16_f32 v18, v18, v19
	v_cvt_pk_bf16_f32 v19, v20, v21
	global_store_dwordx2 v232, v[18:19], s[6:7]
	s_waitcnt vmcnt(7) lgkmcnt(6)
	v_mul_f32_e32 v22, v22, v204
	v_mul_f32_e32 v23, v23, v205
	v_mul_f32_e32 v24, v24, v206
	v_mul_f32_e32 v25, v25, v207
	v_cvt_pk_bf16_f32 v22, v22, v23
	v_cvt_pk_bf16_f32 v23, v24, v25
	global_store_dwordx2 v233, v[22:23], s[6:7]
	s_waitcnt vmcnt(7) lgkmcnt(5)
	v_mul_f32_e32 v26, v26, v208
	v_mul_f32_e32 v27, v27, v209
	v_mul_f32_e32 v28, v28, v210
	v_mul_f32_e32 v29, v29, v211
	v_cvt_pk_bf16_f32 v26, v26, v27
	v_cvt_pk_bf16_f32 v27, v28, v29
	global_store_dwordx2 v234, v[26:27], s[6:7]
	s_waitcnt vmcnt(7) lgkmcnt(4)
	v_mul_f32_e32 v30, v30, v212
	v_mul_f32_e32 v31, v31, v213
	v_mul_f32_e32 v32, v32, v214
	v_mul_f32_e32 v33, v33, v215
	v_cvt_pk_bf16_f32 v30, v30, v31
	v_cvt_pk_bf16_f32 v31, v32, v33
	global_store_dwordx2 v235, v[30:31], s[6:7]
	s_waitcnt vmcnt(7) lgkmcnt(3)
	v_mul_f32_e32 v2, v2, v216
	v_mul_f32_e32 v3, v3, v217
	v_mul_f32_e32 v4, v4, v218
	v_mul_f32_e32 v5, v5, v219
	v_cvt_pk_bf16_f32 v2, v2, v3
	v_cvt_pk_bf16_f32 v3, v4, v5
	global_store_dwordx2 v236, v[2:3], s[6:7]
	s_waitcnt vmcnt(7) lgkmcnt(2)
	v_mul_f32_e32 v6, v6, v220
	v_mul_f32_e32 v7, v7, v221
	v_mul_f32_e32 v8, v8, v222
	v_mul_f32_e32 v9, v9, v223
	v_cvt_pk_bf16_f32 v6, v6, v7
	v_cvt_pk_bf16_f32 v7, v8, v9
	global_store_dwordx2 v237, v[6:7], s[6:7]
	s_waitcnt vmcnt(7) lgkmcnt(1)
	v_mul_f32_e32 v10, v10, v224
	v_mul_f32_e32 v11, v11, v225
	v_mul_f32_e32 v12, v12, v226
	v_mul_f32_e32 v13, v13, v227
	v_cvt_pk_bf16_f32 v10, v10, v11
	v_cvt_pk_bf16_f32 v11, v12, v13
	global_store_dwordx2 v238, v[10:11], s[6:7]
	s_waitcnt vmcnt(7) lgkmcnt(0)
	v_mul_f32_e32 v14, v14, v228
	v_mul_f32_e32 v15, v15, v229
	v_mul_f32_e32 v16, v16, v230
	v_mul_f32_e32 v17, v17, v231
	v_cvt_pk_bf16_f32 v14, v14, v15
	v_cvt_pk_bf16_f32 v15, v16, v17
	global_store_dwordx2 v239, v[14:15], s[6:7]
	s_waitcnt lgkmcnt(0)
	s_load_dword s10, s[8:9], 0x0
	s_waitcnt lgkmcnt(0)
	s_add_i32 s28, s10, s28
	s_cmpk_lt_i32 s28, 0x200
	s_cbranch_scc1 .LBB0_489

.LBB0_540:
	s_or_b64 exec, exec, s[10:11]
	v_mov_b32_e32 v5, 0x2000
	v_mov_b32_e32 v6, 1
	s_waitcnt vmcnt(0)
	global_atomic_add v5, v6, s[6:7] offset:1024
	buffer_inv sc1
	s_waitcnt vmcnt(0)

.LBB0_626:
	s_ashr_i32 s4, s56, 31
	s_lshr_b32 s4, s4, 26
	s_add_i32 s4, s56, s4
	s_ashr_i32 s6, s4, 6
	s_and_b32 s4, s4, 0x3ffffc0
	s_sub_i32 s4, s56, s4
	s_mulk_i32 s4, 0xc0
	v_add_u32_e32 v2, s4, v147
	s_lshr_b32 s7, s4, 6
	s_lshl_b32 s5, s6, 7
	v_ashrrev_i32_e32 v3, 31, v2
	s_add_i32 s7, s7, s6
	v_lshlrev_b64 v[2:3], 11, v[2:3]
	v_or_b32_e32 v4, s5, v147
	s_lshl_b32 s6, s7, 6
	s_lshl_b32 s7, s7, 7
	v_ashrrev_i32_e32 v5, 31, v4
	v_lshl_add_u64 v[138:139], v[100:101], 0, v[2:3]
	s_and_b32 s12, s7, 0x780
	v_readfirstlane_b32 s7, v149
	v_lshlrev_b64 v[4:5], 11, v[4:5]
	v_lshl_add_u64 v[2:3], v[138:139], 0, s[12:13]
	s_mov_b32 m0, s7
	v_readfirstlane_b32 s7, v172
	v_lshl_add_u64 v[140:141], v[102:103], 0, v[4:5]
	s_waitcnt vmcnt(0)
	s_barrier
	s_load_dwordx2 s[66:67], s[0:1], 0x90
	s_load_dwordx2 s[68:69], s[0:1], 0xd8
	v_and_b32_e32 v201, 0x3ff, v0
	v_readfirstlane_b32 s80, v0
	v_and_b32_e32 v200, 31, v201
	v_bfe_u32 v214, v201, 1, 3
	v_bfe_u32 v213, v201, 5, 1
	v_xor_b32_e32 v214, v214, v213
	v_lshlrev_b32_e32 v214, 4, v214
	s_and_b32 s80, s80, 0x3ff
	s_lshr_b32 s83, s80, 6
	s_lshl_b32 s80, s80, 4
	s_lshr_b32 s84, s83, 1
	s_and_b32 s83, s83, 1
	s_mul_i32 s84, s84, 0x3000
	s_lshl_b32 s83, s83, 13
	s_add_u32 s83, s83, 0xc000
	v_lshlrev_b32_e32 v200, 7, v200
	v_or_b32_e32 v200, v200, v214
	v_add_u32_e32 v215, s84, v200
	v_add_u32_e32 v211, s83, v200
	v_xor_b32_e32 v214, 0x20, v215
	v_xor_b32_e32 v210, 0x20, v211
	v_xor_b32_e32 v213, 0x40, v215
	v_xor_b32_e32 v209, 0x40, v211
	v_xor_b32_e32 v212, 0x60, v215
	v_xor_b32_e32 v208, 0x60, v211
	v_bfe_u32 v200, v201, 4, 3
	v_and_b32_e32 v206, 7, v201
	v_xor_b32_e32 v200, v200, v206
	v_lshlrev_b32_e32 v200, 4, v200
	v_lshrrev_b32_e32 v206, 3, v201
	v_lshl_or_b32 v207, v206, 11, v200
	v_add_u32_e32 v206, 0x10000, v207
	v_add_u32_e32 v205, 0x20000, v207
	v_add_u32_e32 v204, 0x30000, v207
	v_add_u32_e32 v203, 0x40000, v207
	v_add_u32_e32 v202, 0x50000, v207
	s_lshr_b32 s83, s56, 6
	s_and_b32 s84, s56, 63
	s_mov_b32 s79, 0
	s_mul_i32 s84, s84, 0x60000
	s_lshl_b32 s83, s83, 18
	s_waitcnt lgkmcnt(0)
	s_add_u32 s66, s66, s84
	s_addc_u32 s67, s67, 0
	s_add_u32 s68, s68, s83
	s_addc_u32 s69, s69, 0
	s_add_u32 s83, s79, 0
	s_and_b32 s83, s83, 15
	s_lshl_b32 s83, s83, 7
	s_add_u32 s70, s66, s83
	s_addc_u32 s71, s67, 0
	s_add_u32 s72, s68, s83
	s_addc_u32 s73, s69, 0
	s_add_u32 s81, s80, 0x0
	s_add_u32 s82, s80, 0xc000
	s_add_u32 m0, s81, 0x0
	s_nop 0
	global_load_lds_dwordx4 v207, s[70:71]
	s_add_u32 m0, s81, 0x1000
	s_nop 0
	global_load_lds_dwordx4 v206, s[70:71]
	s_add_u32 m0, s81, 0x2000
	s_nop 0
	global_load_lds_dwordx4 v205, s[70:71]
	s_add_u32 m0, s81, 0x3000
	s_nop 0
	global_load_lds_dwordx4 v204, s[70:71]
	s_add_u32 m0, s81, 0x4000
	s_nop 0
	global_load_lds_dwordx4 v203, s[70:71]
	s_add_u32 m0, s81, 0x5000
	s_nop 0
	global_load_lds_dwordx4 v202, s[70:71]
	s_add_u32 m0, s82, 0x0
	s_nop 0
	global_load_lds_dwordx4 v207, s[72:73]
	s_add_u32 m0, s82, 0x1000
	s_nop 0
	global_load_lds_dwordx4 v206, s[72:73]
	s_add_u32 m0, s82, 0x2000
	s_nop 0
	global_load_lds_dwordx4 v205, s[72:73]
	s_add_u32 m0, s82, 0x3000
	s_nop 0
	global_load_lds_dwordx4 v204, s[72:73]
	s_add_u32 s83, s79, 1
	s_and_b32 s83, s83, 15
	s_lshl_b32 s83, s83, 7
	s_add_u32 s70, s66, s83
	s_addc_u32 s71, s67, 0
	s_add_u32 s72, s68, s83
	s_addc_u32 s73, s69, 0
	s_add_u32 s81, s80, 0x6000
	s_add_u32 s82, s80, 0x10000
	s_add_u32 m0, s81, 0x0
	s_nop 0
	global_load_lds_dwordx4 v207, s[70:71]
	s_add_u32 m0, s81, 0x1000
	s_nop 0
	global_load_lds_dwordx4 v206, s[70:71]
	s_add_u32 m0, s81, 0x2000
	s_nop 0
	global_load_lds_dwordx4 v205, s[70:71]
	s_add_u32 m0, s81, 0x3000
	s_nop 0
	global_load_lds_dwordx4 v204, s[70:71]
	s_add_u32 m0, s81, 0x4000
	s_nop 0
	global_load_lds_dwordx4 v203, s[70:71]
	s_add_u32 m0, s81, 0x5000
	s_nop 0
	global_load_lds_dwordx4 v202, s[70:71]
	s_add_u32 m0, s82, 0x0
	s_nop 0
	global_load_lds_dwordx4 v207, s[72:73]
	s_add_u32 m0, s82, 0x1000
	s_nop 0
	global_load_lds_dwordx4 v206, s[72:73]
	s_add_u32 m0, s82, 0x2000
	s_nop 0
	global_load_lds_dwordx4 v205, s[72:73]
	s_add_u32 m0, s82, 0x3000
	s_nop 0
	global_load_lds_dwordx4 v204, s[72:73]
	v_mov_b32_e32 v2, 0
	v_mov_b32_e32 v3, 0
	v_mov_b32_e32 v4, 0
	v_mov_b32_e32 v5, 0
	v_mov_b32_e32 v6, 0
	v_mov_b32_e32 v7, 0
	v_mov_b32_e32 v8, 0
	v_mov_b32_e32 v9, 0
	v_mov_b32_e32 v10, 0
	v_mov_b32_e32 v11, 0
	v_mov_b32_e32 v12, 0
	v_mov_b32_e32 v13, 0
	v_mov_b32_e32 v14, 0
	v_mov_b32_e32 v15, 0
	v_mov_b32_e32 v16, 0
	v_mov_b32_e32 v17, 0
	v_mov_b32_e32 v18, 0
	v_mov_b32_e32 v19, 0
	v_mov_b32_e32 v20, 0
	v_mov_b32_e32 v21, 0
	v_mov_b32_e32 v22, 0
	v_mov_b32_e32 v23, 0
	v_mov_b32_e32 v24, 0
	v_mov_b32_e32 v25, 0
	v_mov_b32_e32 v26, 0
	v_mov_b32_e32 v27, 0
	v_mov_b32_e32 v28, 0
	v_mov_b32_e32 v29, 0
	v_mov_b32_e32 v30, 0
	v_mov_b32_e32 v31, 0
	v_mov_b32_e32 v32, 0
	v_mov_b32_e32 v33, 0
	v_mov_b32_e32 v34, 0
	v_mov_b32_e32 v35, 0
	v_mov_b32_e32 v36, 0
	v_mov_b32_e32 v37, 0
	v_mov_b32_e32 v38, 0
	v_mov_b32_e32 v39, 0
	v_mov_b32_e32 v40, 0
	v_mov_b32_e32 v41, 0
	v_mov_b32_e32 v42, 0
	v_mov_b32_e32 v43, 0
	v_mov_b32_e32 v44, 0
	v_mov_b32_e32 v45, 0
	v_mov_b32_e32 v46, 0
	v_mov_b32_e32 v47, 0
	v_mov_b32_e32 v48, 0
	v_mov_b32_e32 v49, 0
	v_mov_b32_e32 v50, 0
	v_mov_b32_e32 v51, 0
	v_mov_b32_e32 v52, 0
	v_mov_b32_e32 v53, 0
	v_mov_b32_e32 v54, 0
	v_mov_b32_e32 v55, 0
	v_mov_b32_e32 v56, 0
	v_mov_b32_e32 v57, 0
	v_mov_b32_e32 v58, 0
	v_mov_b32_e32 v59, 0
	v_mov_b32_e32 v60, 0
	v_mov_b32_e32 v61, 0
	v_mov_b32_e32 v62, 0
	v_mov_b32_e32 v63, 0
	v_mov_b32_e32 v64, 0
	v_mov_b32_e32 v65, 0
	v_mov_b32_e32 v66, 0
	v_mov_b32_e32 v67, 0
	v_mov_b32_e32 v68, 0
	v_mov_b32_e32 v69, 0
	v_mov_b32_e32 v70, 0
	v_mov_b32_e32 v71, 0
	v_mov_b32_e32 v72, 0
	v_mov_b32_e32 v73, 0
	v_mov_b32_e32 v74, 0
	v_mov_b32_e32 v75, 0
	v_mov_b32_e32 v76, 0
	v_mov_b32_e32 v77, 0
	v_mov_b32_e32 v78, 0
	v_mov_b32_e32 v79, 0
	v_mov_b32_e32 v80, 0
	v_mov_b32_e32 v81, 0
	v_mov_b32_e32 v82, 0
	v_mov_b32_e32 v83, 0
	v_mov_b32_e32 v84, 0
	v_mov_b32_e32 v85, 0
	v_mov_b32_e32 v86, 0
	v_mov_b32_e32 v87, 0
	v_mov_b32_e32 v88, 0
	v_mov_b32_e32 v89, 0
	v_mov_b32_e32 v90, 0
	v_mov_b32_e32 v91, 0
	v_mov_b32_e32 v92, 0
	v_mov_b32_e32 v93, 0
	v_mov_b32_e32 v94, 0
	v_mov_b32_e32 v95, 0
	v_mov_b32_e32 v96, 0
	v_mov_b32_e32 v97, 0
	s_waitcnt vmcnt(10)
	s_barrier
	ds_read_b128 v[240:243], v211 offset:0
	ds_read_b128 v[252:255], v215 offset:0
	ds_read_b128 v[236:239], v211 offset:4096
	ds_read_b128 v[248:251], v215 offset:4096
	ds_read_b128 v[244:247], v215 offset:8192
	s_mov_b32 s78, 0
.Lgm_ph7_loop:
	s_waitcnt lgkmcnt(1)
	v_mfma_f32_32x32x16_bf16 v[82:97], v[240:243], v[252:255], v[82:97]
	ds_read_b128 v[220:223], v210 offset:0
	v_mfma_f32_32x32x16_bf16 v[66:81], v[236:239], v[252:255], v[66:81]
	ds_read_b128 v[232:235], v214 offset:0
	v_mfma_f32_32x32x16_bf16 v[50:65], v[240:243], v[248:251], v[50:65]
	ds_read_b128 v[216:219], v210 offset:4096
	v_mfma_f32_32x32x16_bf16 v[34:49], v[236:239], v[248:251], v[34:49]
	ds_read_b128 v[228:231], v214 offset:4096
	s_waitcnt lgkmcnt(4)
	v_mfma_f32_32x32x16_bf16 v[18:33], v[240:243], v[244:247], v[18:33]
	ds_read_b128 v[224:227], v214 offset:8192
	v_mfma_f32_32x32x16_bf16 v[2:17], v[236:239], v[244:247], v[2:17]
	s_waitcnt lgkmcnt(1)
	v_mfma_f32_32x32x16_bf16 v[82:97], v[220:223], v[232:235], v[82:97]
	ds_read_b128 v[240:243], v209 offset:0
	v_mfma_f32_32x32x16_bf16 v[66:81], v[216:219], v[232:235], v[66:81]
	ds_read_b128 v[252:255], v213 offset:0
	v_mfma_f32_32x32x16_bf16 v[50:65], v[220:223], v[228:231], v[50:65]
	ds_read_b128 v[236:239], v209 offset:4096
	v_mfma_f32_32x32x16_bf16 v[34:49], v[216:219], v[228:231], v[34:49]
	ds_read_b128 v[248:251], v213 offset:4096
	s_waitcnt lgkmcnt(4)
	v_mfma_f32_32x32x16_bf16 v[18:33], v[220:223], v[224:227], v[18:33]
	ds_read_b128 v[244:247], v213 offset:8192
	v_mfma_f32_32x32x16_bf16 v[2:17], v[216:219], v[224:227], v[2:17]
	s_waitcnt lgkmcnt(1)
	v_mfma_f32_32x32x16_bf16 v[82:97], v[240:243], v[252:255], v[82:97]
	ds_read_b128 v[220:223], v208 offset:0
	s_add_u32 s83, s79, s78
	s_add_u32 s83, s83, 2
	s_and_b32 s83, s83, 15
	v_mfma_f32_32x32x16_bf16 v[66:81], v[236:239], v[252:255], v[66:81]
	ds_read_b128 v[232:235], v212 offset:0
	s_lshl_b32 s83, s83, 7
	s_add_u32 s70, s66, s83
	v_mfma_f32_32x32x16_bf16 v[50:65], v[240:243], v[248:251], v[50:65]
	ds_read_b128 v[216:219], v208 offset:4096
	s_addc_u32 s71, s67, 0
	s_add_u32 s72, s68, s83
	v_mfma_f32_32x32x16_bf16 v[34:49], v[236:239], v[248:251], v[34:49]
	ds_read_b128 v[228:231], v212 offset:4096
	s_addc_u32 s73, s69, 0
	s_add_u32 s81, s80, 0x0
	s_add_u32 s82, s80, 0xc000
	s_waitcnt lgkmcnt(4)
	v_mfma_f32_32x32x16_bf16 v[18:33], v[240:243], v[244:247], v[18:33]
	ds_read_b128 v[224:227], v212 offset:8192
	v_mfma_f32_32x32x16_bf16 v[2:17], v[236:239], v[244:247], v[2:17]
	s_waitcnt vmcnt(0) lgkmcnt(0)
	s_barrier
	v_mfma_f32_32x32x16_bf16 v[82:97], v[220:223], v[232:235], v[82:97]
	s_add_u32 m0, s81, 0x0
	ds_read_b128 v[240:243], v211 offset:16384
	global_load_lds_dwordx4 v207, s[70:71]
	s_add_u32 m0, s81, 0x1000
	s_nop 0
	global_load_lds_dwordx4 v206, s[70:71]
	v_mfma_f32_32x32x16_bf16 v[66:81], v[216:219], v[232:235], v[66:81]
	s_add_u32 m0, s81, 0x2000
	ds_read_b128 v[252:255], v215 offset:24576
	global_load_lds_dwordx4 v205, s[70:71]
	s_add_u32 m0, s81, 0x3000
	s_nop 0
	global_load_lds_dwordx4 v204, s[70:71]
	v_mfma_f32_32x32x16_bf16 v[50:65], v[220:223], v[228:231], v[50:65]
	s_add_u32 m0, s81, 0x4000
	ds_read_b128 v[236:239], v211 offset:20480
	global_load_lds_dwordx4 v203, s[70:71]
	s_add_u32 m0, s81, 0x5000
	s_nop 0
	global_load_lds_dwordx4 v202, s[70:71]
	v_mfma_f32_32x32x16_bf16 v[34:49], v[216:219], v[228:231], v[34:49]
	s_add_u32 m0, s82, 0x0
	ds_read_b128 v[248:251], v215 offset:28672
	global_load_lds_dwordx4 v207, s[72:73]
	s_add_u32 m0, s82, 0x1000
	s_nop 0
	global_load_lds_dwordx4 v206, s[72:73]
	v_mfma_f32_32x32x16_bf16 v[18:33], v[220:223], v[224:227], v[18:33]
	s_add_u32 m0, s82, 0x2000
	ds_read_b128 v[244:247], v215 offset:32768
	global_load_lds_dwordx4 v205, s[72:73]
	s_add_u32 m0, s82, 0x3000
	s_nop 0
	global_load_lds_dwordx4 v204, s[72:73]
	v_mfma_f32_32x32x16_bf16 v[2:17], v[216:219], v[224:227], v[2:17]
	s_waitcnt lgkmcnt(1)
	v_mfma_f32_32x32x16_bf16 v[82:97], v[240:243], v[252:255], v[82:97]
	ds_read_b128 v[220:223], v210 offset:16384
	v_mfma_f32_32x32x16_bf16 v[66:81], v[236:239], v[252:255], v[66:81]
	ds_read_b128 v[232:235], v214 offset:24576
	v_mfma_f32_32x32x16_bf16 v[50:65], v[240:243], v[248:251], v[50:65]
	ds_read_b128 v[216:219], v210 offset:20480
	v_mfma_f32_32x32x16_bf16 v[34:49], v[236:239], v[248:251], v[34:49]
	ds_read_b128 v[228:231], v214 offset:28672
	s_waitcnt lgkmcnt(4)
	v_mfma_f32_32x32x16_bf16 v[18:33], v[240:243], v[244:247], v[18:33]
	ds_read_b128 v[224:227], v214 offset:32768
	v_mfma_f32_32x32x16_bf16 v[2:17], v[236:239], v[244:247], v[2:17]
	s_waitcnt lgkmcnt(1)
	v_mfma_f32_32x32x16_bf16 v[82:97], v[220:223], v[232:235], v[82:97]
	ds_read_b128 v[240:243], v209 offset:16384
	v_mfma_f32_32x32x16_bf16 v[66:81], v[216:219], v[232:235], v[66:81]
	ds_read_b128 v[252:255], v213 offset:24576
	v_mfma_f32_32x32x16_bf16 v[50:65], v[220:223], v[228:231], v[50:65]
	ds_read_b128 v[236:239], v209 offset:20480
	v_mfma_f32_32x32x16_bf16 v[34:49], v[216:219], v[228:231], v[34:49]
	ds_read_b128 v[248:251], v213 offset:28672
	s_waitcnt lgkmcnt(4)
	v_mfma_f32_32x32x16_bf16 v[18:33], v[220:223], v[224:227], v[18:33]
	ds_read_b128 v[244:247], v213 offset:32768
	v_mfma_f32_32x32x16_bf16 v[2:17], v[216:219], v[224:227], v[2:17]
	s_waitcnt lgkmcnt(1)
	v_mfma_f32_32x32x16_bf16 v[82:97], v[240:243], v[252:255], v[82:97]
	ds_read_b128 v[220:223], v208 offset:16384
	s_add_u32 s83, s79, s78
	s_add_u32 s83, s83, 3
	s_and_b32 s83, s83, 15
	v_mfma_f32_32x32x16_bf16 v[66:81], v[236:239], v[252:255], v[66:81]
	ds_read_b128 v[232:235], v212 offset:24576
	s_lshl_b32 s83, s83, 7
	s_add_u32 s70, s66, s83
	v_mfma_f32_32x32x16_bf16 v[50:65], v[240:243], v[248:251], v[50:65]
	ds_read_b128 v[216:219], v208 offset:20480
	s_addc_u32 s71, s67, 0
	s_add_u32 s72, s68, s83
	v_mfma_f32_32x32x16_bf16 v[34:49], v[236:239], v[248:251], v[34:49]
	ds_read_b128 v[228:231], v212 offset:28672
	s_addc_u32 s73, s69, 0
	s_add_u32 s81, s80, 0x6000
	s_add_u32 s82, s80, 0x10000
	s_waitcnt lgkmcnt(4)
	v_mfma_f32_32x32x16_bf16 v[18:33], v[240:243], v[244:247], v[18:33]
	ds_read_b128 v[224:227], v212 offset:32768
	v_mfma_f32_32x32x16_bf16 v[2:17], v[236:239], v[244:247], v[2:17]
	s_waitcnt vmcnt(0) lgkmcnt(0)
	s_barrier
	v_mfma_f32_32x32x16_bf16 v[82:97], v[220:223], v[232:235], v[82:97]
	s_add_u32 m0, s81, 0x0
	ds_read_b128 v[240:243], v211 offset:0
	global_load_lds_dwordx4 v207, s[70:71]
	s_add_u32 m0, s81, 0x1000
	s_nop 0
	global_load_lds_dwordx4 v206, s[70:71]
	v_mfma_f32_32x32x16_bf16 v[66:81], v[216:219], v[232:235], v[66:81]
	s_add_u32 m0, s81, 0x2000
	ds_read_b128 v[252:255], v215 offset:0
	global_load_lds_dwordx4 v205, s[70:71]
	s_add_u32 m0, s81, 0x3000
	s_nop 0
	global_load_lds_dwordx4 v204, s[70:71]
	v_mfma_f32_32x32x16_bf16 v[50:65], v[220:223], v[228:231], v[50:65]
	s_add_u32 m0, s81, 0x4000
	ds_read_b128 v[236:239], v211 offset:4096
	global_load_lds_dwordx4 v203, s[70:71]
	s_add_u32 m0, s81, 0x5000
	s_nop 0
	global_load_lds_dwordx4 v202, s[70:71]
	v_mfma_f32_32x32x16_bf16 v[34:49], v[216:219], v[228:231], v[34:49]
	s_add_u32 m0, s82, 0x0
	ds_read_b128 v[248:251], v215 offset:4096
	global_load_lds_dwordx4 v207, s[72:73]
	s_add_u32 m0, s82, 0x1000
	s_nop 0
	global_load_lds_dwordx4 v206, s[72:73]
	v_mfma_f32_32x32x16_bf16 v[18:33], v[220:223], v[224:227], v[18:33]
	s_add_u32 m0, s82, 0x2000
	ds_read_b128 v[244:247], v215 offset:8192
	global_load_lds_dwordx4 v205, s[72:73]
	s_add_u32 m0, s82, 0x3000
	s_nop 0
	global_load_lds_dwordx4 v204, s[72:73]
	v_mfma_f32_32x32x16_bf16 v[2:17], v[216:219], v[224:227], v[2:17]
	s_add_u32 s78, s78, 2
	s_cmp_lt_u32 s78, 14
	s_cbranch_scc1 .Lgm_ph7_loop
	s_waitcnt lgkmcnt(1)
	v_mfma_f32_32x32x16_bf16 v[82:97], v[240:243], v[252:255], v[82:97]
	ds_read_b128 v[220:223], v210 offset:0
	v_mfma_f32_32x32x16_bf16 v[66:81], v[236:239], v[252:255], v[66:81]
	ds_read_b128 v[232:235], v214 offset:0
	v_mfma_f32_32x32x16_bf16 v[50:65], v[240:243], v[248:251], v[50:65]
	ds_read_b128 v[216:219], v210 offset:4096
	v_mfma_f32_32x32x16_bf16 v[34:49], v[236:239], v[248:251], v[34:49]
	ds_read_b128 v[228:231], v214 offset:4096
	s_waitcnt lgkmcnt(4)
	v_mfma_f32_32x32x16_bf16 v[18:33], v[240:243], v[244:247], v[18:33]
	ds_read_b128 v[224:227], v214 offset:8192
	v_mfma_f32_32x32x16_bf16 v[2:17], v[236:239], v[244:247], v[2:17]
	s_waitcnt lgkmcnt(1)
	v_mfma_f32_32x32x16_bf16 v[82:97], v[220:223], v[232:235], v[82:97]
	ds_read_b128 v[240:243], v209 offset:0
	v_mfma_f32_32x32x16_bf16 v[66:81], v[216:219], v[232:235], v[66:81]
	ds_read_b128 v[252:255], v213 offset:0
	v_mfma_f32_32x32x16_bf16 v[50:65], v[220:223], v[228:231], v[50:65]
	ds_read_b128 v[236:239], v209 offset:4096
	v_mfma_f32_32x32x16_bf16 v[34:49], v[216:219], v[228:231], v[34:49]
	ds_read_b128 v[248:251], v213 offset:4096
	s_waitcnt lgkmcnt(4)
	v_mfma_f32_32x32x16_bf16 v[18:33], v[220:223], v[224:227], v[18:33]
	ds_read_b128 v[244:247], v213 offset:8192
	v_mfma_f32_32x32x16_bf16 v[2:17], v[216:219], v[224:227], v[2:17]
	s_waitcnt lgkmcnt(1)
	v_mfma_f32_32x32x16_bf16 v[82:97], v[240:243], v[252:255], v[82:97]
	ds_read_b128 v[220:223], v208 offset:0
	v_mfma_f32_32x32x16_bf16 v[66:81], v[236:239], v[252:255], v[66:81]
	ds_read_b128 v[232:235], v212 offset:0
	v_mfma_f32_32x32x16_bf16 v[50:65], v[240:243], v[248:251], v[50:65]
	ds_read_b128 v[216:219], v208 offset:4096
	v_mfma_f32_32x32x16_bf16 v[34:49], v[236:239], v[248:251], v[34:49]
	ds_read_b128 v[228:231], v212 offset:4096
	s_waitcnt lgkmcnt(4)
	v_mfma_f32_32x32x16_bf16 v[18:33], v[240:243], v[244:247], v[18:33]
	ds_read_b128 v[224:227], v212 offset:8192
	v_mfma_f32_32x32x16_bf16 v[2:17], v[236:239], v[244:247], v[2:17]
	s_waitcnt vmcnt(0) lgkmcnt(0)
	s_barrier
	v_mfma_f32_32x32x16_bf16 v[82:97], v[220:223], v[232:235], v[82:97]
	ds_read_b128 v[240:243], v211 offset:16384
	v_mfma_f32_32x32x16_bf16 v[66:81], v[216:219], v[232:235], v[66:81]
	ds_read_b128 v[252:255], v215 offset:24576
	v_mfma_f32_32x32x16_bf16 v[50:65], v[220:223], v[228:231], v[50:65]
	ds_read_b128 v[236:239], v211 offset:20480
	v_mfma_f32_32x32x16_bf16 v[34:49], v[216:219], v[228:231], v[34:49]
	ds_read_b128 v[248:251], v215 offset:28672
	v_mfma_f32_32x32x16_bf16 v[18:33], v[220:223], v[224:227], v[18:33]
	ds_read_b128 v[244:247], v215 offset:32768
	v_mfma_f32_32x32x16_bf16 v[2:17], v[216:219], v[224:227], v[2:17]
	s_waitcnt lgkmcnt(1)
	v_mfma_f32_32x32x16_bf16 v[82:97], v[240:243], v[252:255], v[82:97]
	ds_read_b128 v[220:223], v210 offset:16384
	v_mfma_f32_32x32x16_bf16 v[66:81], v[236:239], v[252:255], v[66:81]
	ds_read_b128 v[232:235], v214 offset:24576
	v_mfma_f32_32x32x16_bf16 v[50:65], v[240:243], v[248:251], v[50:65]
	ds_read_b128 v[216:219], v210 offset:20480
	v_mfma_f32_32x32x16_bf16 v[34:49], v[236:239], v[248:251], v[34:49]
	ds_read_b128 v[228:231], v214 offset:28672
	s_waitcnt lgkmcnt(4)
	v_mfma_f32_32x32x16_bf16 v[18:33], v[240:243], v[244:247], v[18:33]
	ds_read_b128 v[224:227], v214 offset:32768
	v_mfma_f32_32x32x16_bf16 v[2:17], v[236:239], v[244:247], v[2:17]
	s_waitcnt lgkmcnt(1)
	v_mfma_f32_32x32x16_bf16 v[82:97], v[220:223], v[232:235], v[82:97]
	ds_read_b128 v[240:243], v209 offset:16384
	v_mfma_f32_32x32x16_bf16 v[66:81], v[216:219], v[232:235], v[66:81]
	ds_read_b128 v[252:255], v213 offset:24576
	v_mfma_f32_32x32x16_bf16 v[50:65], v[220:223], v[228:231], v[50:65]
	ds_read_b128 v[236:239], v209 offset:20480
	v_mfma_f32_32x32x16_bf16 v[34:49], v[216:219], v[228:231], v[34:49]
	ds_read_b128 v[248:251], v213 offset:28672
	s_waitcnt lgkmcnt(4)
	v_mfma_f32_32x32x16_bf16 v[18:33], v[220:223], v[224:227], v[18:33]
	ds_read_b128 v[244:247], v213 offset:32768
	v_mfma_f32_32x32x16_bf16 v[2:17], v[216:219], v[224:227], v[2:17]
	s_waitcnt lgkmcnt(1)
	v_mfma_f32_32x32x16_bf16 v[82:97], v[240:243], v[252:255], v[82:97]
	ds_read_b128 v[220:223], v208 offset:16384
	v_mfma_f32_32x32x16_bf16 v[66:81], v[236:239], v[252:255], v[66:81]
	ds_read_b128 v[232:235], v212 offset:24576
	v_mfma_f32_32x32x16_bf16 v[50:65], v[240:243], v[248:251], v[50:65]
	ds_read_b128 v[216:219], v208 offset:20480
	v_mfma_f32_32x32x16_bf16 v[34:49], v[236:239], v[248:251], v[34:49]
	ds_read_b128 v[228:231], v212 offset:28672
	s_waitcnt lgkmcnt(4)
	v_mfma_f32_32x32x16_bf16 v[18:33], v[240:243], v[244:247], v[18:33]
	ds_read_b128 v[224:227], v212 offset:32768
	v_mfma_f32_32x32x16_bf16 v[2:17], v[236:239], v[244:247], v[2:17]
	s_waitcnt vmcnt(0) lgkmcnt(0)
	s_barrier
	v_mfma_f32_32x32x16_bf16 v[82:97], v[220:223], v[232:235], v[82:97]
	v_mfma_f32_32x32x16_bf16 v[66:81], v[216:219], v[232:235], v[66:81]
	v_mfma_f32_32x32x16_bf16 v[50:65], v[220:223], v[228:231], v[50:65]
	v_mfma_f32_32x32x16_bf16 v[34:49], v[216:219], v[228:231], v[34:49]
	v_mfma_f32_32x32x16_bf16 v[18:33], v[220:223], v[224:227], v[18:33]
	v_mfma_f32_32x32x16_bf16 v[2:17], v[216:219], v[224:227], v[2:17]
	s_nop 7
	s_nop 7
	s_waitcnt lgkmcnt(0)
	v_add_u32_e32 v140, s4, v154
	v_add_u32_e32 v98, 0xfffff000, v140
	v_lshrrev_b32_e32 v98, 11, v98
	v_or_b32_e32 v138, s5, v162
	v_ashrrev_i32_e32 v141, 31, v140
	v_mul_u32_u24_e32 v98, 0x900, v98
	v_and_b32_e32 v139, 0x7ff, v140
	v_cmp_lt_i32_e64 s[6:7], s48, v140
	v_cmp_gt_i32_e64 s[8:9], s3, v140
	v_add3_u32 v139, v139, v98, s49
	v_mad_i64_i32 v[152:153], s[4:5], v140, s50, 0
	v_cmp_gt_i32_e64 s[10:11], s51, v138
	v_lshlrev_b64 v[142:143], 11, v[140:141]
	v_lshlrev_b64 v[144:145], 6, v[140:141]
	s_and_saveexec_b64 s[4:5], s[10:11]
	s_cbranch_execz .LBB0_656
	v_cmp_lt_i32_e32 vcc, s52, v138
	s_and_saveexec_b64 s[40:41], vcc
	s_xor_b64 s[40:41], exec, s[40:41]
	s_cbranch_execz .LBB0_654
	v_cmp_lt_u32_e32 vcc, s53, v138
	s_and_saveexec_b64 s[42:43], vcc
	s_xor_b64 s[42:43], exec, s[42:43]
	s_cbranch_execz .LBB0_632
	v_mul_f32_e32 v98, 0xbfb8aa3b, v82
	v_exp_f32_e32 v190, v98
	v_mul_f32_e32 v98, 0xbfb8aa3b, v83
	v_exp_f32_e32 v191, v98
	v_or_b32_e32 v98, v138, v104
	v_pk_add_f32 v[190:191], v[190:191], 1.0 op_sel_hi:[1,0]
	s_nop 0
	v_div_scale_f32 v141, s[44:45], v191, v191, v83
	v_rcp_f32_e32 v192, v141
	v_div_scale_f32 v193, vcc, v83, v191, v83
	v_fma_f32 v194, -v141, v192, 1.0
	v_fmac_f32_e32 v192, v194, v192
	v_mul_f32_e32 v194, v193, v192
	v_fma_f32 v195, -v141, v194, v193
	v_fmac_f32_e32 v194, v195, v192
	v_div_scale_f32 v195, s[44:45], v190, v190, v82
	v_rcp_f32_e32 v196, v195
	v_fma_f32 v141, -v141, v194, v193
	v_div_fmas_f32 v141, v141, v192, v194
	v_mul_f32_e32 v192, 0xbfb8aa3b, v84
	v_mul_f32_e32 v193, 0xbfb8aa3b, v85
	v_exp_f32_e32 v192, v192
	v_exp_f32_e32 v193, v193
	v_div_fixup_f32 v83, v141, v191, v83
	v_fma_f32 v141, -v195, v196, 1.0
	v_fmac_f32_e32 v196, v141, v196
	v_div_scale_f32 v141, vcc, v82, v190, v82
	v_mul_f32_e32 v191, v141, v196
	v_fma_f32 v194, -v195, v191, v141
	v_pk_add_f32 v[192:193], v[192:193], 1.0 op_sel_hi:[1,0]
	v_fmac_f32_e32 v191, v194, v196
	v_div_scale_f32 v194, s[44:45], v193, v193, v85
	v_fma_f32 v141, -v195, v191, v141
	v_rcp_f32_e32 v195, v194
	v_div_fmas_f32 v141, v141, v196, v191
	v_div_fixup_f32 v82, v141, v190, v82
	v_cvt_pk_bf16_f32 v190, v82, v83
	v_fma_f32 v82, -v194, v195, 1.0
	v_fmac_f32_e32 v195, v82, v195
	v_div_scale_f32 v82, vcc, v85, v193, v85
	v_mul_f32_e32 v83, v82, v195
	v_fma_f32 v141, -v194, v83, v82
	v_fmac_f32_e32 v83, v141, v195
	v_div_scale_f32 v141, s[44:45], v192, v192, v84
	v_rcp_f32_e32 v191, v141
	v_fma_f32 v82, -v194, v83, v82
	v_div_fmas_f32 v82, v82, v195, v83
	v_div_fixup_f32 v85, v82, v193, v85
	v_fma_f32 v82, -v141, v191, 1.0
	v_fmac_f32_e32 v191, v82, v191
	v_div_scale_f32 v82, vcc, v84, v192, v84
	v_mul_f32_e32 v193, v82, v191
	v_fma_f32 v83, -v141, v193, v82
	v_fmac_f32_e32 v193, v83, v191
	v_fma_f32 v141, -v141, v193, v82
	v_mul_f32_e32 v82, 0xbfb8aa3b, v86
	v_mul_f32_e32 v83, 0xbfb8aa3b, v87
	v_exp_f32_e32 v82, v82
	v_exp_f32_e32 v83, v83
	v_div_fmas_f32 v141, v141, v191, v193
	v_div_fixup_f32 v84, v141, v192, v84
	v_cvt_pk_bf16_f32 v191, v84, v85
	v_pk_add_f32 v[84:85], v[82:83], 1.0 op_sel_hi:[1,0]
	v_lshl_add_u64 v[82:83], s[14:15], 0, v[142:143]
	v_div_scale_f32 v141, s[44:45], v85, v85, v87
	v_rcp_f32_e32 v192, v141
	v_lshl_add_u64 v[82:83], v[98:99], 1, v[82:83]
	global_store_dwordx2 v[82:83], v[190:191], off offset:-1664
	v_fma_f32 v98, -v141, v192, 1.0
	v_fmac_f32_e32 v192, v98, v192
	v_div_scale_f32 v98, vcc, v87, v85, v87
	v_mul_f32_e32 v190, v98, v192
	v_fma_f32 v191, -v141, v190, v98
	v_fmac_f32_e32 v190, v191, v192
	v_fma_f32 v98, -v141, v190, v98
	v_div_scale_f32 v141, s[44:45], v84, v84, v86
	v_rcp_f32_e32 v193, v141
	v_div_fmas_f32 v98, v98, v192, v190
	v_mul_f32_e32 v190, 0xbfb8aa3b, v88
	v_mul_f32_e32 v191, 0xbfb8aa3b, v89
	v_div_fixup_f32 v85, v98, v85, v87
	v_fma_f32 v87, -v141, v193, 1.0
	v_exp_f32_e32 v190, v190
	v_exp_f32_e32 v191, v191
	v_fmac_f32_e32 v193, v87, v193
	v_div_scale_f32 v87, vcc, v86, v84, v86
	v_mul_f32_e32 v98, v87, v193
	v_fma_f32 v192, -v141, v98, v87
	v_fmac_f32_e32 v98, v192, v193
	v_pk_add_f32 v[190:191], v[190:191], 1.0 op_sel_hi:[1,0]
	v_fma_f32 v87, -v141, v98, v87
	v_div_scale_f32 v141, s[44:45], v191, v191, v89
	v_rcp_f32_e32 v192, v141
	v_div_fmas_f32 v87, v87, v193, v98
	v_div_fixup_f32 v84, v87, v84, v86
	v_cvt_pk_bf16_f32 v84, v84, v85
	v_fma_f32 v85, -v141, v192, 1.0
	v_fmac_f32_e32 v192, v85, v192
	v_div_scale_f32 v85, vcc, v89, v191, v89
	v_mul_f32_e32 v86, v85, v192
	v_fma_f32 v87, -v141, v86, v85
	v_fmac_f32_e32 v86, v87, v192
	v_div_scale_f32 v98, s[44:45], v190, v190, v88
	v_fma_f32 v85, -v141, v86, v85
	v_rcp_f32_e32 v141, v98
	v_div_fmas_f32 v85, v85, v192, v86
	v_div_fixup_f32 v85, v85, v191, v89
	v_div_scale_f32 v89, vcc, v88, v190, v88
	v_fma_f32 v86, -v98, v141, 1.0
	v_fmac_f32_e32 v141, v86, v141
	v_mul_f32_e32 v191, v89, v141
	v_fma_f32 v86, -v98, v191, v89
	v_fmac_f32_e32 v191, v86, v141
	v_mul_f32_e32 v86, 0xbfb8aa3b, v90
	v_mul_f32_e32 v87, 0xbfb8aa3b, v91
	v_exp_f32_e32 v86, v86
	v_exp_f32_e32 v87, v87
	v_fma_f32 v89, -v98, v191, v89
	v_div_fmas_f32 v89, v89, v141, v191
	v_div_fixup_f32 v88, v89, v190, v88
	v_pk_add_f32 v[86:87], v[86:87], 1.0 op_sel_hi:[1,0]
	v_cvt_pk_bf16_f32 v85, v88, v85
	v_div_scale_f32 v98, s[44:45], v87, v87, v91
	v_rcp_f32_e32 v141, v98
	global_store_dwordx2 v[82:83], v[84:85], off offset:-1648
	v_fma_f32 v84, -v98, v141, 1.0
	v_fmac_f32_e32 v141, v84, v141
	v_div_scale_f32 v84, vcc, v91, v87, v91
	v_mul_f32_e32 v85, v84, v141
	v_fma_f32 v88, -v98, v85, v84
	v_fmac_f32_e32 v85, v88, v141
	v_div_scale_f32 v88, s[44:45], v86, v86, v90
	v_rcp_f32_e32 v89, v88
	v_fma_f32 v84, -v98, v85, v84
	v_div_fmas_f32 v84, v84, v141, v85
	v_div_fixup_f32 v87, v84, v87, v91
	v_fma_f32 v84, -v88, v89, 1.0
	v_fmac_f32_e32 v89, v84, v89
	v_mul_f32_e32 v84, 0xbfb8aa3b, v92
	v_mul_f32_e32 v85, 0xbfb8aa3b, v93
	v_exp_f32_e32 v84, v84
	v_exp_f32_e32 v85, v85
	v_div_scale_f32 v91, vcc, v90, v86, v90
	v_mul_f32_e32 v98, v91, v89
	v_fma_f32 v141, -v88, v98, v91
	v_fmac_f32_e32 v98, v141, v89
	v_pk_add_f32 v[84:85], v[84:85], 1.0 op_sel_hi:[1,0]
	v_fma_f32 v88, -v88, v98, v91
	v_div_scale_f32 v91, s[44:45], v85, v85, v93
	v_rcp_f32_e32 v141, v91
	v_div_fmas_f32 v88, v88, v89, v98
	v_div_fixup_f32 v86, v88, v86, v90
	v_cvt_pk_bf16_f32 v86, v86, v87
	v_fma_f32 v87, -v91, v141, 1.0
	v_fmac_f32_e32 v141, v87, v141
	v_div_scale_f32 v87, vcc, v93, v85, v93
	v_mul_f32_e32 v88, v87, v141
	v_fma_f32 v89, -v91, v88, v87
	v_fmac_f32_e32 v88, v89, v141
	v_div_scale_f32 v90, s[44:45], v84, v84, v92
	v_fma_f32 v87, -v91, v88, v87
	v_rcp_f32_e32 v91, v90
	v_div_fmas_f32 v87, v87, v141, v88
	v_div_fixup_f32 v85, v87, v85, v93
	v_mul_f32_e32 v89, 0xbfb8aa3b, v95
	v_fma_f32 v87, -v90, v91, 1.0
	v_fmac_f32_e32 v91, v87, v91
	v_div_scale_f32 v87, vcc, v92, v84, v92
	v_mul_f32_e32 v93, v87, v91
	v_fma_f32 v88, -v90, v93, v87
	v_fmac_f32_e32 v93, v88, v91
	v_mul_f32_e32 v88, 0xbfb8aa3b, v94
	v_exp_f32_e32 v88, v88
	v_exp_f32_e32 v89, v89
	v_fma_f32 v87, -v90, v93, v87
	v_div_fmas_f32 v87, v87, v91, v93
	v_div_fixup_f32 v84, v87, v84, v92
	v_pk_add_f32 v[88:89], v[88:89], 1.0 op_sel_hi:[1,0]
	v_cvt_pk_bf16_f32 v87, v84, v85
	v_div_scale_f32 v90, s[44:45], v89, v89, v95
	v_rcp_f32_e32 v91, v90
	global_store_dwordx2 v[82:83], v[86:87], off offset:-1632
	v_fma_f32 v84, -v90, v91, 1.0
	v_fmac_f32_e32 v91, v84, v91
	v_div_scale_f32 v84, vcc, v95, v89, v95
	v_mul_f32_e32 v85, v84, v91
	v_fma_f32 v86, -v90, v85, v84
	v_fmac_f32_e32 v85, v86, v91
	v_div_scale_f32 v86, s[44:45], v88, v88, v94
	v_rcp_f32_e32 v87, v86
	v_fma_f32 v84, -v90, v85, v84
	v_div_fmas_f32 v84, v84, v91, v85
	v_div_fixup_f32 v89, v84, v89, v95
	v_fma_f32 v84, -v86, v87, 1.0
	v_fmac_f32_e32 v87, v84, v87
	v_mul_f32_e32 v84, 0xbfb8aa3b, v96
	v_mul_f32_e32 v85, 0xbfb8aa3b, v97
	v_exp_f32_e32 v84, v84
	v_exp_f32_e32 v85, v85
	v_div_scale_f32 v90, vcc, v94, v88, v94
	v_mul_f32_e32 v91, v90, v87
	v_fma_f32 v92, -v86, v91, v90
	v_fmac_f32_e32 v91, v92, v87
	v_pk_add_f32 v[84:85], v[84:85], 1.0 op_sel_hi:[1,0]
	v_fma_f32 v86, -v86, v91, v90
	v_div_scale_f32 v90, s[44:45], v85, v85, v97
	v_rcp_f32_e32 v92, v90
	v_div_fmas_f32 v86, v86, v87, v91
	v_div_fixup_f32 v86, v86, v88, v94
	v_cvt_pk_bf16_f32 v86, v86, v89
	v_fma_f32 v87, -v90, v92, 1.0
	v_fmac_f32_e32 v92, v87, v92
	v_div_scale_f32 v87, vcc, v97, v85, v97
	v_mul_f32_e32 v88, v87, v92
	v_fma_f32 v89, -v90, v88, v87
	v_fmac_f32_e32 v88, v89, v92
	v_div_scale_f32 v89, s[44:45], v84, v84, v96
	v_fma_f32 v87, -v90, v88, v87
	v_rcp_f32_e32 v90, v89
	v_div_fmas_f32 v87, v87, v92, v88
	v_div_fixup_f32 v85, v87, v85, v97
	v_fma_f32 v87, -v89, v90, 1.0
	v_fmac_f32_e32 v90, v87, v90
	v_div_scale_f32 v87, vcc, v96, v84, v96
	v_mul_f32_e32 v88, v87, v90
	v_fma_f32 v91, -v89, v88, v87
	v_fmac_f32_e32 v88, v91, v90
	v_fma_f32 v87, -v89, v88, v87
	v_div_fmas_f32 v87, v87, v90, v88
	v_div_fixup_f32 v84, v87, v84, v96
	v_cvt_pk_bf16_f32 v87, v84, v85
	global_store_dwordx2 v[82:83], v[86:87], off offset:-1616

.LBB0_1069:
	s_add_i32 s4, s40, 64
	s_cmp_ge_u32 s4, s43
	s_cselect_b64 s[38:39], -1, 0
	s_mul_i32 s31, s45, 0xa000
	v_or_b32_e32 v2, s31, v179
	s_and_b64 vcc, exec, s[38:39]
	s_cbranch_vccnz .Lattn10_nodma
	v_lshl_add_u32 v16, v149, 8, s31
	v_lshl_add_u32 v17, v149, 7, s31
	v_or_b32_e32 v15, 32, v149
	v_lshl_add_u32 v14, v15, 8, s31
	v_lshl_add_u32 v15, v15, 7, s31
	v_add_u32_e32 v206, v16, v180
	ds_read_b128 v[206:209], v206
	v_add_u32_e32 v210, v16, v181
	ds_read_b128 v[210:213], v210
	v_add_u32_e32 v214, v16, v182
	ds_read_b128 v[214:217], v214
	v_add_u32_e32 v218, v16, v183
	ds_read_b128 v[218:221], v218
	v_add_u32_e32 v222, v16, v184
	ds_read_b128 v[222:225], v222
	v_add_u32_e32 v226, v16, v185
	ds_read_b128 v[226:229], v226
	v_add_u32_e32 v230, v16, v186
	ds_read_b128 v[230:233], v230
	v_add_u32_e32 v234, v16, v187
	ds_read_b128 v[234:237], v234
	s_mov_b32 s35, 0
	v_bitop3_b32 v254, s35, v178, v175 bitop3:0x36
	v_lshl_add_u32 v254, v254, 4, v2
	v_or_b32_e32 v255, s35, v175
	v_bitop3_b32 v255, v255, v178, 2 bitop3:0x36
	v_lshl_add_u32 v255, v255, 4, v2
	s_waitcnt lgkmcnt(7)
	v_mfma_f32_32x32x16_bf16 v[82:97], v[206:209], v[98:101], 0
	v_add_u32_e32 v206, v17, v188
	ds_read_b128 v[206:209], v206 offset:16384
	s_xor_b32 s31, s45, 1
	s_mul_i32 s31, s31, 0xa000
	v_add_u32_e32 v2, s31, v177
	s_lshl_b64 s[46:47], s[4:5], 11
	v_lshl_add_u64 v[4:5], v[170:171], 0, s[46:47]
	v_readfirstlane_b32 s31, v2
	s_add_i32 s46, s40, 0x50
	s_mov_b32 s47, s5
	s_mov_b32 m0, s31
	s_lshl_b64 s[46:47], s[46:47], 11
	v_add_u32_e32 v6, 0x1000, v2
	global_load_lds_dwordx4 v[4:5], off
	s_waitcnt lgkmcnt(7)
	v_mfma_f32_32x32x16_bf16 v[82:97], v[210:213], v[102:105], v[82:97]
	v_add_u32_e32 v210, v17, v189
	ds_read_b128 v[210:213], v210 offset:16384
	v_lshl_add_u64 v[4:5], v[170:171], 0, s[46:47]
	v_readfirstlane_b32 s31, v6
	s_add_i32 s46, s40, 0x60
	s_mov_b32 s47, s5
	s_mov_b32 m0, s31
	s_lshl_b64 s[48:49], s[46:47], 11
	v_add_u32_e32 v6, 0x2000, v2
	global_load_lds_dwordx4 v[4:5], off
	s_waitcnt lgkmcnt(7)
	v_mfma_f32_32x32x16_bf16 v[82:97], v[214:217], v[106:109], v[82:97]
	v_add_u32_e32 v214, v17, v190
	ds_read_b128 v[214:217], v214 offset:16384
	v_lshl_add_u64 v[4:5], v[170:171], 0, s[48:49]
	v_readfirstlane_b32 s31, v6
	s_add_i32 s48, s40, 0x70
	s_mov_b32 s49, s5
	v_add_u32_e32 v6, 0x3000, v2
	s_mov_b32 m0, s31
	s_lshl_b64 s[48:49], s[48:49], 11
	v_readfirstlane_b32 s31, v6
	v_add_u32_e32 v6, 0x4000, v2
	global_load_lds_dwordx4 v[4:5], off
	s_waitcnt lgkmcnt(7)
	v_mfma_f32_32x32x16_bf16 v[82:97], v[218:221], v[110:113], v[82:97]
	v_add_u32_e32 v218, v17, v191
	ds_read_b128 v[218:221], v218 offset:16384
	v_lshl_add_u64 v[4:5], v[170:171], 0, s[48:49]
	s_mov_b32 m0, s31
	s_lshl_b64 s[48:49], s[4:5], 7
	v_readfirstlane_b32 s31, v6
	v_add_u32_e32 v6, 0x5000, v2
	global_load_lds_dwordx4 v[4:5], off
	s_waitcnt lgkmcnt(7)
	v_mfma_f32_32x32x16_bf16 v[82:97], v[222:225], v[114:117], v[82:97]
	v_add_u32_e32 v222, v14, v180
	ds_read_b128 v[222:225], v222
	v_lshl_add_u64 v[4:5], v[172:173], 0, s[48:49]
	s_mov_b32 m0, s31
	s_lshl_b64 s[46:47], s[46:47], 7
	v_readfirstlane_b32 s31, v6
	global_load_lds_dwordx4 v[4:5], off
	s_waitcnt lgkmcnt(7)
	v_mfma_f32_32x32x16_bf16 v[82:97], v[226:229], v[118:121], v[82:97]
	v_add_u32_e32 v226, v14, v181
	ds_read_b128 v[226:229], v226
	v_lshl_add_u64 v[4:5], v[172:173], 0, s[46:47]
	s_mov_b32 m0, s31
	s_mov_b32 s41, s5
	v_add_u32_e32 v8, 0x6000, v2
	global_load_lds_dwordx4 v[4:5], off
	s_waitcnt lgkmcnt(7)
	v_mfma_f32_32x32x16_bf16 v[82:97], v[230:233], v[122:125], v[82:97]
	v_add_u32_e32 v230, v14, v182
	ds_read_b128 v[230:233], v230
	v_lshl_add_u64 v[4:5], s[40:41], 1, v[168:169]
	v_readfirstlane_b32 s31, v8
	v_lshl_add_u64 v[6:7], v[4:5], 0, s[28:29]
	s_mov_b32 m0, s31
	s_mov_b32 s31, s5
	v_add_u32_e32 v8, 0x7000, v2
	global_load_lds_dwordx4 v[6:7], off
	s_waitcnt lgkmcnt(7)
	v_mfma_f32_32x32x16_bf16 v[82:97], v[234:237], v[126:129], v[82:97]
	v_add_u32_e32 v234, v14, v183
	ds_read_b128 v[234:237], v234
	v_lshl_add_u64 v[6:7], v[4:5], 0, s[30:31]
	v_readfirstlane_b32 s31, v8
	v_lshl_add_u64 v[6:7], v[6:7], 0, s[28:29]
	s_mov_b32 m0, s31
	s_mov_b32 s35, s5
	v_add_u32_e32 v8, 0x8000, v2
	global_load_lds_dwordx4 v[6:7], off
	s_waitcnt lgkmcnt(7)
	v_mfma_f32_32x32x16_bf16 v[82:97], v[206:209], v[130:133], v[82:97]
	v_add_u32_e32 v206, v14, v184
	ds_read_b128 v[206:209], v206
	v_lshl_add_u64 v[6:7], v[4:5], 0, s[34:35]
	v_readfirstlane_b32 s31, v8
	s_mov_b32 s37, s5
	v_add_u32_e32 v2, 0x9000, v2
	v_lshl_add_u64 v[6:7], v[6:7], 0, s[28:29]
	s_mov_b32 m0, s31
	v_lshl_add_u64 v[4:5], v[4:5], 0, s[36:37]
	v_readfirstlane_b32 s31, v2
	global_load_lds_dwordx4 v[6:7], off
	s_waitcnt lgkmcnt(7)
	v_mfma_f32_32x32x16_bf16 v[82:97], v[210:213], v[134:137], v[82:97]
	v_add_u32_e32 v210, v14, v185
	ds_read_b128 v[210:213], v210
	v_lshl_add_u64 v[4:5], v[4:5], 0, s[28:29]
	s_mov_b32 m0, s31
	s_nop 0
	global_load_lds_dwordx4 v[4:5], off
	s_waitcnt lgkmcnt(7)
	v_mfma_f32_32x32x16_bf16 v[82:97], v[214:217], v[138:141], v[82:97]
	v_add_u32_e32 v214, v14, v186
	ds_read_b128 v[214:217], v214
	s_waitcnt lgkmcnt(7)
	v_mfma_f32_32x32x16_bf16 v[82:97], v[218:221], v[142:145], v[82:97]
	v_add_u32_e32 v218, v14, v187
	ds_read_b128 v[218:221], v218
	s_mul_i32 s31, s45, 0xa000
	v_or_b32_e32 v2, s31, v179
	s_mov_b32 s35, 4
	v_bitop3_b32 v16, s35, v178, v175 bitop3:0x36
	v_lshl_add_u32 v16, v16, 4, v2
	v_or_b32_e32 v17, s35, v175
	v_bitop3_b32 v17, v17, v178, 2 bitop3:0x36
	v_lshl_add_u32 v17, v17, 4, v2
	s_nop 3
	v_max_f32_e32 v4, v83, v83
	v_max_f32_e32 v5, v82, v82
	v_max_f32_e32 v4, v5, v4
	v_max3_f32 v4, v4, v84, v85
	v_max3_f32 v4, v4, v86, v87
	v_max3_f32 v4, v4, v88, v89
	v_max3_f32 v4, v4, v90, v91
	v_max3_f32 v4, v4, v92, v93
	v_max3_f32 v4, v4, v94, v95
	v_max3_f32 v4, v4, v96, v97
	v_mov_b32_e32 v5, v4
	s_nop 1
	v_permlane32_swap_b32_e32 v5, v4
	v_max_f32_e32 v4, v4, v5
	v_add_f32_e32 v5, 0x41000000, v165
	v_cmp_gt_f32_e32 vcc, v4, v5
	s_cbranch_vccnz .Lattn10_d_resc0
.Lattn10_d_ret0:
	s_waitcnt lgkmcnt(7)
	v_mfma_f32_32x32x16_bf16 v[238:253], v[222:225], v[98:101], 0
	v_add_u32_e32 v222, v15, v188
	ds_read_b128 v[222:225], v222 offset:16384
	v_sub_f32_e32 v6, v82, v165
	v_exp_f32_e32 v82, v6
	v_sub_f32_e32 v7, v83, v165
	v_exp_f32_e32 v83, v7
	v_sub_f32_e32 v6, v84, v165
	s_waitcnt lgkmcnt(7)
	v_mfma_f32_32x32x16_bf16 v[238:253], v[226:229], v[102:105], v[238:253]
	v_add_u32_e32 v226, v15, v189
	ds_read_b128 v[226:229], v226 offset:16384
	v_exp_f32_e32 v84, v6
	v_sub_f32_e32 v7, v85, v165
	v_exp_f32_e32 v85, v7
	v_sub_f32_e32 v6, v86, v165
	v_exp_f32_e32 v86, v6
	s_waitcnt lgkmcnt(7)
	v_mfma_f32_32x32x16_bf16 v[238:253], v[230:233], v[106:109], v[238:253]
	v_add_u32_e32 v230, v15, v190
	ds_read_b128 v[230:233], v230 offset:16384
	v_sub_f32_e32 v7, v87, v165
	v_exp_f32_e32 v87, v7
	v_sub_f32_e32 v6, v88, v165
	v_exp_f32_e32 v88, v6
	v_sub_f32_e32 v7, v89, v165
	s_waitcnt lgkmcnt(7)
	v_mfma_f32_32x32x16_bf16 v[238:253], v[234:237], v[110:113], v[238:253]
	v_add_u32_e32 v234, v15, v191
	ds_read_b128 v[234:237], v234 offset:16384
	v_exp_f32_e32 v89, v7
	v_cvt_pk_bf16_f32 v8, v82, v83
	v_cvt_pk_bf16_f32 v9, v84, v85
	v_cvt_pk_bf16_f32 v10, v86, v87
	v_cvt_pk_bf16_f32 v11, v88, v89
	s_waitcnt lgkmcnt(7)
	v_mfma_f32_32x32x16_bf16 v[238:253], v[206:209], v[114:117], v[238:253]
	ds_read_b128 v[206:209], v254 offset:24576
	v_sub_f32_e32 v6, v90, v165
	v_exp_f32_e32 v90, v6
	v_sub_f32_e32 v7, v91, v165
	v_exp_f32_e32 v91, v7
	s_waitcnt lgkmcnt(7)
	v_mfma_f32_32x32x16_bf16 v[238:253], v[210:213], v[118:121], v[238:253]
	ds_read_b128 v[210:213], v254 offset:28672
	v_sub_f32_e32 v6, v92, v165
	v_exp_f32_e32 v92, v6
	v_sub_f32_e32 v7, v93, v165
	v_exp_f32_e32 v93, v7
	s_waitcnt lgkmcnt(7)
	v_mfma_f32_32x32x16_bf16 v[238:253], v[214:217], v[122:125], v[238:253]
	ds_read_b128 v[214:217], v254 offset:32768
	v_sub_f32_e32 v6, v94, v165
	v_exp_f32_e32 v94, v6
	v_sub_f32_e32 v7, v95, v165
	v_exp_f32_e32 v95, v7
	s_waitcnt lgkmcnt(7)
	v_mfma_f32_32x32x16_bf16 v[238:253], v[218:221], v[126:129], v[238:253]
	ds_read_b128 v[218:221], v254 offset:36864
	v_sub_f32_e32 v6, v96, v165
	v_exp_f32_e32 v96, v6
	v_sub_f32_e32 v7, v97, v165
	v_exp_f32_e32 v97, v7
	s_waitcnt lgkmcnt(7)
	v_mfma_f32_32x32x16_bf16 v[238:253], v[222:225], v[130:133], v[238:253]
	ds_read_b128 v[222:225], v255 offset:24576
	v_cvt_pk_bf16_f32 v12, v90, v91
	v_cvt_pk_bf16_f32 v13, v92, v93
	v_cvt_pk_bf16_f32 v14, v94, v95
	v_cvt_pk_bf16_f32 v15, v96, v97
	v_add_f32_e32 v4, 0, v82
	v_add_f32_e32 v4, v83, v4
	s_waitcnt lgkmcnt(7)
	v_mfma_f32_32x32x16_bf16 v[238:253], v[226:229], v[134:137], v[238:253]
	ds_read_b128 v[226:229], v255 offset:28672
	v_add_f32_e32 v4, v84, v4
	v_add_f32_e32 v4, v85, v4
	v_add_f32_e32 v4, v86, v4
	v_add_f32_e32 v4, v87, v4
	v_add_f32_e32 v4, v88, v4
	s_waitcnt lgkmcnt(7)
	v_mfma_f32_32x32x16_bf16 v[238:253], v[230:233], v[138:141], v[238:253]
	ds_read_b128 v[230:233], v255 offset:32768
	v_add_f32_e32 v4, v89, v4
	v_add_f32_e32 v4, v90, v4
	v_add_f32_e32 v4, v91, v4
	v_add_f32_e32 v4, v92, v4
	v_add_f32_e32 v4, v93, v4
	s_waitcnt lgkmcnt(7)
	v_mfma_f32_32x32x16_bf16 v[238:253], v[234:237], v[142:145], v[238:253]
	ds_read_b128 v[234:237], v255 offset:36864
	v_add_f32_e32 v4, v94, v4
	v_add_f32_e32 v4, v95, v4
	v_add_f32_e32 v4, v96, v4
	v_add_f32_e32 v4, v97, v4
	v_add_f32_e32 v204, v204, v4
	s_nop 1
	s_waitcnt lgkmcnt(7)
	v_mfma_f32_32x32x16_bf16 v[66:81], v[206:209], v[8:11], v[66:81]
	ds_read_b128 v[206:209], v16 offset:24576
	s_waitcnt lgkmcnt(7)
	v_mfma_f32_32x32x16_bf16 v[50:65], v[210:213], v[8:11], v[50:65]
	ds_read_b128 v[210:213], v16 offset:28672
	s_waitcnt lgkmcnt(7)
	v_mfma_f32_32x32x16_bf16 v[34:49], v[214:217], v[8:11], v[34:49]
	ds_read_b128 v[214:217], v16 offset:32768
	s_waitcnt lgkmcnt(7)
	v_mfma_f32_32x32x16_bf16 v[18:33], v[218:221], v[8:11], v[18:33]
	ds_read_b128 v[218:221], v16 offset:36864
	s_nop 3
	v_max_f32_e32 v4, v239, v239
	v_max_f32_e32 v5, v238, v238
	v_max_f32_e32 v4, v5, v4
	v_max3_f32 v4, v4, v240, v241
	v_max3_f32 v4, v4, v242, v243
	v_max3_f32 v4, v4, v244, v245
	v_max3_f32 v4, v4, v246, v247
	v_max3_f32 v4, v4, v248, v249
	v_max3_f32 v4, v4, v250, v251
	v_max3_f32 v4, v4, v252, v253
	v_mov_b32_e32 v5, v4
	s_nop 1
	v_permlane32_swap_b32_e32 v5, v4
	v_max_f32_e32 v4, v4, v5
	s_waitcnt lgkmcnt(7)
	v_mfma_f32_32x32x16_bf16 v[66:81], v[222:225], v[12:15], v[66:81]
	ds_read_b128 v[222:225], v17 offset:24576
	s_waitcnt lgkmcnt(7)
	v_mfma_f32_32x32x16_bf16 v[50:65], v[226:229], v[12:15], v[50:65]
	ds_read_b128 v[226:229], v17 offset:28672
	s_waitcnt lgkmcnt(7)
	v_mfma_f32_32x32x16_bf16 v[34:49], v[230:233], v[12:15], v[34:49]
	ds_read_b128 v[230:233], v17 offset:32768
	s_waitcnt lgkmcnt(7)
	v_mfma_f32_32x32x16_bf16 v[18:33], v[234:237], v[12:15], v[18:33]
	ds_read_b128 v[234:237], v17 offset:36864
	v_add_f32_e32 v5, 0x41000000, v165
	v_cmp_gt_f32_e32 vcc, v4, v5
	s_cbranch_vccnz .Lattn10_d_resc1
.Lattn10_d_ret1:
	v_sub_f32_e32 v6, v238, v165
	v_exp_f32_e32 v238, v6
	v_sub_f32_e32 v7, v239, v165
	v_exp_f32_e32 v239, v7
	v_sub_f32_e32 v6, v240, v165
	v_exp_f32_e32 v240, v6
	v_sub_f32_e32 v7, v241, v165
	v_exp_f32_e32 v241, v7
	v_sub_f32_e32 v6, v242, v165
	v_exp_f32_e32 v242, v6
	v_sub_f32_e32 v7, v243, v165
	v_exp_f32_e32 v243, v7
	v_sub_f32_e32 v6, v244, v165
	v_exp_f32_e32 v244, v6
	v_sub_f32_e32 v7, v245, v165
	v_exp_f32_e32 v245, v7
	v_cvt_pk_bf16_f32 v8, v238, v239
	v_cvt_pk_bf16_f32 v9, v240, v241
	v_cvt_pk_bf16_f32 v10, v242, v243
	v_cvt_pk_bf16_f32 v11, v244, v245
	s_nop 1
	s_waitcnt lgkmcnt(7)
	v_mfma_f32_32x32x16_bf16 v[66:81], v[206:209], v[8:11], v[66:81]
	v_sub_f32_e32 v6, v246, v165
	v_exp_f32_e32 v246, v6
	v_sub_f32_e32 v7, v247, v165
	v_exp_f32_e32 v247, v7
	s_waitcnt lgkmcnt(6)
	v_mfma_f32_32x32x16_bf16 v[50:65], v[210:213], v[8:11], v[50:65]
	v_sub_f32_e32 v6, v248, v165
	v_exp_f32_e32 v248, v6
	v_sub_f32_e32 v7, v249, v165
	v_exp_f32_e32 v249, v7
	s_waitcnt lgkmcnt(5)
	v_mfma_f32_32x32x16_bf16 v[34:49], v[214:217], v[8:11], v[34:49]
	v_sub_f32_e32 v6, v250, v165
	v_exp_f32_e32 v250, v6
	v_sub_f32_e32 v7, v251, v165
	v_exp_f32_e32 v251, v7
	s_waitcnt lgkmcnt(4)
	v_mfma_f32_32x32x16_bf16 v[18:33], v[218:221], v[8:11], v[18:33]
	v_sub_f32_e32 v6, v252, v165
	v_exp_f32_e32 v252, v6
	v_sub_f32_e32 v7, v253, v165
	v_exp_f32_e32 v253, v7
	v_cvt_pk_bf16_f32 v12, v246, v247
	v_cvt_pk_bf16_f32 v13, v248, v249
	v_cvt_pk_bf16_f32 v14, v250, v251
	v_cvt_pk_bf16_f32 v15, v252, v253
	s_nop 1
	s_waitcnt lgkmcnt(3)
	v_mfma_f32_32x32x16_bf16 v[66:81], v[222:225], v[12:15], v[66:81]
	v_add_f32_e32 v4, 0, v238
	v_add_f32_e32 v4, v239, v4
	v_add_f32_e32 v4, v240, v4
	v_add_f32_e32 v4, v241, v4
	v_add_f32_e32 v4, v242, v4
	s_waitcnt lgkmcnt(2)
	v_mfma_f32_32x32x16_bf16 v[50:65], v[226:229], v[12:15], v[50:65]
	v_add_f32_e32 v4, v243, v4
	v_add_f32_e32 v4, v244, v4
	v_add_f32_e32 v4, v245, v4
	v_add_f32_e32 v4, v246, v4
	s_waitcnt lgkmcnt(1)
	v_mfma_f32_32x32x16_bf16 v[34:49], v[230:233], v[12:15], v[34:49]
	v_add_f32_e32 v4, v247, v4
	v_add_f32_e32 v4, v248, v4
	v_add_f32_e32 v4, v249, v4
	v_add_f32_e32 v4, v250, v4
	s_waitcnt lgkmcnt(0)
	v_mfma_f32_32x32x16_bf16 v[18:33], v[234:237], v[12:15], v[18:33]
	v_add_f32_e32 v4, v251, v4
	v_add_f32_e32 v4, v252, v4
	v_add_f32_e32 v4, v253, v4
	v_add_f32_e32 v204, v204, v4
	s_branch .LBB0_1075
.Lattn10_nodma:
	v_lshl_add_u32 v16, v149, 8, s31
	v_lshl_add_u32 v17, v149, 7, s31
	v_or_b32_e32 v15, 32, v149
	v_lshl_add_u32 v14, v15, 8, s31
	v_lshl_add_u32 v15, v15, 7, s31
	v_add_u32_e32 v206, v16, v180
	ds_read_b128 v[206:209], v206
	v_add_u32_e32 v210, v16, v181
	ds_read_b128 v[210:213], v210
	v_add_u32_e32 v214, v16, v182
	ds_read_b128 v[214:217], v214
	v_add_u32_e32 v218, v16, v183
	ds_read_b128 v[218:221], v218
	v_add_u32_e32 v222, v16, v184
	ds_read_b128 v[222:225], v222
	v_add_u32_e32 v226, v16, v185
	ds_read_b128 v[226:229], v226
	v_add_u32_e32 v230, v16, v186
	ds_read_b128 v[230:233], v230
	v_add_u32_e32 v234, v16, v187
	ds_read_b128 v[234:237], v234
	s_mov_b32 s35, 0
	v_bitop3_b32 v254, s35, v178, v175 bitop3:0x36
	v_lshl_add_u32 v254, v254, 4, v2
	v_or_b32_e32 v255, s35, v175
	v_bitop3_b32 v255, v255, v178, 2 bitop3:0x36
	v_lshl_add_u32 v255, v255, 4, v2
	s_waitcnt lgkmcnt(7)
	v_mfma_f32_32x32x16_bf16 v[82:97], v[206:209], v[98:101], 0
	v_add_u32_e32 v206, v17, v188
	ds_read_b128 v[206:209], v206 offset:16384
	s_waitcnt lgkmcnt(7)
	v_mfma_f32_32x32x16_bf16 v[82:97], v[210:213], v[102:105], v[82:97]
	v_add_u32_e32 v210, v17, v189
	ds_read_b128 v[210:213], v210 offset:16384
	s_waitcnt lgkmcnt(7)
	v_mfma_f32_32x32x16_bf16 v[82:97], v[214:217], v[106:109], v[82:97]
	v_add_u32_e32 v214, v17, v190
	ds_read_b128 v[214:217], v214 offset:16384
	s_waitcnt lgkmcnt(7)
	v_mfma_f32_32x32x16_bf16 v[82:97], v[218:221], v[110:113], v[82:97]
	v_add_u32_e32 v218, v17, v191
	ds_read_b128 v[218:221], v218 offset:16384
	s_waitcnt lgkmcnt(7)
	v_mfma_f32_32x32x16_bf16 v[82:97], v[222:225], v[114:117], v[82:97]
	v_add_u32_e32 v222, v14, v180
	ds_read_b128 v[222:225], v222
	s_waitcnt lgkmcnt(7)
	v_mfma_f32_32x32x16_bf16 v[82:97], v[226:229], v[118:121], v[82:97]
	v_add_u32_e32 v226, v14, v181
	ds_read_b128 v[226:229], v226
	s_waitcnt lgkmcnt(7)
	v_mfma_f32_32x32x16_bf16 v[82:97], v[230:233], v[122:125], v[82:97]
	v_add_u32_e32 v230, v14, v182
	ds_read_b128 v[230:233], v230
	s_waitcnt lgkmcnt(7)
	v_mfma_f32_32x32x16_bf16 v[82:97], v[234:237], v[126:129], v[82:97]
	v_add_u32_e32 v234, v14, v183
	ds_read_b128 v[234:237], v234
	s_waitcnt lgkmcnt(7)
	v_mfma_f32_32x32x16_bf16 v[82:97], v[206:209], v[130:133], v[82:97]
	v_add_u32_e32 v206, v14, v184
	ds_read_b128 v[206:209], v206
	s_waitcnt lgkmcnt(7)
	v_mfma_f32_32x32x16_bf16 v[82:97], v[210:213], v[134:137], v[82:97]
	v_add_u32_e32 v210, v14, v185
	ds_read_b128 v[210:213], v210
	s_waitcnt lgkmcnt(7)
	v_mfma_f32_32x32x16_bf16 v[82:97], v[214:217], v[138:141], v[82:97]
	v_add_u32_e32 v214, v14, v186
	ds_read_b128 v[214:217], v214
	s_waitcnt lgkmcnt(7)
	v_mfma_f32_32x32x16_bf16 v[82:97], v[218:221], v[142:145], v[82:97]
	v_add_u32_e32 v218, v14, v187
	ds_read_b128 v[218:221], v218
	s_mul_i32 s31, s45, 0xa000
	v_or_b32_e32 v2, s31, v179
	s_mov_b32 s35, 4
	v_bitop3_b32 v16, s35, v178, v175 bitop3:0x36
	v_lshl_add_u32 v16, v16, 4, v2
	v_or_b32_e32 v17, s35, v175
	v_bitop3_b32 v17, v17, v178, 2 bitop3:0x36
	v_lshl_add_u32 v17, v17, 4, v2
	s_nop 3
	v_max_f32_e32 v4, v83, v83
	v_max_f32_e32 v5, v82, v82
	v_max_f32_e32 v4, v5, v4
	v_max3_f32 v4, v4, v84, v85
	v_max3_f32 v4, v4, v86, v87
	v_max3_f32 v4, v4, v88, v89
	v_max3_f32 v4, v4, v90, v91
	v_max3_f32 v4, v4, v92, v93
	v_max3_f32 v4, v4, v94, v95
	v_max3_f32 v4, v4, v96, v97
	v_mov_b32_e32 v5, v4
	s_nop 1
	v_permlane32_swap_b32_e32 v5, v4
	v_max_f32_e32 v4, v4, v5
	v_add_f32_e32 v5, 0x41000000, v165
	v_cmp_gt_f32_e32 vcc, v4, v5
	s_cbranch_vccnz .Lattn10_n_resc0

.Lattn10_d_resc0:
	v_max_f32_e32 v4, v4, v4
	v_max_f32_e32 v5, v165, v165
	v_max_f32_e32 v5, v5, v4
	v_sub_f32_e32 v4, v165, v5
	v_exp_f32_e32 v4, v4
	v_mov_b32_e32 v165, v5
	v_pk_mul_f32 v[80:81], v[80:81], v[4:5] op_sel_hi:[1,0]
	v_pk_mul_f32 v[78:79], v[78:79], v[4:5] op_sel_hi:[1,0]
	v_pk_mul_f32 v[76:77], v[76:77], v[4:5] op_sel_hi:[1,0]
	v_pk_mul_f32 v[74:75], v[74:75], v[4:5] op_sel_hi:[1,0]
	v_pk_mul_f32 v[72:73], v[72:73], v[4:5] op_sel_hi:[1,0]
	v_pk_mul_f32 v[70:71], v[70:71], v[4:5] op_sel_hi:[1,0]
	v_pk_mul_f32 v[68:69], v[68:69], v[4:5] op_sel_hi:[1,0]
	v_pk_mul_f32 v[66:67], v[66:67], v[4:5] op_sel_hi:[1,0]
	v_pk_mul_f32 v[64:65], v[64:65], v[4:5] op_sel_hi:[1,0]
	v_pk_mul_f32 v[62:63], v[62:63], v[4:5] op_sel_hi:[1,0]
	v_pk_mul_f32 v[60:61], v[60:61], v[4:5] op_sel_hi:[1,0]
	v_pk_mul_f32 v[58:59], v[58:59], v[4:5] op_sel_hi:[1,0]
	v_pk_mul_f32 v[56:57], v[56:57], v[4:5] op_sel_hi:[1,0]
	v_pk_mul_f32 v[54:55], v[54:55], v[4:5] op_sel_hi:[1,0]
	v_pk_mul_f32 v[52:53], v[52:53], v[4:5] op_sel_hi:[1,0]
	v_pk_mul_f32 v[50:51], v[50:51], v[4:5] op_sel_hi:[1,0]
	v_pk_mul_f32 v[48:49], v[48:49], v[4:5] op_sel_hi:[1,0]
	v_pk_mul_f32 v[46:47], v[46:47], v[4:5] op_sel_hi:[1,0]
	v_pk_mul_f32 v[44:45], v[44:45], v[4:5] op_sel_hi:[1,0]
	v_pk_mul_f32 v[42:43], v[42:43], v[4:5] op_sel_hi:[1,0]
	v_pk_mul_f32 v[40:41], v[40:41], v[4:5] op_sel_hi:[1,0]
	v_pk_mul_f32 v[38:39], v[38:39], v[4:5] op_sel_hi:[1,0]
	v_pk_mul_f32 v[36:37], v[36:37], v[4:5] op_sel_hi:[1,0]
	v_pk_mul_f32 v[34:35], v[34:35], v[4:5] op_sel_hi:[1,0]
	v_pk_mul_f32 v[32:33], v[32:33], v[4:5] op_sel_hi:[1,0]
	v_pk_mul_f32 v[30:31], v[30:31], v[4:5] op_sel_hi:[1,0]
	v_pk_mul_f32 v[28:29], v[28:29], v[4:5] op_sel_hi:[1,0]
	v_pk_mul_f32 v[26:27], v[26:27], v[4:5] op_sel_hi:[1,0]
	v_pk_mul_f32 v[24:25], v[24:25], v[4:5] op_sel_hi:[1,0]
	v_pk_mul_f32 v[22:23], v[22:23], v[4:5] op_sel_hi:[1,0]
	v_pk_mul_f32 v[20:21], v[20:21], v[4:5] op_sel_hi:[1,0]
	v_pk_mul_f32 v[18:19], v[18:19], v[4:5] op_sel_hi:[1,0]
	v_mul_f32_e32 v204, v204, v4
	s_branch .Lattn10_d_ret0
.Lattn10_d_resc1:
	s_nop 15
	v_max_f32_e32 v4, v4, v4
	v_max_f32_e32 v5, v165, v165
	v_max_f32_e32 v5, v5, v4
	v_sub_f32_e32 v4, v165, v5
	v_exp_f32_e32 v4, v4
	v_mov_b32_e32 v165, v5
	v_pk_mul_f32 v[80:81], v[80:81], v[4:5] op_sel_hi:[1,0]
	v_pk_mul_f32 v[78:79], v[78:79], v[4:5] op_sel_hi:[1,0]
	v_pk_mul_f32 v[76:77], v[76:77], v[4:5] op_sel_hi:[1,0]
	v_pk_mul_f32 v[74:75], v[74:75], v[4:5] op_sel_hi:[1,0]
	v_pk_mul_f32 v[72:73], v[72:73], v[4:5] op_sel_hi:[1,0]
	v_pk_mul_f32 v[70:71], v[70:71], v[4:5] op_sel_hi:[1,0]
	v_pk_mul_f32 v[68:69], v[68:69], v[4:5] op_sel_hi:[1,0]
	v_pk_mul_f32 v[66:67], v[66:67], v[4:5] op_sel_hi:[1,0]
	v_pk_mul_f32 v[64:65], v[64:65], v[4:5] op_sel_hi:[1,0]
	v_pk_mul_f32 v[62:63], v[62:63], v[4:5] op_sel_hi:[1,0]
	v_pk_mul_f32 v[60:61], v[60:61], v[4:5] op_sel_hi:[1,0]
	v_pk_mul_f32 v[58:59], v[58:59], v[4:5] op_sel_hi:[1,0]
	v_pk_mul_f32 v[56:57], v[56:57], v[4:5] op_sel_hi:[1,0]
	v_pk_mul_f32 v[54:55], v[54:55], v[4:5] op_sel_hi:[1,0]
	v_pk_mul_f32 v[52:53], v[52:53], v[4:5] op_sel_hi:[1,0]
	v_pk_mul_f32 v[50:51], v[50:51], v[4:5] op_sel_hi:[1,0]
	v_pk_mul_f32 v[48:49], v[48:49], v[4:5] op_sel_hi:[1,0]
	v_pk_mul_f32 v[46:47], v[46:47], v[4:5] op_sel_hi:[1,0]
	v_pk_mul_f32 v[44:45], v[44:45], v[4:5] op_sel_hi:[1,0]
	v_pk_mul_f32 v[42:43], v[42:43], v[4:5] op_sel_hi:[1,0]
	v_pk_mul_f32 v[40:41], v[40:41], v[4:5] op_sel_hi:[1,0]
	v_pk_mul_f32 v[38:39], v[38:39], v[4:5] op_sel_hi:[1,0]
	v_pk_mul_f32 v[36:37], v[36:37], v[4:5] op_sel_hi:[1,0]
	v_pk_mul_f32 v[34:35], v[34:35], v[4:5] op_sel_hi:[1,0]
	v_pk_mul_f32 v[32:33], v[32:33], v[4:5] op_sel_hi:[1,0]
	v_pk_mul_f32 v[30:31], v[30:31], v[4:5] op_sel_hi:[1,0]
	v_pk_mul_f32 v[28:29], v[28:29], v[4:5] op_sel_hi:[1,0]
	v_pk_mul_f32 v[26:27], v[26:27], v[4:5] op_sel_hi:[1,0]
	v_pk_mul_f32 v[24:25], v[24:25], v[4:5] op_sel_hi:[1,0]
	v_pk_mul_f32 v[22:23], v[22:23], v[4:5] op_sel_hi:[1,0]
	v_pk_mul_f32 v[20:21], v[20:21], v[4:5] op_sel_hi:[1,0]
	v_pk_mul_f32 v[18:19], v[18:19], v[4:5] op_sel_hi:[1,0]
	v_mul_f32_e32 v204, v204, v4
	s_branch .Lattn10_d_ret1

.LBB0_1133:
	s_ashr_i32 s10, s28, 31
	s_lshr_b32 s10, s10, 26
	s_add_i32 s10, s28, s10
	s_ashr_i32 s31, s10, 6
	s_and_b32 s10, s10, 0x3ffffc0
	s_sub_i32 s29, s28, s10
	s_mulk_i32 s29, 0xc0
	v_add_u32_e32 v2, s29, v108
	s_lshr_b32 s10, s29, 6
	s_lshl_b32 s30, s31, 7
	v_ashrrev_i32_e32 v3, 31, v2
	s_add_i32 s10, s10, s31
	v_lshlrev_b64 v[2:3], 11, v[2:3]
	v_or_b32_e32 v4, s30, v108
	s_lshl_b32 s31, s10, 6
	s_lshl_b32 s10, s10, 7
	v_ashrrev_i32_e32 v5, 31, v4
	v_lshl_add_u64 v[104:105], v[100:101], 0, v[2:3]
	s_and_b32 s10, s10, 0x780
	v_readfirstlane_b32 s34, v109
	v_lshlrev_b64 v[4:5], 11, v[4:5]
	v_lshl_add_u64 v[2:3], v[104:105], 0, s[10:11]
	s_mov_b32 m0, s34
	v_readfirstlane_b32 s34, v128
	v_lshl_add_u64 v[106:107], v[102:103], 0, v[4:5]
	s_waitcnt vmcnt(0)
	s_barrier
	s_load_dwordx2 s[66:67], s[0:1], 0x128
	s_load_dwordx2 s[68:69], s[0:1], 0xf0
	v_and_b32_e32 v201, 0x3ff, v0
	v_readfirstlane_b32 s80, v0
	v_and_b32_e32 v200, 31, v201
	v_bfe_u32 v214, v201, 1, 3
	v_bfe_u32 v213, v201, 5, 1
	v_xor_b32_e32 v214, v214, v213
	v_lshlrev_b32_e32 v214, 4, v214
	s_and_b32 s80, s80, 0x3ff
	s_lshr_b32 s83, s80, 6
	s_lshl_b32 s80, s80, 4
	s_lshr_b32 s84, s83, 1
	s_and_b32 s83, s83, 1
	s_mul_i32 s84, s84, 0x3000
	s_lshl_b32 s83, s83, 13
	s_add_u32 s83, s83, 0xc000
	v_lshlrev_b32_e32 v200, 7, v200
	v_or_b32_e32 v200, v200, v214
	v_add_u32_e32 v215, s84, v200
	v_add_u32_e32 v211, s83, v200
	v_xor_b32_e32 v214, 0x20, v215
	v_xor_b32_e32 v210, 0x20, v211
	v_xor_b32_e32 v213, 0x40, v215
	v_xor_b32_e32 v209, 0x40, v211
	v_xor_b32_e32 v212, 0x60, v215
	v_xor_b32_e32 v208, 0x60, v211
	v_bfe_u32 v200, v201, 4, 3
	v_and_b32_e32 v206, 7, v201
	v_xor_b32_e32 v200, v200, v206
	v_lshlrev_b32_e32 v200, 4, v200
	v_lshrrev_b32_e32 v206, 3, v201
	v_lshl_or_b32 v207, v206, 11, v200
	v_add_u32_e32 v206, 0x10000, v207
	v_add_u32_e32 v205, 0x20000, v207
	v_add_u32_e32 v204, 0x30000, v207
	v_add_u32_e32 v203, 0x40000, v207
	v_add_u32_e32 v202, 0x50000, v207
	s_lshr_b32 s83, s28, 6
	s_and_b32 s84, s28, 63
	s_mov_b32 s79, 0
	s_mul_i32 s84, s84, 0x60000
	s_lshl_b32 s83, s83, 18
	s_waitcnt lgkmcnt(0)
	s_add_u32 s66, s66, s84
	s_addc_u32 s67, s67, 0
	s_add_u32 s68, s68, s83
	s_addc_u32 s69, s69, 0
	s_add_u32 s83, s79, 0
	s_and_b32 s83, s83, 15
	s_lshl_b32 s83, s83, 7
	s_add_u32 s70, s66, s83
	s_addc_u32 s71, s67, 0
	s_add_u32 s72, s68, s83
	s_addc_u32 s73, s69, 0
	s_add_u32 s81, s80, 0x0
	s_add_u32 s82, s80, 0xc000
	s_add_u32 m0, s81, 0x0
	s_nop 0
	global_load_lds_dwordx4 v207, s[70:71]
	s_add_u32 m0, s81, 0x1000
	s_nop 0
	global_load_lds_dwordx4 v206, s[70:71]
	s_add_u32 m0, s81, 0x2000
	s_nop 0
	global_load_lds_dwordx4 v205, s[70:71]
	s_add_u32 m0, s81, 0x3000
	s_nop 0
	global_load_lds_dwordx4 v204, s[70:71]
	s_add_u32 m0, s81, 0x4000
	s_nop 0
	global_load_lds_dwordx4 v203, s[70:71]
	s_add_u32 m0, s81, 0x5000
	s_nop 0
	global_load_lds_dwordx4 v202, s[70:71]
	s_add_u32 m0, s82, 0x0
	s_nop 0
	global_load_lds_dwordx4 v207, s[72:73]
	s_add_u32 m0, s82, 0x1000
	s_nop 0
	global_load_lds_dwordx4 v206, s[72:73]
	s_add_u32 m0, s82, 0x2000
	s_nop 0
	global_load_lds_dwordx4 v205, s[72:73]
	s_add_u32 m0, s82, 0x3000
	s_nop 0
	global_load_lds_dwordx4 v204, s[72:73]
	s_add_u32 s83, s79, 1
	s_and_b32 s83, s83, 15
	s_lshl_b32 s83, s83, 7
	s_add_u32 s70, s66, s83
	s_addc_u32 s71, s67, 0
	s_add_u32 s72, s68, s83
	s_addc_u32 s73, s69, 0
	s_add_u32 s81, s80, 0x6000
	s_add_u32 s82, s80, 0x10000
	s_add_u32 m0, s81, 0x0
	s_nop 0
	global_load_lds_dwordx4 v207, s[70:71]
	s_add_u32 m0, s81, 0x1000
	s_nop 0
	global_load_lds_dwordx4 v206, s[70:71]
	s_add_u32 m0, s81, 0x2000
	s_nop 0
	global_load_lds_dwordx4 v205, s[70:71]
	s_add_u32 m0, s81, 0x3000
	s_nop 0
	global_load_lds_dwordx4 v204, s[70:71]
	s_add_u32 m0, s81, 0x4000
	s_nop 0
	global_load_lds_dwordx4 v203, s[70:71]
	s_add_u32 m0, s81, 0x5000
	s_nop 0
	global_load_lds_dwordx4 v202, s[70:71]
	s_add_u32 m0, s82, 0x0
	s_nop 0
	global_load_lds_dwordx4 v207, s[72:73]
	s_add_u32 m0, s82, 0x1000
	s_nop 0
	global_load_lds_dwordx4 v206, s[72:73]
	s_add_u32 m0, s82, 0x2000
	s_nop 0
	global_load_lds_dwordx4 v205, s[72:73]
	s_add_u32 m0, s82, 0x3000
	s_nop 0
	global_load_lds_dwordx4 v204, s[72:73]
	v_mov_b32_e32 v2, 0
	v_mov_b32_e32 v3, 0
	v_mov_b32_e32 v4, 0
	v_mov_b32_e32 v5, 0
	v_mov_b32_e32 v6, 0
	v_mov_b32_e32 v7, 0
	v_mov_b32_e32 v8, 0
	v_mov_b32_e32 v9, 0
	v_mov_b32_e32 v10, 0
	v_mov_b32_e32 v11, 0
	v_mov_b32_e32 v12, 0
	v_mov_b32_e32 v13, 0
	v_mov_b32_e32 v14, 0
	v_mov_b32_e32 v15, 0
	v_mov_b32_e32 v16, 0
	v_mov_b32_e32 v17, 0
	v_mov_b32_e32 v18, 0
	v_mov_b32_e32 v19, 0
	v_mov_b32_e32 v20, 0
	v_mov_b32_e32 v21, 0
	v_mov_b32_e32 v22, 0
	v_mov_b32_e32 v23, 0
	v_mov_b32_e32 v24, 0
	v_mov_b32_e32 v25, 0
	v_mov_b32_e32 v26, 0
	v_mov_b32_e32 v27, 0
	v_mov_b32_e32 v28, 0
	v_mov_b32_e32 v29, 0
	v_mov_b32_e32 v30, 0
	v_mov_b32_e32 v31, 0
	v_mov_b32_e32 v32, 0
	v_mov_b32_e32 v33, 0
	v_mov_b32_e32 v34, 0
	v_mov_b32_e32 v35, 0
	v_mov_b32_e32 v36, 0
	v_mov_b32_e32 v37, 0
	v_mov_b32_e32 v38, 0
	v_mov_b32_e32 v39, 0
	v_mov_b32_e32 v40, 0
	v_mov_b32_e32 v41, 0
	v_mov_b32_e32 v42, 0
	v_mov_b32_e32 v43, 0
	v_mov_b32_e32 v44, 0
	v_mov_b32_e32 v45, 0
	v_mov_b32_e32 v46, 0
	v_mov_b32_e32 v47, 0
	v_mov_b32_e32 v48, 0
	v_mov_b32_e32 v49, 0
	v_mov_b32_e32 v50, 0
	v_mov_b32_e32 v51, 0
	v_mov_b32_e32 v52, 0
	v_mov_b32_e32 v53, 0
	v_mov_b32_e32 v54, 0
	v_mov_b32_e32 v55, 0
	v_mov_b32_e32 v56, 0
	v_mov_b32_e32 v57, 0
	v_mov_b32_e32 v58, 0
	v_mov_b32_e32 v59, 0
	v_mov_b32_e32 v60, 0
	v_mov_b32_e32 v61, 0
	v_mov_b32_e32 v62, 0
	v_mov_b32_e32 v63, 0
	v_mov_b32_e32 v64, 0
	v_mov_b32_e32 v65, 0
	v_mov_b32_e32 v66, 0
	v_mov_b32_e32 v67, 0
	v_mov_b32_e32 v68, 0
	v_mov_b32_e32 v69, 0
	v_mov_b32_e32 v70, 0
	v_mov_b32_e32 v71, 0
	v_mov_b32_e32 v72, 0
	v_mov_b32_e32 v73, 0
	v_mov_b32_e32 v74, 0
	v_mov_b32_e32 v75, 0
	v_mov_b32_e32 v76, 0
	v_mov_b32_e32 v77, 0
	v_mov_b32_e32 v78, 0
	v_mov_b32_e32 v79, 0
	v_mov_b32_e32 v80, 0
	v_mov_b32_e32 v81, 0
	v_mov_b32_e32 v82, 0
	v_mov_b32_e32 v83, 0
	v_mov_b32_e32 v84, 0
	v_mov_b32_e32 v85, 0
	v_mov_b32_e32 v86, 0
	v_mov_b32_e32 v87, 0
	v_mov_b32_e32 v88, 0
	v_mov_b32_e32 v89, 0
	v_mov_b32_e32 v90, 0
	v_mov_b32_e32 v91, 0
	v_mov_b32_e32 v92, 0
	v_mov_b32_e32 v93, 0
	v_mov_b32_e32 v94, 0
	v_mov_b32_e32 v95, 0
	v_mov_b32_e32 v96, 0
	v_mov_b32_e32 v97, 0
	s_waitcnt vmcnt(10)
	s_barrier
	ds_read_b128 v[240:243], v211 offset:0
	ds_read_b128 v[252:255], v215 offset:0
	ds_read_b128 v[236:239], v211 offset:4096
	ds_read_b128 v[248:251], v215 offset:4096
	ds_read_b128 v[244:247], v215 offset:8192
	s_mov_b32 s78, 0
.Lgm_ph11_loop:
	s_waitcnt lgkmcnt(1)
	v_mfma_f32_32x32x16_bf16 v[82:97], v[240:243], v[252:255], v[82:97]
	ds_read_b128 v[220:223], v210 offset:0
	v_mfma_f32_32x32x16_bf16 v[66:81], v[236:239], v[252:255], v[66:81]
	ds_read_b128 v[232:235], v214 offset:0
	v_mfma_f32_32x32x16_bf16 v[50:65], v[240:243], v[248:251], v[50:65]
	ds_read_b128 v[216:219], v210 offset:4096
	v_mfma_f32_32x32x16_bf16 v[34:49], v[236:239], v[248:251], v[34:49]
	ds_read_b128 v[228:231], v214 offset:4096
	s_waitcnt lgkmcnt(4)
	v_mfma_f32_32x32x16_bf16 v[18:33], v[240:243], v[244:247], v[18:33]
	ds_read_b128 v[224:227], v214 offset:8192
	v_mfma_f32_32x32x16_bf16 v[2:17], v[236:239], v[244:247], v[2:17]
	s_waitcnt lgkmcnt(1)
	v_mfma_f32_32x32x16_bf16 v[82:97], v[220:223], v[232:235], v[82:97]
	ds_read_b128 v[240:243], v209 offset:0
	v_mfma_f32_32x32x16_bf16 v[66:81], v[216:219], v[232:235], v[66:81]
	ds_read_b128 v[252:255], v213 offset:0
	v_mfma_f32_32x32x16_bf16 v[50:65], v[220:223], v[228:231], v[50:65]
	ds_read_b128 v[236:239], v209 offset:4096
	v_mfma_f32_32x32x16_bf16 v[34:49], v[216:219], v[228:231], v[34:49]
	ds_read_b128 v[248:251], v213 offset:4096
	s_waitcnt lgkmcnt(4)
	v_mfma_f32_32x32x16_bf16 v[18:33], v[220:223], v[224:227], v[18:33]
	ds_read_b128 v[244:247], v213 offset:8192
	v_mfma_f32_32x32x16_bf16 v[2:17], v[216:219], v[224:227], v[2:17]
	s_waitcnt lgkmcnt(1)
	v_mfma_f32_32x32x16_bf16 v[82:97], v[240:243], v[252:255], v[82:97]
	ds_read_b128 v[220:223], v208 offset:0
	s_add_u32 s83, s79, s78
	s_add_u32 s83, s83, 2
	s_and_b32 s83, s83, 15
	v_mfma_f32_32x32x16_bf16 v[66:81], v[236:239], v[252:255], v[66:81]
	ds_read_b128 v[232:235], v212 offset:0
	s_lshl_b32 s83, s83, 7
	s_add_u32 s70, s66, s83
	v_mfma_f32_32x32x16_bf16 v[50:65], v[240:243], v[248:251], v[50:65]
	ds_read_b128 v[216:219], v208 offset:4096
	s_addc_u32 s71, s67, 0
	s_add_u32 s72, s68, s83
	v_mfma_f32_32x32x16_bf16 v[34:49], v[236:239], v[248:251], v[34:49]
	ds_read_b128 v[228:231], v212 offset:4096
	s_addc_u32 s73, s69, 0
	s_add_u32 s81, s80, 0x0
	s_add_u32 s82, s80, 0xc000
	s_waitcnt lgkmcnt(4)
	v_mfma_f32_32x32x16_bf16 v[18:33], v[240:243], v[244:247], v[18:33]
	ds_read_b128 v[224:227], v212 offset:8192
	v_mfma_f32_32x32x16_bf16 v[2:17], v[236:239], v[244:247], v[2:17]
	s_waitcnt vmcnt(0) lgkmcnt(0)
	s_barrier
	v_mfma_f32_32x32x16_bf16 v[82:97], v[220:223], v[232:235], v[82:97]
	s_add_u32 m0, s81, 0x0
	ds_read_b128 v[240:243], v211 offset:16384
	global_load_lds_dwordx4 v207, s[70:71]
	s_add_u32 m0, s81, 0x1000
	s_nop 0
	global_load_lds_dwordx4 v206, s[70:71]
	v_mfma_f32_32x32x16_bf16 v[66:81], v[216:219], v[232:235], v[66:81]
	s_add_u32 m0, s81, 0x2000
	ds_read_b128 v[252:255], v215 offset:24576
	global_load_lds_dwordx4 v205, s[70:71]
	s_add_u32 m0, s81, 0x3000
	s_nop 0
	global_load_lds_dwordx4 v204, s[70:71]
	v_mfma_f32_32x32x16_bf16 v[50:65], v[220:223], v[228:231], v[50:65]
	s_add_u32 m0, s81, 0x4000
	ds_read_b128 v[236:239], v211 offset:20480
	global_load_lds_dwordx4 v203, s[70:71]
	s_add_u32 m0, s81, 0x5000
	s_nop 0
	global_load_lds_dwordx4 v202, s[70:71]
	v_mfma_f32_32x32x16_bf16 v[34:49], v[216:219], v[228:231], v[34:49]
	s_add_u32 m0, s82, 0x0
	ds_read_b128 v[248:251], v215 offset:28672
	global_load_lds_dwordx4 v207, s[72:73]
	s_add_u32 m0, s82, 0x1000
	s_nop 0
	global_load_lds_dwordx4 v206, s[72:73]
	v_mfma_f32_32x32x16_bf16 v[18:33], v[220:223], v[224:227], v[18:33]
	s_add_u32 m0, s82, 0x2000
	ds_read_b128 v[244:247], v215 offset:32768
	global_load_lds_dwordx4 v205, s[72:73]
	s_add_u32 m0, s82, 0x3000
	s_nop 0
	global_load_lds_dwordx4 v204, s[72:73]
	v_mfma_f32_32x32x16_bf16 v[2:17], v[216:219], v[224:227], v[2:17]
	s_waitcnt lgkmcnt(1)
	v_mfma_f32_32x32x16_bf16 v[82:97], v[240:243], v[252:255], v[82:97]
	ds_read_b128 v[220:223], v210 offset:16384
	v_mfma_f32_32x32x16_bf16 v[66:81], v[236:239], v[252:255], v[66:81]
	ds_read_b128 v[232:235], v214 offset:24576
	v_mfma_f32_32x32x16_bf16 v[50:65], v[240:243], v[248:251], v[50:65]
	ds_read_b128 v[216:219], v210 offset:20480
	v_mfma_f32_32x32x16_bf16 v[34:49], v[236:239], v[248:251], v[34:49]
	ds_read_b128 v[228:231], v214 offset:28672
	s_waitcnt lgkmcnt(4)
	v_mfma_f32_32x32x16_bf16 v[18:33], v[240:243], v[244:247], v[18:33]
	ds_read_b128 v[224:227], v214 offset:32768
	v_mfma_f32_32x32x16_bf16 v[2:17], v[236:239], v[244:247], v[2:17]
	s_waitcnt lgkmcnt(1)
	v_mfma_f32_32x32x16_bf16 v[82:97], v[220:223], v[232:235], v[82:97]
	ds_read_b128 v[240:243], v209 offset:16384
	v_mfma_f32_32x32x16_bf16 v[66:81], v[216:219], v[232:235], v[66:81]
	ds_read_b128 v[252:255], v213 offset:24576
	v_mfma_f32_32x32x16_bf16 v[50:65], v[220:223], v[228:231], v[50:65]
	ds_read_b128 v[236:239], v209 offset:20480
	v_mfma_f32_32x32x16_bf16 v[34:49], v[216:219], v[228:231], v[34:49]
	ds_read_b128 v[248:251], v213 offset:28672
	s_waitcnt lgkmcnt(4)
	v_mfma_f32_32x32x16_bf16 v[18:33], v[220:223], v[224:227], v[18:33]
	ds_read_b128 v[244:247], v213 offset:32768
	v_mfma_f32_32x32x16_bf16 v[2:17], v[216:219], v[224:227], v[2:17]
	s_waitcnt lgkmcnt(1)
	v_mfma_f32_32x32x16_bf16 v[82:97], v[240:243], v[252:255], v[82:97]
	ds_read_b128 v[220:223], v208 offset:16384
	s_add_u32 s83, s79, s78
	s_add_u32 s83, s83, 3
	s_and_b32 s83, s83, 15
	v_mfma_f32_32x32x16_bf16 v[66:81], v[236:239], v[252:255], v[66:81]
	ds_read_b128 v[232:235], v212 offset:24576
	s_lshl_b32 s83, s83, 7
	s_add_u32 s70, s66, s83
	v_mfma_f32_32x32x16_bf16 v[50:65], v[240:243], v[248:251], v[50:65]
	ds_read_b128 v[216:219], v208 offset:20480
	s_addc_u32 s71, s67, 0
	s_add_u32 s72, s68, s83
	v_mfma_f32_32x32x16_bf16 v[34:49], v[236:239], v[248:251], v[34:49]
	ds_read_b128 v[228:231], v212 offset:28672
	s_addc_u32 s73, s69, 0
	s_add_u32 s81, s80, 0x6000
	s_add_u32 s82, s80, 0x10000
	s_waitcnt lgkmcnt(4)
	v_mfma_f32_32x32x16_bf16 v[18:33], v[240:243], v[244:247], v[18:33]
	ds_read_b128 v[224:227], v212 offset:32768
	v_mfma_f32_32x32x16_bf16 v[2:17], v[236:239], v[244:247], v[2:17]
	s_waitcnt vmcnt(0) lgkmcnt(0)
	s_barrier
	v_mfma_f32_32x32x16_bf16 v[82:97], v[220:223], v[232:235], v[82:97]
	s_add_u32 m0, s81, 0x0
	ds_read_b128 v[240:243], v211 offset:0
	global_load_lds_dwordx4 v207, s[70:71]
	s_add_u32 m0, s81, 0x1000
	s_nop 0
	global_load_lds_dwordx4 v206, s[70:71]
	v_mfma_f32_32x32x16_bf16 v[66:81], v[216:219], v[232:235], v[66:81]
	s_add_u32 m0, s81, 0x2000
	ds_read_b128 v[252:255], v215 offset:0
	global_load_lds_dwordx4 v205, s[70:71]
	s_add_u32 m0, s81, 0x3000
	s_nop 0
	global_load_lds_dwordx4 v204, s[70:71]
	v_mfma_f32_32x32x16_bf16 v[50:65], v[220:223], v[228:231], v[50:65]
	s_add_u32 m0, s81, 0x4000
	ds_read_b128 v[236:239], v211 offset:4096
	global_load_lds_dwordx4 v203, s[70:71]
	s_add_u32 m0, s81, 0x5000
	s_nop 0
	global_load_lds_dwordx4 v202, s[70:71]
	v_mfma_f32_32x32x16_bf16 v[34:49], v[216:219], v[228:231], v[34:49]
	s_add_u32 m0, s82, 0x0
	ds_read_b128 v[248:251], v215 offset:4096
	global_load_lds_dwordx4 v207, s[72:73]
	s_add_u32 m0, s82, 0x1000
	s_nop 0
	global_load_lds_dwordx4 v206, s[72:73]
	v_mfma_f32_32x32x16_bf16 v[18:33], v[220:223], v[224:227], v[18:33]
	s_add_u32 m0, s82, 0x2000
	ds_read_b128 v[244:247], v215 offset:8192
	global_load_lds_dwordx4 v205, s[72:73]
	s_add_u32 m0, s82, 0x3000
	s_nop 0
	global_load_lds_dwordx4 v204, s[72:73]
	v_mfma_f32_32x32x16_bf16 v[2:17], v[216:219], v[224:227], v[2:17]
	s_add_u32 s78, s78, 2
	s_cmp_lt_u32 s78, 14
	s_cbranch_scc1 .Lgm_ph11_loop
	s_waitcnt lgkmcnt(1)
	v_mfma_f32_32x32x16_bf16 v[82:97], v[240:243], v[252:255], v[82:97]
	ds_read_b128 v[220:223], v210 offset:0
	v_mfma_f32_32x32x16_bf16 v[66:81], v[236:239], v[252:255], v[66:81]
	ds_read_b128 v[232:235], v214 offset:0
	v_mfma_f32_32x32x16_bf16 v[50:65], v[240:243], v[248:251], v[50:65]
	ds_read_b128 v[216:219], v210 offset:4096
	v_mfma_f32_32x32x16_bf16 v[34:49], v[236:239], v[248:251], v[34:49]
	ds_read_b128 v[228:231], v214 offset:4096
	s_waitcnt lgkmcnt(4)
	v_mfma_f32_32x32x16_bf16 v[18:33], v[240:243], v[244:247], v[18:33]
	ds_read_b128 v[224:227], v214 offset:8192
	v_mfma_f32_32x32x16_bf16 v[2:17], v[236:239], v[244:247], v[2:17]
	s_waitcnt lgkmcnt(1)
	v_mfma_f32_32x32x16_bf16 v[82:97], v[220:223], v[232:235], v[82:97]
	ds_read_b128 v[240:243], v209 offset:0
	v_mfma_f32_32x32x16_bf16 v[66:81], v[216:219], v[232:235], v[66:81]
	ds_read_b128 v[252:255], v213 offset:0
	v_mfma_f32_32x32x16_bf16 v[50:65], v[220:223], v[228:231], v[50:65]
	ds_read_b128 v[236:239], v209 offset:4096
	v_mfma_f32_32x32x16_bf16 v[34:49], v[216:219], v[228:231], v[34:49]
	ds_read_b128 v[248:251], v213 offset:4096
	s_waitcnt lgkmcnt(4)
	v_mfma_f32_32x32x16_bf16 v[18:33], v[220:223], v[224:227], v[18:33]
	ds_read_b128 v[244:247], v213 offset:8192
	v_mfma_f32_32x32x16_bf16 v[2:17], v[216:219], v[224:227], v[2:17]
	s_waitcnt lgkmcnt(1)
	v_mfma_f32_32x32x16_bf16 v[82:97], v[240:243], v[252:255], v[82:97]
	ds_read_b128 v[220:223], v208 offset:0
	v_mfma_f32_32x32x16_bf16 v[66:81], v[236:239], v[252:255], v[66:81]
	ds_read_b128 v[232:235], v212 offset:0
	v_mfma_f32_32x32x16_bf16 v[50:65], v[240:243], v[248:251], v[50:65]
	ds_read_b128 v[216:219], v208 offset:4096
	v_mfma_f32_32x32x16_bf16 v[34:49], v[236:239], v[248:251], v[34:49]
	ds_read_b128 v[228:231], v212 offset:4096
	s_waitcnt lgkmcnt(4)
	v_mfma_f32_32x32x16_bf16 v[18:33], v[240:243], v[244:247], v[18:33]
	ds_read_b128 v[224:227], v212 offset:8192
	v_mfma_f32_32x32x16_bf16 v[2:17], v[236:239], v[244:247], v[2:17]
	s_waitcnt vmcnt(0) lgkmcnt(0)
	s_barrier
	v_mfma_f32_32x32x16_bf16 v[82:97], v[220:223], v[232:235], v[82:97]
	ds_read_b128 v[240:243], v211 offset:16384
	v_mfma_f32_32x32x16_bf16 v[66:81], v[216:219], v[232:235], v[66:81]
	ds_read_b128 v[252:255], v215 offset:24576
	v_mfma_f32_32x32x16_bf16 v[50:65], v[220:223], v[228:231], v[50:65]
	ds_read_b128 v[236:239], v211 offset:20480
	v_mfma_f32_32x32x16_bf16 v[34:49], v[216:219], v[228:231], v[34:49]
	ds_read_b128 v[248:251], v215 offset:28672
	v_mfma_f32_32x32x16_bf16 v[18:33], v[220:223], v[224:227], v[18:33]
	ds_read_b128 v[244:247], v215 offset:32768
	v_mfma_f32_32x32x16_bf16 v[2:17], v[216:219], v[224:227], v[2:17]
	s_waitcnt lgkmcnt(1)
	v_mfma_f32_32x32x16_bf16 v[82:97], v[240:243], v[252:255], v[82:97]
	ds_read_b128 v[220:223], v210 offset:16384
	v_mfma_f32_32x32x16_bf16 v[66:81], v[236:239], v[252:255], v[66:81]
	ds_read_b128 v[232:235], v214 offset:24576
	v_mfma_f32_32x32x16_bf16 v[50:65], v[240:243], v[248:251], v[50:65]
	ds_read_b128 v[216:219], v210 offset:20480
	v_mfma_f32_32x32x16_bf16 v[34:49], v[236:239], v[248:251], v[34:49]
	ds_read_b128 v[228:231], v214 offset:28672
	s_waitcnt lgkmcnt(4)
	v_mfma_f32_32x32x16_bf16 v[18:33], v[240:243], v[244:247], v[18:33]
	ds_read_b128 v[224:227], v214 offset:32768
	v_mfma_f32_32x32x16_bf16 v[2:17], v[236:239], v[244:247], v[2:17]
	s_waitcnt lgkmcnt(1)
	v_mfma_f32_32x32x16_bf16 v[82:97], v[220:223], v[232:235], v[82:97]
	ds_read_b128 v[240:243], v209 offset:16384
	v_mfma_f32_32x32x16_bf16 v[66:81], v[216:219], v[232:235], v[66:81]
	ds_read_b128 v[252:255], v213 offset:24576
	v_mfma_f32_32x32x16_bf16 v[50:65], v[220:223], v[228:231], v[50:65]
	ds_read_b128 v[236:239], v209 offset:20480
	v_mfma_f32_32x32x16_bf16 v[34:49], v[216:219], v[228:231], v[34:49]
	ds_read_b128 v[248:251], v213 offset:28672
	s_waitcnt lgkmcnt(4)
	v_mfma_f32_32x32x16_bf16 v[18:33], v[220:223], v[224:227], v[18:33]
	ds_read_b128 v[244:247], v213 offset:32768
	v_mfma_f32_32x32x16_bf16 v[2:17], v[216:219], v[224:227], v[2:17]
	s_waitcnt lgkmcnt(1)
	v_mfma_f32_32x32x16_bf16 v[82:97], v[240:243], v[252:255], v[82:97]
	ds_read_b128 v[220:223], v208 offset:16384
	v_mfma_f32_32x32x16_bf16 v[66:81], v[236:239], v[252:255], v[66:81]
	ds_read_b128 v[232:235], v212 offset:24576
	v_mfma_f32_32x32x16_bf16 v[50:65], v[240:243], v[248:251], v[50:65]
	ds_read_b128 v[216:219], v208 offset:20480
	v_mfma_f32_32x32x16_bf16 v[34:49], v[236:239], v[248:251], v[34:49]
	ds_read_b128 v[228:231], v212 offset:28672
	s_waitcnt lgkmcnt(4)
	v_mfma_f32_32x32x16_bf16 v[18:33], v[240:243], v[244:247], v[18:33]
	ds_read_b128 v[224:227], v212 offset:32768
	v_mfma_f32_32x32x16_bf16 v[2:17], v[236:239], v[244:247], v[2:17]
	s_waitcnt vmcnt(0) lgkmcnt(0)
	s_barrier
	v_mfma_f32_32x32x16_bf16 v[82:97], v[220:223], v[232:235], v[82:97]
	v_mfma_f32_32x32x16_bf16 v[66:81], v[216:219], v[232:235], v[66:81]
	v_mfma_f32_32x32x16_bf16 v[50:65], v[220:223], v[228:231], v[50:65]
	v_mfma_f32_32x32x16_bf16 v[34:49], v[216:219], v[228:231], v[34:49]
	v_mfma_f32_32x32x16_bf16 v[18:33], v[220:223], v[224:227], v[18:33]
	v_mfma_f32_32x32x16_bf16 v[2:17], v[216:219], v[224:227], v[2:17]
	s_nop 7
	s_nop 7
	s_waitcnt lgkmcnt(0)
	s_nop 10
	ds_write_b128 v147, v[82:85]
	ds_write_b128 v147, v[86:89] offset:32
	ds_write_b128 v147, v[90:93] offset:64
	ds_write_b128 v147, v[94:97] offset:96
	ds_write_b128 v147, v[66:69] offset:128
	ds_write_b128 v147, v[70:73] offset:160
	ds_write_b128 v147, v[74:77] offset:192
	ds_write_b128 v147, v[78:81] offset:224
	s_waitcnt lgkmcnt(0)
	v_add_u32_e32 v104, s29, v111
	v_or_b32_e32 v244, s30, v120
	v_lshlrev_b32_e32 v242, 2, v244
	v_add_u32_e32 v242, s3, v242
	v_lshlrev_b32_e32 v243, 1, v244
	v_mov_b32_e32 v240, v104
	v_add_u32_e32 v241, 0xfffff000, v240
	v_lshrrev_b32_e32 v241, 11, v241
	v_mad_u32_u24 v241, v241, s26, s26
	v_lshlrev_b32_e32 v241, 2, v241
	v_or_b32_e32 v232, v240, v119
	v_or_b32_e32 v233, v240, v121
	v_or_b32_e32 v234, v240, v122
	v_or_b32_e32 v235, v240, v123
	v_or_b32_e32 v236, v240, v124
	v_or_b32_e32 v237, v240, v125
	v_or_b32_e32 v238, v240, v126
	v_or_b32_e32 v239, v240, v127
	v_cmp_lt_i32_e64 s[82:83], s27, v232
	v_cmp_lt_i32_e64 s[84:85], s27, v233
	v_cmp_lt_i32_e64 s[86:87], s27, v234
	v_cmp_lt_i32_e64 s[88:89], s27, v235
	v_cmp_lt_i32_e64 s[90:91], s27, v236
	v_cmp_lt_i32_e64 s[92:93], s27, v237
	v_cmp_lt_i32_e64 s[94:95], s27, v238
	v_cmp_lt_i32_e64 s[96:97], s27, v239
	s_waitcnt lgkmcnt(0)
	v_cndmask_b32_e64 v200, 0, v241, s[82:83]
	v_cndmask_b32_e64 v204, 0, v241, s[84:85]
	v_cndmask_b32_e64 v208, 0, v241, s[86:87]
	v_cndmask_b32_e64 v212, 0, v241, s[88:89]
	v_cndmask_b32_e64 v216, 0, v241, s[90:91]
	v_cndmask_b32_e64 v220, 0, v241, s[92:93]
	v_cndmask_b32_e64 v224, 0, v241, s[94:95]
	v_cndmask_b32_e64 v228, 0, v241, s[96:97]
	v_add_u32_e32 v200, v200, v242
	v_add_u32_e32 v204, v204, v242
	v_add_u32_e32 v208, v208, v242
	v_add_u32_e32 v212, v212, v242
	v_add_u32_e32 v216, v216, v242
	v_add_u32_e32 v220, v220, v242
	v_add_u32_e32 v224, v224, v242
	v_add_u32_e32 v228, v228, v242
	ds_read_b128 v[82:85], v149
	global_load_dwordx4 v[200:203], v200, s[6:7]
	ds_read_b128 v[86:89], v149 offset:1088
	global_load_dwordx4 v[204:207], v204, s[6:7]
	ds_read_b128 v[90:93], v149 offset:2176
	global_load_dwordx4 v[208:211], v208, s[6:7]
	ds_read_b128 v[94:97], v149 offset:3264
	global_load_dwordx4 v[212:215], v212, s[6:7]
	ds_read_b128 v[66:69], v149 offset:4352
	global_load_dwordx4 v[216:219], v216, s[6:7]
	ds_read_b128 v[70:73], v149 offset:5440
	global_load_dwordx4 v[220:223], v220, s[6:7]
	ds_read_b128 v[74:77], v149 offset:6528
	global_load_dwordx4 v[224:227], v224, s[6:7]
	ds_read_b128 v[78:81], v149 offset:7616
	global_load_dwordx4 v[228:231], v228, s[6:7]
	v_lshl_add_u32 v232, v232, 11, v243
	v_lshl_add_u32 v233, v233, 11, v243
	v_lshl_add_u32 v234, v234, 11, v243
	v_lshl_add_u32 v235, v235, 11, v243
	v_lshl_add_u32 v236, v236, 11, v243
	v_lshl_add_u32 v237, v237, 11, v243
	v_lshl_add_u32 v238, v238, 11, v243
	v_lshl_add_u32 v239, v239, 11, v243
	s_waitcnt vmcnt(7) lgkmcnt(7)
	v_mul_f32_e32 v82, v82, v200
	v_mul_f32_e32 v83, v83, v201
	v_mul_f32_e32 v84, v84, v202
	v_mul_f32_e32 v85, v85, v203
	v_cvt_pk_bf16_f32 v82, v82, v83
	v_cvt_pk_bf16_f32 v83, v84, v85
	global_store_dwordx2 v232, v[82:83], s[4:5]
	s_waitcnt vmcnt(7) lgkmcnt(6)
	v_mul_f32_e32 v86, v86, v204
	v_mul_f32_e32 v87, v87, v205
	v_mul_f32_e32 v88, v88, v206
	v_mul_f32_e32 v89, v89, v207
	v_cvt_pk_bf16_f32 v86, v86, v87
	v_cvt_pk_bf16_f32 v87, v88, v89
	global_store_dwordx2 v233, v[86:87], s[4:5]
	s_waitcnt vmcnt(7) lgkmcnt(5)
	v_mul_f32_e32 v90, v90, v208
	v_mul_f32_e32 v91, v91, v209
	v_mul_f32_e32 v92, v92, v210
	v_mul_f32_e32 v93, v93, v211
	v_cvt_pk_bf16_f32 v90, v90, v91
	v_cvt_pk_bf16_f32 v91, v92, v93
	global_store_dwordx2 v234, v[90:91], s[4:5]
	s_waitcnt vmcnt(7) lgkmcnt(4)
	v_mul_f32_e32 v94, v94, v212
	v_mul_f32_e32 v95, v95, v213
	v_mul_f32_e32 v96, v96, v214
	v_mul_f32_e32 v97, v97, v215
	v_cvt_pk_bf16_f32 v94, v94, v95
	v_cvt_pk_bf16_f32 v95, v96, v97
	global_store_dwordx2 v235, v[94:95], s[4:5]
	s_waitcnt vmcnt(7) lgkmcnt(3)
	v_mul_f32_e32 v66, v66, v216
	v_mul_f32_e32 v67, v67, v217
	v_mul_f32_e32 v68, v68, v218
	v_mul_f32_e32 v69, v69, v219
	v_cvt_pk_bf16_f32 v66, v66, v67
	v_cvt_pk_bf16_f32 v67, v68, v69
	global_store_dwordx2 v236, v[66:67], s[4:5]
	s_waitcnt vmcnt(7) lgkmcnt(2)
	v_mul_f32_e32 v70, v70, v220
	v_mul_f32_e32 v71, v71, v221
	v_mul_f32_e32 v72, v72, v222
	v_mul_f32_e32 v73, v73, v223
	v_cvt_pk_bf16_f32 v70, v70, v71
	v_cvt_pk_bf16_f32 v71, v72, v73
	global_store_dwordx2 v237, v[70:71], s[4:5]
	s_waitcnt vmcnt(7) lgkmcnt(1)
	v_mul_f32_e32 v74, v74, v224
	v_mul_f32_e32 v75, v75, v225
	v_mul_f32_e32 v76, v76, v226
	v_mul_f32_e32 v77, v77, v227
	v_cvt_pk_bf16_f32 v74, v74, v75
	v_cvt_pk_bf16_f32 v75, v76, v77
	global_store_dwordx2 v238, v[74:75], s[4:5]
	s_waitcnt vmcnt(7) lgkmcnt(0)
	v_mul_f32_e32 v78, v78, v228
	v_mul_f32_e32 v79, v79, v229
	v_mul_f32_e32 v80, v80, v230
	v_mul_f32_e32 v81, v81, v231
	v_cvt_pk_bf16_f32 v78, v78, v79
	v_cvt_pk_bf16_f32 v79, v80, v81
	global_store_dwordx2 v239, v[78:79], s[4:5]
	ds_write_b128 v147, v[50:53]
	ds_write_b128 v147, v[54:57] offset:32
	ds_write_b128 v147, v[58:61] offset:64
	ds_write_b128 v147, v[62:65] offset:96
	ds_write_b128 v147, v[34:37] offset:128
	ds_write_b128 v147, v[38:41] offset:160
	ds_write_b128 v147, v[42:45] offset:192
	ds_write_b128 v147, v[46:49] offset:224
	v_add_u32_e32 v240, 0x20, v104
	v_add_u32_e32 v241, 0xfffff000, v240
	v_lshrrev_b32_e32 v241, 11, v241
	v_mad_u32_u24 v241, v241, s26, s26
	v_lshlrev_b32_e32 v241, 2, v241
	v_or_b32_e32 v232, v240, v119
	v_or_b32_e32 v233, v240, v121
	v_or_b32_e32 v234, v240, v122
	v_or_b32_e32 v235, v240, v123
	v_or_b32_e32 v236, v240, v124
	v_or_b32_e32 v237, v240, v125
	v_or_b32_e32 v238, v240, v126
	v_or_b32_e32 v239, v240, v127
	v_cmp_lt_i32_e64 s[82:83], s27, v232
	v_cmp_lt_i32_e64 s[84:85], s27, v233
	v_cmp_lt_i32_e64 s[86:87], s27, v234
	v_cmp_lt_i32_e64 s[88:89], s27, v235
	v_cmp_lt_i32_e64 s[90:91], s27, v236
	v_cmp_lt_i32_e64 s[92:93], s27, v237
	v_cmp_lt_i32_e64 s[94:95], s27, v238
	v_cmp_lt_i32_e64 s[96:97], s27, v239
	s_waitcnt lgkmcnt(0)
	v_cndmask_b32_e64 v200, 0, v241, s[82:83]
	v_cndmask_b32_e64 v204, 0, v241, s[84:85]
	v_cndmask_b32_e64 v208, 0, v241, s[86:87]
	v_cndmask_b32_e64 v212, 0, v241, s[88:89]
	v_cndmask_b32_e64 v216, 0, v241, s[90:91]
	v_cndmask_b32_e64 v220, 0, v241, s[92:93]
	v_cndmask_b32_e64 v224, 0, v241, s[94:95]
	v_cndmask_b32_e64 v228, 0, v241, s[96:97]
	v_add_u32_e32 v200, v200, v242
	v_add_u32_e32 v204, v204, v242
	v_add_u32_e32 v208, v208, v242
	v_add_u32_e32 v212, v212, v242
	v_add_u32_e32 v216, v216, v242
	v_add_u32_e32 v220, v220, v242
	v_add_u32_e32 v224, v224, v242
	v_add_u32_e32 v228, v228, v242
	ds_read_b128 v[50:53], v149
	global_load_dwordx4 v[200:203], v200, s[6:7]
	ds_read_b128 v[54:57], v149 offset:1088
	global_load_dwordx4 v[204:207], v204, s[6:7]
	ds_read_b128 v[58:61], v149 offset:2176
	global_load_dwordx4 v[208:211], v208, s[6:7]
	ds_read_b128 v[62:65], v149 offset:3264
	global_load_dwordx4 v[212:215], v212, s[6:7]
	ds_read_b128 v[34:37], v149 offset:4352
	global_load_dwordx4 v[216:219], v216, s[6:7]
	ds_read_b128 v[38:41], v149 offset:5440
	global_load_dwordx4 v[220:223], v220, s[6:7]
	ds_read_b128 v[42:45], v149 offset:6528
	global_load_dwordx4 v[224:227], v224, s[6:7]
	ds_read_b128 v[46:49], v149 offset:7616
	global_load_dwordx4 v[228:231], v228, s[6:7]
	v_lshl_add_u32 v232, v232, 11, v243
	v_lshl_add_u32 v233, v233, 11, v243
	v_lshl_add_u32 v234, v234, 11, v243
	v_lshl_add_u32 v235, v235, 11, v243
	v_lshl_add_u32 v236, v236, 11, v243
	v_lshl_add_u32 v237, v237, 11, v243
	v_lshl_add_u32 v238, v238, 11, v243
	v_lshl_add_u32 v239, v239, 11, v243
	s_waitcnt vmcnt(7) lgkmcnt(7)
	v_mul_f32_e32 v50, v50, v200
	v_mul_f32_e32 v51, v51, v201
	v_mul_f32_e32 v52, v52, v202
	v_mul_f32_e32 v53, v53, v203
	v_cvt_pk_bf16_f32 v50, v50, v51
	v_cvt_pk_bf16_f32 v51, v52, v53
	global_store_dwordx2 v232, v[50:51], s[4:5]
	s_waitcnt vmcnt(7) lgkmcnt(6)
	v_mul_f32_e32 v54, v54, v204
	v_mul_f32_e32 v55, v55, v205
	v_mul_f32_e32 v56, v56, v206
	v_mul_f32_e32 v57, v57, v207
	v_cvt_pk_bf16_f32 v54, v54, v55
	v_cvt_pk_bf16_f32 v55, v56, v57
	global_store_dwordx2 v233, v[54:55], s[4:5]
	s_waitcnt vmcnt(7) lgkmcnt(5)
	v_mul_f32_e32 v58, v58, v208
	v_mul_f32_e32 v59, v59, v209
	v_mul_f32_e32 v60, v60, v210
	v_mul_f32_e32 v61, v61, v211
	v_cvt_pk_bf16_f32 v58, v58, v59
	v_cvt_pk_bf16_f32 v59, v60, v61
	global_store_dwordx2 v234, v[58:59], s[4:5]
	s_waitcnt vmcnt(7) lgkmcnt(4)
	v_mul_f32_e32 v62, v62, v212
	v_mul_f32_e32 v63, v63, v213
	v_mul_f32_e32 v64, v64, v214
	v_mul_f32_e32 v65, v65, v215
	v_cvt_pk_bf16_f32 v62, v62, v63
	v_cvt_pk_bf16_f32 v63, v64, v65
	global_store_dwordx2 v235, v[62:63], s[4:5]
	s_waitcnt vmcnt(7) lgkmcnt(3)
	v_mul_f32_e32 v34, v34, v216
	v_mul_f32_e32 v35, v35, v217
	v_mul_f32_e32 v36, v36, v218
	v_mul_f32_e32 v37, v37, v219
	v_cvt_pk_bf16_f32 v34, v34, v35
	v_cvt_pk_bf16_f32 v35, v36, v37
	global_store_dwordx2 v236, v[34:35], s[4:5]
	s_waitcnt vmcnt(7) lgkmcnt(2)
	v_mul_f32_e32 v38, v38, v220
	v_mul_f32_e32 v39, v39, v221
	v_mul_f32_e32 v40, v40, v222
	v_mul_f32_e32 v41, v41, v223
	v_cvt_pk_bf16_f32 v38, v38, v39
	v_cvt_pk_bf16_f32 v39, v40, v41
	global_store_dwordx2 v237, v[38:39], s[4:5]
	s_waitcnt vmcnt(7) lgkmcnt(1)
	v_mul_f32_e32 v42, v42, v224
	v_mul_f32_e32 v43, v43, v225
	v_mul_f32_e32 v44, v44, v226
	v_mul_f32_e32 v45, v45, v227
	v_cvt_pk_bf16_f32 v42, v42, v43
	v_cvt_pk_bf16_f32 v43, v44, v45
	global_store_dwordx2 v238, v[42:43], s[4:5]
	s_waitcnt vmcnt(7) lgkmcnt(0)
	v_mul_f32_e32 v46, v46, v228
	v_mul_f32_e32 v47, v47, v229
	v_mul_f32_e32 v48, v48, v230
	v_mul_f32_e32 v49, v49, v231
	v_cvt_pk_bf16_f32 v46, v46, v47
	v_cvt_pk_bf16_f32 v47, v48, v49
	global_store_dwordx2 v239, v[46:47], s[4:5]
	ds_write_b128 v147, v[18:21]
	ds_write_b128 v147, v[22:25] offset:32
	ds_write_b128 v147, v[26:29] offset:64
	ds_write_b128 v147, v[30:33] offset:96
	ds_write_b128 v147, v[2:5] offset:128
	ds_write_b128 v147, v[6:9] offset:160
	ds_write_b128 v147, v[10:13] offset:192
	ds_write_b128 v147, v[14:17] offset:224
	v_add_u32_e32 v240, 0x40, v104
	v_add_u32_e32 v241, 0xfffff000, v240
	v_lshrrev_b32_e32 v241, 11, v241
	v_mad_u32_u24 v241, v241, s26, s26
	v_lshlrev_b32_e32 v241, 2, v241
	v_or_b32_e32 v232, v240, v119
	v_or_b32_e32 v233, v240, v121
	v_or_b32_e32 v234, v240, v122
	v_or_b32_e32 v235, v240, v123
	v_or_b32_e32 v236, v240, v124
	v_or_b32_e32 v237, v240, v125
	v_or_b32_e32 v238, v240, v126
	v_or_b32_e32 v239, v240, v127
	v_cmp_lt_i32_e64 s[82:83], s27, v232
	v_cmp_lt_i32_e64 s[84:85], s27, v233
	v_cmp_lt_i32_e64 s[86:87], s27, v234
	v_cmp_lt_i32_e64 s[88:89], s27, v235
	v_cmp_lt_i32_e64 s[90:91], s27, v236
	v_cmp_lt_i32_e64 s[92:93], s27, v237
	v_cmp_lt_i32_e64 s[94:95], s27, v238
	v_cmp_lt_i32_e64 s[96:97], s27, v239
	s_waitcnt lgkmcnt(0)
	v_cndmask_b32_e64 v200, 0, v241, s[82:83]
	v_cndmask_b32_e64 v204, 0, v241, s[84:85]
	v_cndmask_b32_e64 v208, 0, v241, s[86:87]
	v_cndmask_b32_e64 v212, 0, v241, s[88:89]
	v_cndmask_b32_e64 v216, 0, v241, s[90:91]
	v_cndmask_b32_e64 v220, 0, v241, s[92:93]
	v_cndmask_b32_e64 v224, 0, v241, s[94:95]
	v_cndmask_b32_e64 v228, 0, v241, s[96:97]
	v_add_u32_e32 v200, v200, v242
	v_add_u32_e32 v204, v204, v242
	v_add_u32_e32 v208, v208, v242
	v_add_u32_e32 v212, v212, v242
	v_add_u32_e32 v216, v216, v242
	v_add_u32_e32 v220, v220, v242
	v_add_u32_e32 v224, v224, v242
	v_add_u32_e32 v228, v228, v242
	ds_read_b128 v[18:21], v149
	global_load_dwordx4 v[200:203], v200, s[6:7]
	ds_read_b128 v[22:25], v149 offset:1088
	global_load_dwordx4 v[204:207], v204, s[6:7]
	ds_read_b128 v[26:29], v149 offset:2176
	global_load_dwordx4 v[208:211], v208, s[6:7]
	ds_read_b128 v[30:33], v149 offset:3264
	global_load_dwordx4 v[212:215], v212, s[6:7]
	ds_read_b128 v[2:5], v149 offset:4352
	global_load_dwordx4 v[216:219], v216, s[6:7]
	ds_read_b128 v[6:9], v149 offset:5440
	global_load_dwordx4 v[220:223], v220, s[6:7]
	ds_read_b128 v[10:13], v149 offset:6528
	global_load_dwordx4 v[224:227], v224, s[6:7]
	ds_read_b128 v[14:17], v149 offset:7616
	global_load_dwordx4 v[228:231], v228, s[6:7]
	v_lshl_add_u32 v232, v232, 11, v243
	v_lshl_add_u32 v233, v233, 11, v243
	v_lshl_add_u32 v234, v234, 11, v243
	v_lshl_add_u32 v235, v235, 11, v243
	v_lshl_add_u32 v236, v236, 11, v243
	v_lshl_add_u32 v237, v237, 11, v243
	v_lshl_add_u32 v238, v238, 11, v243
	v_lshl_add_u32 v239, v239, 11, v243
	s_waitcnt vmcnt(7) lgkmcnt(7)
	v_mul_f32_e32 v18, v18, v200
	v_mul_f32_e32 v19, v19, v201
	v_mul_f32_e32 v20, v20, v202
	v_mul_f32_e32 v21, v21, v203
	v_cvt_pk_bf16_f32 v18, v18, v19
	v_cvt_pk_bf16_f32 v19, v20, v21
	global_store_dwordx2 v232, v[18:19], s[4:5]
	s_waitcnt vmcnt(7) lgkmcnt(6)
	v_mul_f32_e32 v22, v22, v204
	v_mul_f32_e32 v23, v23, v205
	v_mul_f32_e32 v24, v24, v206
	v_mul_f32_e32 v25, v25, v207
	v_cvt_pk_bf16_f32 v22, v22, v23
	v_cvt_pk_bf16_f32 v23, v24, v25
	global_store_dwordx2 v233, v[22:23], s[4:5]
	s_waitcnt vmcnt(7) lgkmcnt(5)
	v_mul_f32_e32 v26, v26, v208
	v_mul_f32_e32 v27, v27, v209
	v_mul_f32_e32 v28, v28, v210
	v_mul_f32_e32 v29, v29, v211
	v_cvt_pk_bf16_f32 v26, v26, v27
	v_cvt_pk_bf16_f32 v27, v28, v29
	global_store_dwordx2 v234, v[26:27], s[4:5]
	s_waitcnt vmcnt(7) lgkmcnt(4)
	v_mul_f32_e32 v30, v30, v212
	v_mul_f32_e32 v31, v31, v213
	v_mul_f32_e32 v32, v32, v214
	v_mul_f32_e32 v33, v33, v215
	v_cvt_pk_bf16_f32 v30, v30, v31
	v_cvt_pk_bf16_f32 v31, v32, v33
	global_store_dwordx2 v235, v[30:31], s[4:5]
	s_waitcnt vmcnt(7) lgkmcnt(3)
	v_mul_f32_e32 v2, v2, v216
	v_mul_f32_e32 v3, v3, v217
	v_mul_f32_e32 v4, v4, v218
	v_mul_f32_e32 v5, v5, v219
	v_cvt_pk_bf16_f32 v2, v2, v3
	v_cvt_pk_bf16_f32 v3, v4, v5
	global_store_dwordx2 v236, v[2:3], s[4:5]
	s_waitcnt vmcnt(7) lgkmcnt(2)
	v_mul_f32_e32 v6, v6, v220
	v_mul_f32_e32 v7, v7, v221
	v_mul_f32_e32 v8, v8, v222
	v_mul_f32_e32 v9, v9, v223
	v_cvt_pk_bf16_f32 v6, v6, v7
	v_cvt_pk_bf16_f32 v7, v8, v9
	global_store_dwordx2 v237, v[6:7], s[4:5]
	s_waitcnt vmcnt(7) lgkmcnt(1)
	v_mul_f32_e32 v10, v10, v224
	v_mul_f32_e32 v11, v11, v225
	v_mul_f32_e32 v12, v12, v226
	v_mul_f32_e32 v13, v13, v227
	v_cvt_pk_bf16_f32 v10, v10, v11
	v_cvt_pk_bf16_f32 v11, v12, v13
	global_store_dwordx2 v238, v[10:11], s[4:5]
	s_waitcnt vmcnt(7) lgkmcnt(0)
	v_mul_f32_e32 v14, v14, v228
	v_mul_f32_e32 v15, v15, v229
	v_mul_f32_e32 v16, v16, v230
	v_mul_f32_e32 v17, v17, v231
	v_cvt_pk_bf16_f32 v14, v14, v15
	v_cvt_pk_bf16_f32 v15, v16, v17
	global_store_dwordx2 v239, v[14:15], s[4:5]
	s_waitcnt lgkmcnt(0)
	s_load_dword s10, s[8:9], 0x0
	s_waitcnt lgkmcnt(0)
	s_add_i32 s28, s10, s28
	s_cmpk_lt_i32 s28, 0x200
	s_cbranch_scc1 .LBB0_1133

.LBB0_1270:
	s_ashr_i32 s4, s64, 31
	s_lshr_b32 s4, s4, 26
	s_add_i32 s4, s64, s4
	s_ashr_i32 s5, s4, 6
	s_and_b32 s4, s4, 0x3ffffc0
	s_sub_i32 s6, s64, s4
	s_mulk_i32 s6, 0xc0
	v_add_u32_e32 v2, s6, v116
	s_lshr_b32 s7, s6, 6
	s_lshl_b32 s4, s5, 7
	v_ashrrev_i32_e32 v3, 31, v2
	s_add_i32 s7, s7, s5
	v_lshlrev_b64 v[2:3], 11, v[2:3]
	v_or_b32_e32 v4, s4, v116
	s_lshl_b32 s46, s7, 6
	s_lshl_b32 s7, s7, 7
	v_ashrrev_i32_e32 v5, 31, v4
	v_lshl_add_u64 v[112:113], v[104:105], 0, v[2:3]
	s_and_b32 s16, s7, 0x780
	v_readfirstlane_b32 s7, v117
	v_add_u32_e32 v6, 0x1000, v117
	v_lshlrev_b64 v[4:5], 11, v[4:5]
	v_lshl_add_u64 v[2:3], v[112:113], 0, s[16:17]
	s_mov_b32 m0, s7
	v_readfirstlane_b32 s7, v6
	v_add_u32_e32 v6, 0x2000, v117
	v_lshl_add_u64 v[114:115], v[106:107], 0, v[4:5]
	s_waitcnt vmcnt(0)
	s_barrier
	s_load_dwordx2 s[66:67], s[0:1], 0x90
	s_load_dwordx2 s[68:69], s[0:1], 0xf8
	v_and_b32_e32 v201, 0x3ff, v0
	v_readfirstlane_b32 s80, v0
	v_and_b32_e32 v200, 31, v201
	v_bfe_u32 v214, v201, 1, 3
	v_bfe_u32 v213, v201, 5, 1
	v_xor_b32_e32 v214, v214, v213
	v_lshlrev_b32_e32 v214, 4, v214
	s_and_b32 s80, s80, 0x3ff
	s_lshr_b32 s83, s80, 6
	s_lshl_b32 s80, s80, 4
	s_lshr_b32 s84, s83, 1
	s_and_b32 s83, s83, 1
	s_mul_i32 s84, s84, 0x3000
	s_lshl_b32 s83, s83, 13
	s_add_u32 s83, s83, 0xc000
	v_lshlrev_b32_e32 v200, 7, v200
	v_or_b32_e32 v200, v200, v214
	v_add_u32_e32 v215, s84, v200
	v_add_u32_e32 v211, s83, v200
	v_xor_b32_e32 v214, 0x20, v215
	v_xor_b32_e32 v210, 0x20, v211
	v_xor_b32_e32 v213, 0x40, v215
	v_xor_b32_e32 v209, 0x40, v211
	v_xor_b32_e32 v212, 0x60, v215
	v_xor_b32_e32 v208, 0x60, v211
	v_bfe_u32 v200, v201, 4, 3
	v_and_b32_e32 v206, 7, v201
	v_xor_b32_e32 v200, v200, v206
	v_lshlrev_b32_e32 v200, 4, v200
	v_lshrrev_b32_e32 v206, 3, v201
	v_lshl_or_b32 v207, v206, 11, v200
	v_add_u32_e32 v206, 0x10000, v207
	v_add_u32_e32 v205, 0x20000, v207
	v_add_u32_e32 v204, 0x30000, v207
	v_add_u32_e32 v203, 0x40000, v207
	v_add_u32_e32 v202, 0x50000, v207
	s_lshr_b32 s83, s64, 6
	s_and_b32 s84, s64, 63
	s_mov_b32 s79, 0
	s_mul_i32 s84, s84, 0x60000
	s_lshl_b32 s83, s83, 18
	s_waitcnt lgkmcnt(0)
	s_add_u32 s66, s66, s84
	s_addc_u32 s67, s67, 0
	s_add_u32 s68, s68, s83
	s_addc_u32 s69, s69, 0
	s_add_u32 s83, s79, 0
	s_and_b32 s83, s83, 15
	s_lshl_b32 s83, s83, 7
	s_add_u32 s70, s66, s83
	s_addc_u32 s71, s67, 0
	s_add_u32 s72, s68, s83
	s_addc_u32 s73, s69, 0
	s_add_u32 s81, s80, 0x0
	s_add_u32 s82, s80, 0xc000
	s_add_u32 m0, s81, 0x0
	s_nop 0
	global_load_lds_dwordx4 v207, s[70:71]
	s_add_u32 m0, s81, 0x1000
	s_nop 0
	global_load_lds_dwordx4 v206, s[70:71]
	s_add_u32 m0, s81, 0x2000
	s_nop 0
	global_load_lds_dwordx4 v205, s[70:71]
	s_add_u32 m0, s81, 0x3000
	s_nop 0
	global_load_lds_dwordx4 v204, s[70:71]
	s_add_u32 m0, s81, 0x4000
	s_nop 0
	global_load_lds_dwordx4 v203, s[70:71]
	s_add_u32 m0, s81, 0x5000
	s_nop 0
	global_load_lds_dwordx4 v202, s[70:71]
	s_add_u32 m0, s82, 0x0
	s_nop 0
	global_load_lds_dwordx4 v207, s[72:73]
	s_add_u32 m0, s82, 0x1000
	s_nop 0
	global_load_lds_dwordx4 v206, s[72:73]
	s_add_u32 m0, s82, 0x2000
	s_nop 0
	global_load_lds_dwordx4 v205, s[72:73]
	s_add_u32 m0, s82, 0x3000
	s_nop 0
	global_load_lds_dwordx4 v204, s[72:73]
	s_add_u32 s83, s79, 1
	s_and_b32 s83, s83, 15
	s_lshl_b32 s83, s83, 7
	s_add_u32 s70, s66, s83
	s_addc_u32 s71, s67, 0
	s_add_u32 s72, s68, s83
	s_addc_u32 s73, s69, 0
	s_add_u32 s81, s80, 0x6000
	s_add_u32 s82, s80, 0x10000
	s_add_u32 m0, s81, 0x0
	s_nop 0
	global_load_lds_dwordx4 v207, s[70:71]
	s_add_u32 m0, s81, 0x1000
	s_nop 0
	global_load_lds_dwordx4 v206, s[70:71]
	s_add_u32 m0, s81, 0x2000
	s_nop 0
	global_load_lds_dwordx4 v205, s[70:71]
	s_add_u32 m0, s81, 0x3000
	s_nop 0
	global_load_lds_dwordx4 v204, s[70:71]
	s_add_u32 m0, s81, 0x4000
	s_nop 0
	global_load_lds_dwordx4 v203, s[70:71]
	s_add_u32 m0, s81, 0x5000
	s_nop 0
	global_load_lds_dwordx4 v202, s[70:71]
	s_add_u32 m0, s82, 0x0
	s_nop 0
	global_load_lds_dwordx4 v207, s[72:73]
	s_add_u32 m0, s82, 0x1000
	s_nop 0
	global_load_lds_dwordx4 v206, s[72:73]
	s_add_u32 m0, s82, 0x2000
	s_nop 0
	global_load_lds_dwordx4 v205, s[72:73]
	s_add_u32 m0, s82, 0x3000
	s_nop 0
	global_load_lds_dwordx4 v204, s[72:73]
	v_mov_b32_e32 v2, 0
	v_mov_b32_e32 v3, 0
	v_mov_b32_e32 v4, 0
	v_mov_b32_e32 v5, 0
	v_mov_b32_e32 v6, 0
	v_mov_b32_e32 v7, 0
	v_mov_b32_e32 v8, 0
	v_mov_b32_e32 v9, 0
	v_mov_b32_e32 v10, 0
	v_mov_b32_e32 v11, 0
	v_mov_b32_e32 v12, 0
	v_mov_b32_e32 v13, 0
	v_mov_b32_e32 v14, 0
	v_mov_b32_e32 v15, 0
	v_mov_b32_e32 v16, 0
	v_mov_b32_e32 v17, 0
	v_mov_b32_e32 v18, 0
	v_mov_b32_e32 v19, 0
	v_mov_b32_e32 v20, 0
	v_mov_b32_e32 v21, 0
	v_mov_b32_e32 v22, 0
	v_mov_b32_e32 v23, 0
	v_mov_b32_e32 v24, 0
	v_mov_b32_e32 v25, 0
	v_mov_b32_e32 v26, 0
	v_mov_b32_e32 v27, 0
	v_mov_b32_e32 v28, 0
	v_mov_b32_e32 v29, 0
	v_mov_b32_e32 v30, 0
	v_mov_b32_e32 v31, 0
	v_mov_b32_e32 v32, 0
	v_mov_b32_e32 v33, 0
	v_mov_b32_e32 v34, 0
	v_mov_b32_e32 v35, 0
	v_mov_b32_e32 v36, 0
	v_mov_b32_e32 v37, 0
	v_mov_b32_e32 v38, 0
	v_mov_b32_e32 v39, 0
	v_mov_b32_e32 v40, 0
	v_mov_b32_e32 v41, 0
	v_mov_b32_e32 v42, 0
	v_mov_b32_e32 v43, 0
	v_mov_b32_e32 v44, 0
	v_mov_b32_e32 v45, 0
	v_mov_b32_e32 v46, 0
	v_mov_b32_e32 v47, 0
	v_mov_b32_e32 v48, 0
	v_mov_b32_e32 v49, 0
	v_mov_b32_e32 v50, 0
	v_mov_b32_e32 v51, 0
	v_mov_b32_e32 v52, 0
	v_mov_b32_e32 v53, 0
	v_mov_b32_e32 v54, 0
	v_mov_b32_e32 v55, 0
	v_mov_b32_e32 v56, 0
	v_mov_b32_e32 v57, 0
	v_mov_b32_e32 v58, 0
	v_mov_b32_e32 v59, 0
	v_mov_b32_e32 v60, 0
	v_mov_b32_e32 v61, 0
	v_mov_b32_e32 v62, 0
	v_mov_b32_e32 v63, 0
	v_mov_b32_e32 v64, 0
	v_mov_b32_e32 v65, 0
	v_mov_b32_e32 v66, 0
	v_mov_b32_e32 v67, 0
	v_mov_b32_e32 v68, 0
	v_mov_b32_e32 v69, 0
	v_mov_b32_e32 v70, 0
	v_mov_b32_e32 v71, 0
	v_mov_b32_e32 v72, 0
	v_mov_b32_e32 v73, 0
	v_mov_b32_e32 v74, 0
	v_mov_b32_e32 v75, 0
	v_mov_b32_e32 v76, 0
	v_mov_b32_e32 v77, 0
	v_mov_b32_e32 v78, 0
	v_mov_b32_e32 v79, 0
	v_mov_b32_e32 v80, 0
	v_mov_b32_e32 v81, 0
	v_mov_b32_e32 v82, 0
	v_mov_b32_e32 v83, 0
	v_mov_b32_e32 v84, 0
	v_mov_b32_e32 v85, 0
	v_mov_b32_e32 v86, 0
	v_mov_b32_e32 v87, 0
	v_mov_b32_e32 v88, 0
	v_mov_b32_e32 v89, 0
	v_mov_b32_e32 v90, 0
	v_mov_b32_e32 v91, 0
	v_mov_b32_e32 v92, 0
	v_mov_b32_e32 v93, 0
	v_mov_b32_e32 v94, 0
	v_mov_b32_e32 v95, 0
	v_mov_b32_e32 v96, 0
	v_mov_b32_e32 v97, 0
	s_waitcnt vmcnt(10)
	s_barrier
	ds_read_b128 v[240:243], v211 offset:0
	ds_read_b128 v[252:255], v215 offset:0
	ds_read_b128 v[236:239], v211 offset:4096
	ds_read_b128 v[248:251], v215 offset:4096
	ds_read_b128 v[244:247], v215 offset:8192
	s_mov_b32 s78, 0
.Lgm_ph13_loop:
	s_waitcnt lgkmcnt(1)
	v_mfma_f32_32x32x16_bf16 v[82:97], v[240:243], v[252:255], v[82:97]
	ds_read_b128 v[220:223], v210 offset:0
	v_mfma_f32_32x32x16_bf16 v[66:81], v[236:239], v[252:255], v[66:81]
	ds_read_b128 v[232:235], v214 offset:0
	v_mfma_f32_32x32x16_bf16 v[50:65], v[240:243], v[248:251], v[50:65]
	ds_read_b128 v[216:219], v210 offset:4096
	v_mfma_f32_32x32x16_bf16 v[34:49], v[236:239], v[248:251], v[34:49]
	ds_read_b128 v[228:231], v214 offset:4096
	s_waitcnt lgkmcnt(4)
	v_mfma_f32_32x32x16_bf16 v[18:33], v[240:243], v[244:247], v[18:33]
	ds_read_b128 v[224:227], v214 offset:8192
	v_mfma_f32_32x32x16_bf16 v[2:17], v[236:239], v[244:247], v[2:17]
	s_waitcnt lgkmcnt(1)
	v_mfma_f32_32x32x16_bf16 v[82:97], v[220:223], v[232:235], v[82:97]
	ds_read_b128 v[240:243], v209 offset:0
	v_mfma_f32_32x32x16_bf16 v[66:81], v[216:219], v[232:235], v[66:81]
	ds_read_b128 v[252:255], v213 offset:0
	v_mfma_f32_32x32x16_bf16 v[50:65], v[220:223], v[228:231], v[50:65]
	ds_read_b128 v[236:239], v209 offset:4096
	v_mfma_f32_32x32x16_bf16 v[34:49], v[216:219], v[228:231], v[34:49]
	ds_read_b128 v[248:251], v213 offset:4096
	s_waitcnt lgkmcnt(4)
	v_mfma_f32_32x32x16_bf16 v[18:33], v[220:223], v[224:227], v[18:33]
	ds_read_b128 v[244:247], v213 offset:8192
	v_mfma_f32_32x32x16_bf16 v[2:17], v[216:219], v[224:227], v[2:17]
	s_waitcnt lgkmcnt(1)
	v_mfma_f32_32x32x16_bf16 v[82:97], v[240:243], v[252:255], v[82:97]
	ds_read_b128 v[220:223], v208 offset:0
	s_add_u32 s83, s79, s78
	s_add_u32 s83, s83, 2
	s_and_b32 s83, s83, 15
	v_mfma_f32_32x32x16_bf16 v[66:81], v[236:239], v[252:255], v[66:81]
	ds_read_b128 v[232:235], v212 offset:0
	s_lshl_b32 s83, s83, 7
	s_add_u32 s70, s66, s83
	v_mfma_f32_32x32x16_bf16 v[50:65], v[240:243], v[248:251], v[50:65]
	ds_read_b128 v[216:219], v208 offset:4096
	s_addc_u32 s71, s67, 0
	s_add_u32 s72, s68, s83
	v_mfma_f32_32x32x16_bf16 v[34:49], v[236:239], v[248:251], v[34:49]
	ds_read_b128 v[228:231], v212 offset:4096
	s_addc_u32 s73, s69, 0
	s_add_u32 s81, s80, 0x0
	s_add_u32 s82, s80, 0xc000
	s_waitcnt lgkmcnt(4)
	v_mfma_f32_32x32x16_bf16 v[18:33], v[240:243], v[244:247], v[18:33]
	ds_read_b128 v[224:227], v212 offset:8192
	v_mfma_f32_32x32x16_bf16 v[2:17], v[236:239], v[244:247], v[2:17]
	s_waitcnt vmcnt(0) lgkmcnt(0)
	s_barrier
	v_mfma_f32_32x32x16_bf16 v[82:97], v[220:223], v[232:235], v[82:97]
	s_add_u32 m0, s81, 0x0
	ds_read_b128 v[240:243], v211 offset:16384
	global_load_lds_dwordx4 v207, s[70:71]
	s_add_u32 m0, s81, 0x1000
	s_nop 0
	global_load_lds_dwordx4 v206, s[70:71]
	v_mfma_f32_32x32x16_bf16 v[66:81], v[216:219], v[232:235], v[66:81]
	s_add_u32 m0, s81, 0x2000
	ds_read_b128 v[252:255], v215 offset:24576
	global_load_lds_dwordx4 v205, s[70:71]
	s_add_u32 m0, s81, 0x3000
	s_nop 0
	global_load_lds_dwordx4 v204, s[70:71]
	v_mfma_f32_32x32x16_bf16 v[50:65], v[220:223], v[228:231], v[50:65]
	s_add_u32 m0, s81, 0x4000
	ds_read_b128 v[236:239], v211 offset:20480
	global_load_lds_dwordx4 v203, s[70:71]
	s_add_u32 m0, s81, 0x5000
	s_nop 0
	global_load_lds_dwordx4 v202, s[70:71]
	v_mfma_f32_32x32x16_bf16 v[34:49], v[216:219], v[228:231], v[34:49]
	s_add_u32 m0, s82, 0x0
	ds_read_b128 v[248:251], v215 offset:28672
	global_load_lds_dwordx4 v207, s[72:73]
	s_add_u32 m0, s82, 0x1000
	s_nop 0
	global_load_lds_dwordx4 v206, s[72:73]
	v_mfma_f32_32x32x16_bf16 v[18:33], v[220:223], v[224:227], v[18:33]
	s_add_u32 m0, s82, 0x2000
	ds_read_b128 v[244:247], v215 offset:32768
	global_load_lds_dwordx4 v205, s[72:73]
	s_add_u32 m0, s82, 0x3000
	s_nop 0
	global_load_lds_dwordx4 v204, s[72:73]
	v_mfma_f32_32x32x16_bf16 v[2:17], v[216:219], v[224:227], v[2:17]
	s_waitcnt lgkmcnt(1)
	v_mfma_f32_32x32x16_bf16 v[82:97], v[240:243], v[252:255], v[82:97]
	ds_read_b128 v[220:223], v210 offset:16384
	v_mfma_f32_32x32x16_bf16 v[66:81], v[236:239], v[252:255], v[66:81]
	ds_read_b128 v[232:235], v214 offset:24576
	v_mfma_f32_32x32x16_bf16 v[50:65], v[240:243], v[248:251], v[50:65]
	ds_read_b128 v[216:219], v210 offset:20480
	v_mfma_f32_32x32x16_bf16 v[34:49], v[236:239], v[248:251], v[34:49]
	ds_read_b128 v[228:231], v214 offset:28672
	s_waitcnt lgkmcnt(4)
	v_mfma_f32_32x32x16_bf16 v[18:33], v[240:243], v[244:247], v[18:33]
	ds_read_b128 v[224:227], v214 offset:32768
	v_mfma_f32_32x32x16_bf16 v[2:17], v[236:239], v[244:247], v[2:17]
	s_waitcnt lgkmcnt(1)
	v_mfma_f32_32x32x16_bf16 v[82:97], v[220:223], v[232:235], v[82:97]
	ds_read_b128 v[240:243], v209 offset:16384
	v_mfma_f32_32x32x16_bf16 v[66:81], v[216:219], v[232:235], v[66:81]
	ds_read_b128 v[252:255], v213 offset:24576
	v_mfma_f32_32x32x16_bf16 v[50:65], v[220:223], v[228:231], v[50:65]
	ds_read_b128 v[236:239], v209 offset:20480
	v_mfma_f32_32x32x16_bf16 v[34:49], v[216:219], v[228:231], v[34:49]
	ds_read_b128 v[248:251], v213 offset:28672
	s_waitcnt lgkmcnt(4)
	v_mfma_f32_32x32x16_bf16 v[18:33], v[220:223], v[224:227], v[18:33]
	ds_read_b128 v[244:247], v213 offset:32768
	v_mfma_f32_32x32x16_bf16 v[2:17], v[216:219], v[224:227], v[2:17]
	s_waitcnt lgkmcnt(1)
	v_mfma_f32_32x32x16_bf16 v[82:97], v[240:243], v[252:255], v[82:97]
	ds_read_b128 v[220:223], v208 offset:16384
	s_add_u32 s83, s79, s78
	s_add_u32 s83, s83, 3
	s_and_b32 s83, s83, 15
	v_mfma_f32_32x32x16_bf16 v[66:81], v[236:239], v[252:255], v[66:81]
	ds_read_b128 v[232:235], v212 offset:24576
	s_lshl_b32 s83, s83, 7
	s_add_u32 s70, s66, s83
	v_mfma_f32_32x32x16_bf16 v[50:65], v[240:243], v[248:251], v[50:65]
	ds_read_b128 v[216:219], v208 offset:20480
	s_addc_u32 s71, s67, 0
	s_add_u32 s72, s68, s83
	v_mfma_f32_32x32x16_bf16 v[34:49], v[236:239], v[248:251], v[34:49]
	ds_read_b128 v[228:231], v212 offset:28672
	s_addc_u32 s73, s69, 0
	s_add_u32 s81, s80, 0x6000
	s_add_u32 s82, s80, 0x10000
	s_waitcnt lgkmcnt(4)
	v_mfma_f32_32x32x16_bf16 v[18:33], v[240:243], v[244:247], v[18:33]
	ds_read_b128 v[224:227], v212 offset:32768
	v_mfma_f32_32x32x16_bf16 v[2:17], v[236:239], v[244:247], v[2:17]
	s_waitcnt vmcnt(0) lgkmcnt(0)
	s_barrier
	v_mfma_f32_32x32x16_bf16 v[82:97], v[220:223], v[232:235], v[82:97]
	s_add_u32 m0, s81, 0x0
	ds_read_b128 v[240:243], v211 offset:0
	global_load_lds_dwordx4 v207, s[70:71]
	s_add_u32 m0, s81, 0x1000
	s_nop 0
	global_load_lds_dwordx4 v206, s[70:71]
	v_mfma_f32_32x32x16_bf16 v[66:81], v[216:219], v[232:235], v[66:81]
	s_add_u32 m0, s81, 0x2000
	ds_read_b128 v[252:255], v215 offset:0
	global_load_lds_dwordx4 v205, s[70:71]
	s_add_u32 m0, s81, 0x3000
	s_nop 0
	global_load_lds_dwordx4 v204, s[70:71]
	v_mfma_f32_32x32x16_bf16 v[50:65], v[220:223], v[228:231], v[50:65]
	s_add_u32 m0, s81, 0x4000
	ds_read_b128 v[236:239], v211 offset:4096
	global_load_lds_dwordx4 v203, s[70:71]
	s_add_u32 m0, s81, 0x5000
	s_nop 0
	global_load_lds_dwordx4 v202, s[70:71]
	v_mfma_f32_32x32x16_bf16 v[34:49], v[216:219], v[228:231], v[34:49]
	s_add_u32 m0, s82, 0x0
	ds_read_b128 v[248:251], v215 offset:4096
	global_load_lds_dwordx4 v207, s[72:73]
	s_add_u32 m0, s82, 0x1000
	s_nop 0
	global_load_lds_dwordx4 v206, s[72:73]
	v_mfma_f32_32x32x16_bf16 v[18:33], v[220:223], v[224:227], v[18:33]
	s_add_u32 m0, s82, 0x2000
	ds_read_b128 v[244:247], v215 offset:8192
	global_load_lds_dwordx4 v205, s[72:73]
	s_add_u32 m0, s82, 0x3000
	s_nop 0
	global_load_lds_dwordx4 v204, s[72:73]
	v_mfma_f32_32x32x16_bf16 v[2:17], v[216:219], v[224:227], v[2:17]
	s_add_u32 s78, s78, 2
	s_cmp_lt_u32 s78, 14
	s_cbranch_scc1 .Lgm_ph13_loop
	s_waitcnt lgkmcnt(1)
	v_mfma_f32_32x32x16_bf16 v[82:97], v[240:243], v[252:255], v[82:97]
	ds_read_b128 v[220:223], v210 offset:0
	v_mfma_f32_32x32x16_bf16 v[66:81], v[236:239], v[252:255], v[66:81]
	ds_read_b128 v[232:235], v214 offset:0
	v_mfma_f32_32x32x16_bf16 v[50:65], v[240:243], v[248:251], v[50:65]
	ds_read_b128 v[216:219], v210 offset:4096
	v_mfma_f32_32x32x16_bf16 v[34:49], v[236:239], v[248:251], v[34:49]
	ds_read_b128 v[228:231], v214 offset:4096
	s_waitcnt lgkmcnt(4)
	v_mfma_f32_32x32x16_bf16 v[18:33], v[240:243], v[244:247], v[18:33]
	ds_read_b128 v[224:227], v214 offset:8192
	v_mfma_f32_32x32x16_bf16 v[2:17], v[236:239], v[244:247], v[2:17]
	s_waitcnt lgkmcnt(1)
	v_mfma_f32_32x32x16_bf16 v[82:97], v[220:223], v[232:235], v[82:97]
	ds_read_b128 v[240:243], v209 offset:0
	v_mfma_f32_32x32x16_bf16 v[66:81], v[216:219], v[232:235], v[66:81]
	ds_read_b128 v[252:255], v213 offset:0
	v_mfma_f32_32x32x16_bf16 v[50:65], v[220:223], v[228:231], v[50:65]
	ds_read_b128 v[236:239], v209 offset:4096
	v_mfma_f32_32x32x16_bf16 v[34:49], v[216:219], v[228:231], v[34:49]
	ds_read_b128 v[248:251], v213 offset:4096
	s_waitcnt lgkmcnt(4)
	v_mfma_f32_32x32x16_bf16 v[18:33], v[220:223], v[224:227], v[18:33]
	ds_read_b128 v[244:247], v213 offset:8192
	v_mfma_f32_32x32x16_bf16 v[2:17], v[216:219], v[224:227], v[2:17]
	s_waitcnt lgkmcnt(1)
	v_mfma_f32_32x32x16_bf16 v[82:97], v[240:243], v[252:255], v[82:97]
	ds_read_b128 v[220:223], v208 offset:0
	v_mfma_f32_32x32x16_bf16 v[66:81], v[236:239], v[252:255], v[66:81]
	ds_read_b128 v[232:235], v212 offset:0
	v_mfma_f32_32x32x16_bf16 v[50:65], v[240:243], v[248:251], v[50:65]
	ds_read_b128 v[216:219], v208 offset:4096
	v_mfma_f32_32x32x16_bf16 v[34:49], v[236:239], v[248:251], v[34:49]
	ds_read_b128 v[228:231], v212 offset:4096
	s_waitcnt lgkmcnt(4)
	v_mfma_f32_32x32x16_bf16 v[18:33], v[240:243], v[244:247], v[18:33]
	ds_read_b128 v[224:227], v212 offset:8192
	v_mfma_f32_32x32x16_bf16 v[2:17], v[236:239], v[244:247], v[2:17]
	s_waitcnt vmcnt(0) lgkmcnt(0)
	s_barrier
	v_mfma_f32_32x32x16_bf16 v[82:97], v[220:223], v[232:235], v[82:97]
	ds_read_b128 v[240:243], v211 offset:16384
	v_mfma_f32_32x32x16_bf16 v[66:81], v[216:219], v[232:235], v[66:81]
	ds_read_b128 v[252:255], v215 offset:24576
	v_mfma_f32_32x32x16_bf16 v[50:65], v[220:223], v[228:231], v[50:65]
	ds_read_b128 v[236:239], v211 offset:20480
	v_mfma_f32_32x32x16_bf16 v[34:49], v[216:219], v[228:231], v[34:49]
	ds_read_b128 v[248:251], v215 offset:28672
	v_mfma_f32_32x32x16_bf16 v[18:33], v[220:223], v[224:227], v[18:33]
	ds_read_b128 v[244:247], v215 offset:32768
	v_mfma_f32_32x32x16_bf16 v[2:17], v[216:219], v[224:227], v[2:17]
	s_waitcnt lgkmcnt(1)
	v_mfma_f32_32x32x16_bf16 v[82:97], v[240:243], v[252:255], v[82:97]
	ds_read_b128 v[220:223], v210 offset:16384
	v_mfma_f32_32x32x16_bf16 v[66:81], v[236:239], v[252:255], v[66:81]
	ds_read_b128 v[232:235], v214 offset:24576
	v_mfma_f32_32x32x16_bf16 v[50:65], v[240:243], v[248:251], v[50:65]
	ds_read_b128 v[216:219], v210 offset:20480
	v_mfma_f32_32x32x16_bf16 v[34:49], v[236:239], v[248:251], v[34:49]
	ds_read_b128 v[228:231], v214 offset:28672
	s_waitcnt lgkmcnt(4)
	v_mfma_f32_32x32x16_bf16 v[18:33], v[240:243], v[244:247], v[18:33]
	ds_read_b128 v[224:227], v214 offset:32768
	v_mfma_f32_32x32x16_bf16 v[2:17], v[236:239], v[244:247], v[2:17]
	s_waitcnt lgkmcnt(1)
	v_mfma_f32_32x32x16_bf16 v[82:97], v[220:223], v[232:235], v[82:97]
	ds_read_b128 v[240:243], v209 offset:16384
	v_mfma_f32_32x32x16_bf16 v[66:81], v[216:219], v[232:235], v[66:81]
	ds_read_b128 v[252:255], v213 offset:24576
	v_mfma_f32_32x32x16_bf16 v[50:65], v[220:223], v[228:231], v[50:65]
	ds_read_b128 v[236:239], v209 offset:20480
	v_mfma_f32_32x32x16_bf16 v[34:49], v[216:219], v[228:231], v[34:49]
	ds_read_b128 v[248:251], v213 offset:28672
	s_waitcnt lgkmcnt(4)
	v_mfma_f32_32x32x16_bf16 v[18:33], v[220:223], v[224:227], v[18:33]
	ds_read_b128 v[244:247], v213 offset:32768
	v_mfma_f32_32x32x16_bf16 v[2:17], v[216:219], v[224:227], v[2:17]
	s_waitcnt lgkmcnt(1)
	v_mfma_f32_32x32x16_bf16 v[82:97], v[240:243], v[252:255], v[82:97]
	ds_read_b128 v[220:223], v208 offset:16384
	v_mfma_f32_32x32x16_bf16 v[66:81], v[236:239], v[252:255], v[66:81]
	ds_read_b128 v[232:235], v212 offset:24576
	v_mfma_f32_32x32x16_bf16 v[50:65], v[240:243], v[248:251], v[50:65]
	ds_read_b128 v[216:219], v208 offset:20480
	v_mfma_f32_32x32x16_bf16 v[34:49], v[236:239], v[248:251], v[34:49]
	ds_read_b128 v[228:231], v212 offset:28672
	s_waitcnt lgkmcnt(4)
	v_mfma_f32_32x32x16_bf16 v[18:33], v[240:243], v[244:247], v[18:33]
	ds_read_b128 v[224:227], v212 offset:32768
	v_mfma_f32_32x32x16_bf16 v[2:17], v[236:239], v[244:247], v[2:17]
	s_waitcnt vmcnt(0) lgkmcnt(0)
	s_barrier
	v_mfma_f32_32x32x16_bf16 v[82:97], v[220:223], v[232:235], v[82:97]
	v_mfma_f32_32x32x16_bf16 v[66:81], v[216:219], v[232:235], v[66:81]
	v_mfma_f32_32x32x16_bf16 v[50:65], v[220:223], v[228:231], v[50:65]
	v_mfma_f32_32x32x16_bf16 v[34:49], v[216:219], v[228:231], v[34:49]
	v_mfma_f32_32x32x16_bf16 v[18:33], v[220:223], v[224:227], v[18:33]
	v_mfma_f32_32x32x16_bf16 v[2:17], v[216:219], v[224:227], v[2:17]
	s_nop 7
	s_nop 7
	s_and_b32 s5, s5, 0x1fffff8
	s_nop 4
	s_cmp_eq_u32 s5, 16
	s_nop 4
	s_cselect_b64 s[50:51], -1, 0
	s_nop 4
	s_cmpk_gt_u32 s4, 0x7ff
	s_nop 4
	s_cselect_b64 s[48:49], -1, 0
	s_nop 4
	s_cmpk_gt_u32 s4, 0xbff
	s_nop 4
	s_cselect_b64 s[46:47], -1, 0
	s_nop 4
	s_mov_b64 s[52:53], -1
	s_nop 4
	s_and_b64 vcc, exec, s[50:51]
	s_nop 4
	v_add_u32_e32 v109, s6, v119
	s_nop 4
	v_or_b32_e32 v100, s4, v127
	s_waitcnt lgkmcnt(0)
	s_nop 11
	ds_write_b128 v140, v[82:85]
	ds_write_b128 v140, v[86:89] offset:32
	ds_write_b128 v140, v[90:93] offset:64
	ds_write_b128 v140, v[94:97] offset:96
	s_nop 11
	ds_write_b128 v140, v[66:69] offset:128
	ds_write_b128 v140, v[70:73] offset:160
	ds_write_b128 v140, v[74:77] offset:192
	ds_write_b128 v140, v[78:81] offset:224
	s_waitcnt lgkmcnt(0)
	v_add_u32_e32 v112, v128, v100
	v_or_b32_e32 v100, v100, v131
	v_cmp_lt_i32_e64 s[6:7], s3, v100
	s_cbranch_vccz .LBB0_1278
	v_mov_b32_e32 v80, 0x880
	v_cmp_gt_i32_e64 s[52:53], s57, v109
	v_mov_b32_e32 v81, 0x990
	v_mov_b32_e32 v79, 0xaa0
	v_mov_b32_e32 v78, 0xbb0
	ds_read2_b32 v[70:71], v129 offset1:68
	ds_read2_b32 v[72:73], v129 offset0:136 offset1:204
	v_cndmask_b32_e64 v82, v141, v80, s[52:53]
	v_cndmask_b32_e64 v83, v142, v81, s[52:53]
	v_cndmask_b32_e64 v84, v143, v79, s[52:53]
	v_cndmask_b32_e64 v85, v144, v78, s[52:53]
	v_add_u32_e32 v66, 0xfffff000, v109
	v_ashrrev_i32_e32 v68, 8, v109
	v_add_u32_e32 v82, v129, v82
	v_add_u32_e32 v83, v129, v83
	v_add_u32_e32 v84, v129, v84
	v_add_u32_e32 v85, v129, v85
	v_lshrrev_b32_e32 v66, 11, v66
	v_and_b32_e32 v67, 0x7e0, v109
	v_ashrrev_i32_e32 v69, 31, v68
	ds_read_b32 v82, v82
	ds_read_b32 v83, v83
	ds_read_b32 v84, v84
	ds_read_b32 v85, v85
	v_add_u32_e32 v76, 0x100, v67
	v_mad_u64_u32 v[66:67], s[4:5], v66, s59, v[110:111]
	v_lshlrev_b64 v[68:69], 18, v[68:69]
	v_and_b32_e32 v77, 0xe0, v109
	v_cndmask_b32_e64 v75, v67, v69, s[52:53]
	v_cndmask_b32_e64 v74, v66, v68, s[52:53]
	v_cndmask_b32_e64 v86, v145, v147, s[52:53]
	v_cndmask_b32_e64 v87, v76, v77, s[52:53]
	s_waitcnt lgkmcnt(0)
	v_cvt_pk_bf16_f32 v70, v70, v71
	v_cvt_pk_bf16_f32 v71, v72, v73
	v_cvt_pk_bf16_f32 v72, v82, v83
	v_lshl_add_u64 v[74:75], v[74:75], 1, s[24:25]
	v_mad_u64_u32 v[82:83], s[4:5], v86, v112, 0
	v_lshl_add_u64 v[74:75], v[82:83], 1, v[74:75]
	v_lshlrev_b32_e32 v82, 1, v87
	v_mov_b32_e32 v83, v101
	v_cvt_pk_bf16_f32 v73, v84, v85
	v_lshl_add_u64 v[74:75], v[74:75], 0, v[82:83]
	global_store_dwordx4 v[74:75], v[70:73], off
	v_mov_b32_e32 v84, 0x1540
	v_mov_b32_e32 v83, 0x1650
	v_mov_b64_e32 v[70:71], 0x900
	v_mov_b64_e32 v[72:73], 0x900
	v_mov_b32_e32 v82, 0x1760
	v_mov_b32_e32 v71, 0x1870
	v_mov_b64_e32 v[74:75], v[66:67]
	v_mov_b32_e32 v73, v76
	s_and_saveexec_b64 s[4:5], s[52:53]
	s_cbranch_execz .LBB0_1275
	v_mov_b64_e32 v[72:73], 0x100
	v_mov_b32_e32 v78, 0x770
	v_mov_b32_e32 v79, 0x660
	v_mov_b32_e32 v81, 0x550
	v_mov_b32_e32 v80, 0x440
	v_mov_b32_e32 v84, 0x1980
	v_mov_b32_e32 v83, 0x1a90
	v_mov_b32_e32 v82, 0x1ba0
	v_mov_b32_e32 v71, 0x1cb0
	v_mov_b64_e32 v[74:75], v[68:69]
	v_mov_b32_e32 v73, v77

.LBB0_1859:
	s_ashr_i32 s10, s28, 31
	s_lshr_b32 s10, s10, 26
	s_add_i32 s10, s28, s10
	s_ashr_i32 s31, s10, 6
	s_and_b32 s10, s10, 0x3ffffc0
	s_sub_i32 s29, s28, s10
	s_mulk_i32 s29, 0xc0
	v_add_u32_e32 v2, s29, v108
	s_lshr_b32 s10, s29, 6
	s_lshl_b32 s30, s31, 7
	v_ashrrev_i32_e32 v3, 31, v2
	s_add_i32 s10, s10, s31
	v_lshlrev_b64 v[2:3], 11, v[2:3]
	v_or_b32_e32 v4, s30, v108
	s_lshl_b32 s31, s10, 6
	s_lshl_b32 s10, s10, 7
	v_ashrrev_i32_e32 v5, 31, v4
	v_lshl_add_u64 v[104:105], v[100:101], 0, v[2:3]
	s_and_b32 s10, s10, 0x780
	v_readfirstlane_b32 s34, v109
	v_lshlrev_b64 v[4:5], 11, v[4:5]
	v_lshl_add_u64 v[2:3], v[104:105], 0, s[10:11]
	s_mov_b32 m0, s34
	v_readfirstlane_b32 s34, v128
	v_lshl_add_u64 v[106:107], v[102:103], 0, v[4:5]
	s_waitcnt vmcnt(0)
	s_barrier
	s_load_dwordx2 s[66:67], s[0:1], 0x178
	s_load_dwordx2 s[68:69], s[0:1], 0x100
	v_and_b32_e32 v201, 0x3ff, v0
	v_readfirstlane_b32 s80, v0
	v_and_b32_e32 v200, 31, v201
	v_bfe_u32 v214, v201, 1, 3
	v_bfe_u32 v213, v201, 5, 1
	v_xor_b32_e32 v214, v214, v213
	v_lshlrev_b32_e32 v214, 4, v214
	s_and_b32 s80, s80, 0x3ff
	s_lshr_b32 s83, s80, 6
	s_lshl_b32 s80, s80, 4
	s_lshr_b32 s84, s83, 1
	s_and_b32 s83, s83, 1
	s_mul_i32 s84, s84, 0x3000
	s_lshl_b32 s83, s83, 13
	s_add_u32 s83, s83, 0xc000
	v_lshlrev_b32_e32 v200, 7, v200
	v_or_b32_e32 v200, v200, v214
	v_add_u32_e32 v215, s84, v200
	v_add_u32_e32 v211, s83, v200
	v_xor_b32_e32 v214, 0x20, v215
	v_xor_b32_e32 v210, 0x20, v211
	v_xor_b32_e32 v213, 0x40, v215
	v_xor_b32_e32 v209, 0x40, v211
	v_xor_b32_e32 v212, 0x60, v215
	v_xor_b32_e32 v208, 0x60, v211
	v_bfe_u32 v200, v201, 4, 3
	v_and_b32_e32 v206, 7, v201
	v_xor_b32_e32 v200, v200, v206
	v_lshlrev_b32_e32 v200, 4, v200
	v_lshrrev_b32_e32 v206, 3, v201
	v_lshl_or_b32 v207, v206, 11, v200
	v_add_u32_e32 v206, 0x10000, v207
	v_add_u32_e32 v205, 0x20000, v207
	v_add_u32_e32 v204, 0x30000, v207
	v_add_u32_e32 v203, 0x40000, v207
	v_add_u32_e32 v202, 0x50000, v207
	s_lshr_b32 s83, s28, 6
	s_and_b32 s84, s28, 63
	s_mov_b32 s79, 0
	s_mul_i32 s84, s84, 0x60000
	s_lshl_b32 s83, s83, 18
	s_waitcnt lgkmcnt(0)
	s_add_u32 s66, s66, s84
	s_addc_u32 s67, s67, 0
	s_add_u32 s68, s68, s83
	s_addc_u32 s69, s69, 0
	s_add_u32 s83, s79, 0
	s_and_b32 s83, s83, 15
	s_lshl_b32 s83, s83, 7
	s_add_u32 s70, s66, s83
	s_addc_u32 s71, s67, 0
	s_add_u32 s72, s68, s83
	s_addc_u32 s73, s69, 0
	s_add_u32 s81, s80, 0x0
	s_add_u32 s82, s80, 0xc000
	s_add_u32 m0, s81, 0x0
	s_nop 0
	global_load_lds_dwordx4 v207, s[70:71]
	s_add_u32 m0, s81, 0x1000
	s_nop 0
	global_load_lds_dwordx4 v206, s[70:71]
	s_add_u32 m0, s81, 0x2000
	s_nop 0
	global_load_lds_dwordx4 v205, s[70:71]
	s_add_u32 m0, s81, 0x3000
	s_nop 0
	global_load_lds_dwordx4 v204, s[70:71]
	s_add_u32 m0, s81, 0x4000
	s_nop 0
	global_load_lds_dwordx4 v203, s[70:71]
	s_add_u32 m0, s81, 0x5000
	s_nop 0
	global_load_lds_dwordx4 v202, s[70:71]
	s_add_u32 m0, s82, 0x0
	s_nop 0
	global_load_lds_dwordx4 v207, s[72:73]
	s_add_u32 m0, s82, 0x1000
	s_nop 0
	global_load_lds_dwordx4 v206, s[72:73]
	s_add_u32 m0, s82, 0x2000
	s_nop 0
	global_load_lds_dwordx4 v205, s[72:73]
	s_add_u32 m0, s82, 0x3000
	s_nop 0
	global_load_lds_dwordx4 v204, s[72:73]
	s_add_u32 s83, s79, 1
	s_and_b32 s83, s83, 15
	s_lshl_b32 s83, s83, 7
	s_add_u32 s70, s66, s83
	s_addc_u32 s71, s67, 0
	s_add_u32 s72, s68, s83
	s_addc_u32 s73, s69, 0
	s_add_u32 s81, s80, 0x6000
	s_add_u32 s82, s80, 0x10000
	s_add_u32 m0, s81, 0x0
	s_nop 0
	global_load_lds_dwordx4 v207, s[70:71]
	s_add_u32 m0, s81, 0x1000
	s_nop 0
	global_load_lds_dwordx4 v206, s[70:71]
	s_add_u32 m0, s81, 0x2000
	s_nop 0
	global_load_lds_dwordx4 v205, s[70:71]
	s_add_u32 m0, s81, 0x3000
	s_nop 0
	global_load_lds_dwordx4 v204, s[70:71]
	s_add_u32 m0, s81, 0x4000
	s_nop 0
	global_load_lds_dwordx4 v203, s[70:71]
	s_add_u32 m0, s81, 0x5000
	s_nop 0
	global_load_lds_dwordx4 v202, s[70:71]
	s_add_u32 m0, s82, 0x0
	s_nop 0
	global_load_lds_dwordx4 v207, s[72:73]
	s_add_u32 m0, s82, 0x1000
	s_nop 0
	global_load_lds_dwordx4 v206, s[72:73]
	s_add_u32 m0, s82, 0x2000
	s_nop 0
	global_load_lds_dwordx4 v205, s[72:73]
	s_add_u32 m0, s82, 0x3000
	s_nop 0
	global_load_lds_dwordx4 v204, s[72:73]
	v_mov_b32_e32 v2, 0
	v_mov_b32_e32 v3, 0
	v_mov_b32_e32 v4, 0
	v_mov_b32_e32 v5, 0
	v_mov_b32_e32 v6, 0
	v_mov_b32_e32 v7, 0
	v_mov_b32_e32 v8, 0
	v_mov_b32_e32 v9, 0
	v_mov_b32_e32 v10, 0
	v_mov_b32_e32 v11, 0
	v_mov_b32_e32 v12, 0
	v_mov_b32_e32 v13, 0
	v_mov_b32_e32 v14, 0
	v_mov_b32_e32 v15, 0
	v_mov_b32_e32 v16, 0
	v_mov_b32_e32 v17, 0
	v_mov_b32_e32 v18, 0
	v_mov_b32_e32 v19, 0
	v_mov_b32_e32 v20, 0
	v_mov_b32_e32 v21, 0
	v_mov_b32_e32 v22, 0
	v_mov_b32_e32 v23, 0
	v_mov_b32_e32 v24, 0
	v_mov_b32_e32 v25, 0
	v_mov_b32_e32 v26, 0
	v_mov_b32_e32 v27, 0
	v_mov_b32_e32 v28, 0
	v_mov_b32_e32 v29, 0
	v_mov_b32_e32 v30, 0
	v_mov_b32_e32 v31, 0
	v_mov_b32_e32 v32, 0
	v_mov_b32_e32 v33, 0
	v_mov_b32_e32 v34, 0
	v_mov_b32_e32 v35, 0
	v_mov_b32_e32 v36, 0
	v_mov_b32_e32 v37, 0
	v_mov_b32_e32 v38, 0
	v_mov_b32_e32 v39, 0
	v_mov_b32_e32 v40, 0
	v_mov_b32_e32 v41, 0
	v_mov_b32_e32 v42, 0
	v_mov_b32_e32 v43, 0
	v_mov_b32_e32 v44, 0
	v_mov_b32_e32 v45, 0
	v_mov_b32_e32 v46, 0
	v_mov_b32_e32 v47, 0
	v_mov_b32_e32 v48, 0
	v_mov_b32_e32 v49, 0
	v_mov_b32_e32 v50, 0
	v_mov_b32_e32 v51, 0
	v_mov_b32_e32 v52, 0
	v_mov_b32_e32 v53, 0
	v_mov_b32_e32 v54, 0
	v_mov_b32_e32 v55, 0
	v_mov_b32_e32 v56, 0
	v_mov_b32_e32 v57, 0
	v_mov_b32_e32 v58, 0
	v_mov_b32_e32 v59, 0
	v_mov_b32_e32 v60, 0
	v_mov_b32_e32 v61, 0
	v_mov_b32_e32 v62, 0
	v_mov_b32_e32 v63, 0
	v_mov_b32_e32 v64, 0
	v_mov_b32_e32 v65, 0
	v_mov_b32_e32 v66, 0
	v_mov_b32_e32 v67, 0
	v_mov_b32_e32 v68, 0
	v_mov_b32_e32 v69, 0
	v_mov_b32_e32 v70, 0
	v_mov_b32_e32 v71, 0
	v_mov_b32_e32 v72, 0
	v_mov_b32_e32 v73, 0
	v_mov_b32_e32 v74, 0
	v_mov_b32_e32 v75, 0
	v_mov_b32_e32 v76, 0
	v_mov_b32_e32 v77, 0
	v_mov_b32_e32 v78, 0
	v_mov_b32_e32 v79, 0
	v_mov_b32_e32 v80, 0
	v_mov_b32_e32 v81, 0
	v_mov_b32_e32 v82, 0
	v_mov_b32_e32 v83, 0
	v_mov_b32_e32 v84, 0
	v_mov_b32_e32 v85, 0
	v_mov_b32_e32 v86, 0
	v_mov_b32_e32 v87, 0
	v_mov_b32_e32 v88, 0
	v_mov_b32_e32 v89, 0
	v_mov_b32_e32 v90, 0
	v_mov_b32_e32 v91, 0
	v_mov_b32_e32 v92, 0
	v_mov_b32_e32 v93, 0
	v_mov_b32_e32 v94, 0
	v_mov_b32_e32 v95, 0
	v_mov_b32_e32 v96, 0
	v_mov_b32_e32 v97, 0
	s_waitcnt vmcnt(10)
	s_barrier
	ds_read_b128 v[240:243], v211 offset:0
	ds_read_b128 v[252:255], v215 offset:0
	ds_read_b128 v[236:239], v211 offset:4096
	ds_read_b128 v[248:251], v215 offset:4096
	ds_read_b128 v[244:247], v215 offset:8192
	s_mov_b32 s78, 0

.LBB0_1992:
	s_ashr_i32 s4, s35, 31
	s_lshr_b32 s4, s4, 26
	s_add_i32 s4, s35, s4
	s_ashr_i32 s6, s4, 6
	s_and_b32 s4, s4, 0x3ffffc0
	s_sub_i32 s4, s35, s4
	s_mulk_i32 s4, 0xc0
	v_add_u32_e32 v2, s4, v112
	s_lshr_b32 s7, s4, 6
	s_lshl_b32 s5, s6, 7
	v_ashrrev_i32_e32 v3, 31, v2
	s_add_i32 s7, s7, s6
	v_lshlrev_b64 v[2:3], 11, v[2:3]
	v_or_b32_e32 v4, s5, v112
	s_lshl_b32 s6, s7, 6
	s_lshl_b32 s7, s7, 7
	v_ashrrev_i32_e32 v5, 31, v4
	v_lshl_add_u64 v[104:105], v[100:101], 0, v[2:3]
	s_and_b32 s14, s7, 0x780
	v_readfirstlane_b32 s7, v113
	v_lshlrev_b64 v[4:5], 11, v[4:5]
	v_lshl_add_u64 v[2:3], v[104:105], 0, s[14:15]
	s_mov_b32 m0, s7
	v_readfirstlane_b32 s7, v125
	v_lshl_add_u64 v[106:107], v[102:103], 0, v[4:5]
	s_waitcnt vmcnt(0)
	s_barrier
	s_load_dwordx2 s[66:67], s[0:1], 0x90
	s_load_dwordx2 s[68:69], s[0:1], 0xc0
	v_and_b32_e32 v201, 0x3ff, v0
	v_readfirstlane_b32 s80, v0
	v_and_b32_e32 v200, 31, v201
	v_bfe_u32 v214, v201, 1, 3
	v_bfe_u32 v213, v201, 5, 1
	v_xor_b32_e32 v214, v214, v213
	v_lshlrev_b32_e32 v214, 4, v214
	s_and_b32 s80, s80, 0x3ff
	s_lshr_b32 s83, s80, 6
	s_lshl_b32 s80, s80, 4
	s_lshr_b32 s84, s83, 1
	s_and_b32 s83, s83, 1
	s_mul_i32 s84, s84, 0x3000
	s_lshl_b32 s83, s83, 13
	s_add_u32 s83, s83, 0xc000
	v_lshlrev_b32_e32 v200, 7, v200
	v_or_b32_e32 v200, v200, v214
	v_add_u32_e32 v215, s84, v200
	v_add_u32_e32 v211, s83, v200
	v_xor_b32_e32 v214, 0x20, v215
	v_xor_b32_e32 v210, 0x20, v211
	v_xor_b32_e32 v213, 0x40, v215
	v_xor_b32_e32 v209, 0x40, v211
	v_xor_b32_e32 v212, 0x60, v215
	v_xor_b32_e32 v208, 0x60, v211
	v_bfe_u32 v200, v201, 4, 3
	v_and_b32_e32 v206, 7, v201
	v_xor_b32_e32 v200, v200, v206
	v_lshlrev_b32_e32 v200, 4, v200
	v_lshrrev_b32_e32 v206, 3, v201
	v_lshl_or_b32 v207, v206, 11, v200
	v_add_u32_e32 v206, 0x10000, v207
	v_add_u32_e32 v205, 0x20000, v207
	v_add_u32_e32 v204, 0x30000, v207
	v_add_u32_e32 v203, 0x40000, v207
	v_add_u32_e32 v202, 0x50000, v207
	s_lshr_b32 s83, s35, 6
	s_and_b32 s84, s35, 63
	s_mov_b32 s79, 0
	s_mul_i32 s84, s84, 0x60000
	s_lshl_b32 s83, s83, 18
	s_add_u32 s83, s83, 0x400000
	s_waitcnt lgkmcnt(0)
	s_add_u32 s66, s66, s84
	s_addc_u32 s67, s67, 0
	s_add_u32 s68, s68, s83
	s_addc_u32 s69, s69, 0
	s_add_u32 s83, s79, 0
	s_and_b32 s83, s83, 15
	s_lshl_b32 s83, s83, 7
	s_add_u32 s70, s66, s83
	s_addc_u32 s71, s67, 0
	s_add_u32 s72, s68, s83
	s_addc_u32 s73, s69, 0
	s_add_u32 s81, s80, 0x0
	s_add_u32 s82, s80, 0xc000
	s_add_u32 m0, s81, 0x0
	s_nop 0
	global_load_lds_dwordx4 v207, s[70:71]
	s_add_u32 m0, s81, 0x1000
	s_nop 0
	global_load_lds_dwordx4 v206, s[70:71]
	s_add_u32 m0, s81, 0x2000
	s_nop 0
	global_load_lds_dwordx4 v205, s[70:71]
	s_add_u32 m0, s81, 0x3000
	s_nop 0
	global_load_lds_dwordx4 v204, s[70:71]
	s_add_u32 m0, s81, 0x4000
	s_nop 0
	global_load_lds_dwordx4 v203, s[70:71]
	s_add_u32 m0, s81, 0x5000
	s_nop 0
	global_load_lds_dwordx4 v202, s[70:71]
	s_add_u32 m0, s82, 0x0
	s_nop 0
	global_load_lds_dwordx4 v207, s[72:73]
	s_add_u32 m0, s82, 0x1000
	s_nop 0
	global_load_lds_dwordx4 v206, s[72:73]
	s_add_u32 m0, s82, 0x2000
	s_nop 0
	global_load_lds_dwordx4 v205, s[72:73]
	s_add_u32 m0, s82, 0x3000
	s_nop 0
	global_load_lds_dwordx4 v204, s[72:73]
	s_add_u32 s83, s79, 1
	s_and_b32 s83, s83, 15
	s_lshl_b32 s83, s83, 7
	s_add_u32 s70, s66, s83
	s_addc_u32 s71, s67, 0
	s_add_u32 s72, s68, s83
	s_addc_u32 s73, s69, 0
	s_add_u32 s81, s80, 0x6000
	s_add_u32 s82, s80, 0x10000
	s_add_u32 m0, s81, 0x0
	s_nop 0
	global_load_lds_dwordx4 v207, s[70:71]
	s_add_u32 m0, s81, 0x1000
	s_nop 0
	global_load_lds_dwordx4 v206, s[70:71]
	s_add_u32 m0, s81, 0x2000
	s_nop 0
	global_load_lds_dwordx4 v205, s[70:71]
	s_add_u32 m0, s81, 0x3000
	s_nop 0
	global_load_lds_dwordx4 v204, s[70:71]
	s_add_u32 m0, s81, 0x4000
	s_nop 0
	global_load_lds_dwordx4 v203, s[70:71]
	s_add_u32 m0, s81, 0x5000
	s_nop 0
	global_load_lds_dwordx4 v202, s[70:71]
	s_add_u32 m0, s82, 0x0
	s_nop 0
	global_load_lds_dwordx4 v207, s[72:73]
	s_add_u32 m0, s82, 0x1000
	s_nop 0
	global_load_lds_dwordx4 v206, s[72:73]
	s_add_u32 m0, s82, 0x2000
	s_nop 0
	global_load_lds_dwordx4 v205, s[72:73]
	s_add_u32 m0, s82, 0x3000
	s_nop 0
	global_load_lds_dwordx4 v204, s[72:73]
	v_mov_b32_e32 v2, 0
	v_mov_b32_e32 v3, 0
	v_mov_b32_e32 v4, 0
	v_mov_b32_e32 v5, 0
	v_mov_b32_e32 v6, 0
	v_mov_b32_e32 v7, 0
	v_mov_b32_e32 v8, 0
	v_mov_b32_e32 v9, 0
	v_mov_b32_e32 v10, 0
	v_mov_b32_e32 v11, 0
	v_mov_b32_e32 v12, 0
	v_mov_b32_e32 v13, 0
	v_mov_b32_e32 v14, 0
	v_mov_b32_e32 v15, 0
	v_mov_b32_e32 v16, 0
	v_mov_b32_e32 v17, 0
	v_mov_b32_e32 v18, 0
	v_mov_b32_e32 v19, 0
	v_mov_b32_e32 v20, 0
	v_mov_b32_e32 v21, 0
	v_mov_b32_e32 v22, 0
	v_mov_b32_e32 v23, 0
	v_mov_b32_e32 v24, 0
	v_mov_b32_e32 v25, 0
	v_mov_b32_e32 v26, 0
	v_mov_b32_e32 v27, 0
	v_mov_b32_e32 v28, 0
	v_mov_b32_e32 v29, 0
	v_mov_b32_e32 v30, 0
	v_mov_b32_e32 v31, 0
	v_mov_b32_e32 v32, 0
	v_mov_b32_e32 v33, 0
	v_mov_b32_e32 v34, 0
	v_mov_b32_e32 v35, 0
	v_mov_b32_e32 v36, 0
	v_mov_b32_e32 v37, 0
	v_mov_b32_e32 v38, 0
	v_mov_b32_e32 v39, 0
	v_mov_b32_e32 v40, 0
	v_mov_b32_e32 v41, 0
	v_mov_b32_e32 v42, 0
	v_mov_b32_e32 v43, 0
	v_mov_b32_e32 v44, 0
	v_mov_b32_e32 v45, 0
	v_mov_b32_e32 v46, 0
	v_mov_b32_e32 v47, 0
	v_mov_b32_e32 v48, 0
	v_mov_b32_e32 v49, 0
	v_mov_b32_e32 v50, 0
	v_mov_b32_e32 v51, 0
	v_mov_b32_e32 v52, 0
	v_mov_b32_e32 v53, 0
	v_mov_b32_e32 v54, 0
	v_mov_b32_e32 v55, 0
	v_mov_b32_e32 v56, 0
	v_mov_b32_e32 v57, 0
	v_mov_b32_e32 v58, 0
	v_mov_b32_e32 v59, 0
	v_mov_b32_e32 v60, 0
	v_mov_b32_e32 v61, 0
	v_mov_b32_e32 v62, 0
	v_mov_b32_e32 v63, 0
	v_mov_b32_e32 v64, 0
	v_mov_b32_e32 v65, 0
	v_mov_b32_e32 v66, 0
	v_mov_b32_e32 v67, 0
	v_mov_b32_e32 v68, 0
	v_mov_b32_e32 v69, 0
	v_mov_b32_e32 v70, 0
	v_mov_b32_e32 v71, 0
	v_mov_b32_e32 v72, 0
	v_mov_b32_e32 v73, 0
	v_mov_b32_e32 v74, 0
	v_mov_b32_e32 v75, 0
	v_mov_b32_e32 v76, 0
	v_mov_b32_e32 v77, 0
	v_mov_b32_e32 v78, 0
	v_mov_b32_e32 v79, 0
	v_mov_b32_e32 v80, 0
	v_mov_b32_e32 v81, 0
	v_mov_b32_e32 v82, 0
	v_mov_b32_e32 v83, 0
	v_mov_b32_e32 v84, 0
	v_mov_b32_e32 v85, 0
	v_mov_b32_e32 v86, 0
	v_mov_b32_e32 v87, 0
	v_mov_b32_e32 v88, 0
	v_mov_b32_e32 v89, 0
	v_mov_b32_e32 v90, 0
	v_mov_b32_e32 v91, 0
	v_mov_b32_e32 v92, 0
	v_mov_b32_e32 v93, 0
	v_mov_b32_e32 v94, 0
	v_mov_b32_e32 v95, 0
	v_mov_b32_e32 v96, 0
	v_mov_b32_e32 v97, 0
	s_waitcnt vmcnt(10)
	s_barrier
	ds_read_b128 v[240:243], v211 offset:0
	ds_read_b128 v[252:255], v215 offset:0
	ds_read_b128 v[236:239], v211 offset:4096
	ds_read_b128 v[248:251], v215 offset:4096
	ds_read_b128 v[244:247], v215 offset:8192
	s_mov_b32 s78, 0
.Lgm_ph17_loop:
	s_waitcnt lgkmcnt(1)
	v_mfma_f32_32x32x16_bf16 v[82:97], v[240:243], v[252:255], v[82:97]
	ds_read_b128 v[220:223], v210 offset:0
	v_mfma_f32_32x32x16_bf16 v[66:81], v[236:239], v[252:255], v[66:81]
	ds_read_b128 v[232:235], v214 offset:0
	v_mfma_f32_32x32x16_bf16 v[50:65], v[240:243], v[248:251], v[50:65]
	ds_read_b128 v[216:219], v210 offset:4096
	v_mfma_f32_32x32x16_bf16 v[34:49], v[236:239], v[248:251], v[34:49]
	ds_read_b128 v[228:231], v214 offset:4096
	s_waitcnt lgkmcnt(4)
	v_mfma_f32_32x32x16_bf16 v[18:33], v[240:243], v[244:247], v[18:33]
	ds_read_b128 v[224:227], v214 offset:8192
	v_mfma_f32_32x32x16_bf16 v[2:17], v[236:239], v[244:247], v[2:17]
	s_waitcnt lgkmcnt(1)
	v_mfma_f32_32x32x16_bf16 v[82:97], v[220:223], v[232:235], v[82:97]
	ds_read_b128 v[240:243], v209 offset:0
	v_mfma_f32_32x32x16_bf16 v[66:81], v[216:219], v[232:235], v[66:81]
	ds_read_b128 v[252:255], v213 offset:0
	v_mfma_f32_32x32x16_bf16 v[50:65], v[220:223], v[228:231], v[50:65]
	ds_read_b128 v[236:239], v209 offset:4096
	v_mfma_f32_32x32x16_bf16 v[34:49], v[216:219], v[228:231], v[34:49]
	ds_read_b128 v[248:251], v213 offset:4096
	s_waitcnt lgkmcnt(4)
	v_mfma_f32_32x32x16_bf16 v[18:33], v[220:223], v[224:227], v[18:33]
	ds_read_b128 v[244:247], v213 offset:8192
	v_mfma_f32_32x32x16_bf16 v[2:17], v[216:219], v[224:227], v[2:17]
	s_waitcnt lgkmcnt(1)
	v_mfma_f32_32x32x16_bf16 v[82:97], v[240:243], v[252:255], v[82:97]
	ds_read_b128 v[220:223], v208 offset:0
	s_add_u32 s83, s79, s78
	s_add_u32 s83, s83, 2
	s_and_b32 s83, s83, 15
	v_mfma_f32_32x32x16_bf16 v[66:81], v[236:239], v[252:255], v[66:81]
	ds_read_b128 v[232:235], v212 offset:0
	s_lshl_b32 s83, s83, 7
	s_add_u32 s70, s66, s83
	v_mfma_f32_32x32x16_bf16 v[50:65], v[240:243], v[248:251], v[50:65]
	ds_read_b128 v[216:219], v208 offset:4096
	s_addc_u32 s71, s67, 0
	s_add_u32 s72, s68, s83
	v_mfma_f32_32x32x16_bf16 v[34:49], v[236:239], v[248:251], v[34:49]
	ds_read_b128 v[228:231], v212 offset:4096
	s_addc_u32 s73, s69, 0
	s_add_u32 s81, s80, 0x0
	s_add_u32 s82, s80, 0xc000
	s_waitcnt lgkmcnt(4)
	v_mfma_f32_32x32x16_bf16 v[18:33], v[240:243], v[244:247], v[18:33]
	ds_read_b128 v[224:227], v212 offset:8192
	v_mfma_f32_32x32x16_bf16 v[2:17], v[236:239], v[244:247], v[2:17]
	s_waitcnt vmcnt(0) lgkmcnt(0)
	s_barrier
	v_mfma_f32_32x32x16_bf16 v[82:97], v[220:223], v[232:235], v[82:97]
	s_add_u32 m0, s81, 0x0
	ds_read_b128 v[240:243], v211 offset:16384
	global_load_lds_dwordx4 v207, s[70:71]
	s_add_u32 m0, s81, 0x1000
	s_nop 0
	global_load_lds_dwordx4 v206, s[70:71]
	v_mfma_f32_32x32x16_bf16 v[66:81], v[216:219], v[232:235], v[66:81]
	s_add_u32 m0, s81, 0x2000
	ds_read_b128 v[252:255], v215 offset:24576
	global_load_lds_dwordx4 v205, s[70:71]
	s_add_u32 m0, s81, 0x3000
	s_nop 0
	global_load_lds_dwordx4 v204, s[70:71]
	v_mfma_f32_32x32x16_bf16 v[50:65], v[220:223], v[228:231], v[50:65]
	s_add_u32 m0, s81, 0x4000
	ds_read_b128 v[236:239], v211 offset:20480
	global_load_lds_dwordx4 v203, s[70:71]
	s_add_u32 m0, s81, 0x5000
	s_nop 0
	global_load_lds_dwordx4 v202, s[70:71]
	v_mfma_f32_32x32x16_bf16 v[34:49], v[216:219], v[228:231], v[34:49]
	s_add_u32 m0, s82, 0x0
	ds_read_b128 v[248:251], v215 offset:28672
	global_load_lds_dwordx4 v207, s[72:73]
	s_add_u32 m0, s82, 0x1000
	s_nop 0
	global_load_lds_dwordx4 v206, s[72:73]
	v_mfma_f32_32x32x16_bf16 v[18:33], v[220:223], v[224:227], v[18:33]
	s_add_u32 m0, s82, 0x2000
	ds_read_b128 v[244:247], v215 offset:32768
	global_load_lds_dwordx4 v205, s[72:73]
	s_add_u32 m0, s82, 0x3000
	s_nop 0
	global_load_lds_dwordx4 v204, s[72:73]
	v_mfma_f32_32x32x16_bf16 v[2:17], v[216:219], v[224:227], v[2:17]
	s_waitcnt lgkmcnt(1)
	v_mfma_f32_32x32x16_bf16 v[82:97], v[240:243], v[252:255], v[82:97]
	ds_read_b128 v[220:223], v210 offset:16384
	v_mfma_f32_32x32x16_bf16 v[66:81], v[236:239], v[252:255], v[66:81]
	ds_read_b128 v[232:235], v214 offset:24576
	v_mfma_f32_32x32x16_bf16 v[50:65], v[240:243], v[248:251], v[50:65]
	ds_read_b128 v[216:219], v210 offset:20480
	v_mfma_f32_32x32x16_bf16 v[34:49], v[236:239], v[248:251], v[34:49]
	ds_read_b128 v[228:231], v214 offset:28672
	s_waitcnt lgkmcnt(4)
	v_mfma_f32_32x32x16_bf16 v[18:33], v[240:243], v[244:247], v[18:33]
	ds_read_b128 v[224:227], v214 offset:32768
	v_mfma_f32_32x32x16_bf16 v[2:17], v[236:239], v[244:247], v[2:17]
	s_waitcnt lgkmcnt(1)
	v_mfma_f32_32x32x16_bf16 v[82:97], v[220:223], v[232:235], v[82:97]
	ds_read_b128 v[240:243], v209 offset:16384
	v_mfma_f32_32x32x16_bf16 v[66:81], v[216:219], v[232:235], v[66:81]
	ds_read_b128 v[252:255], v213 offset:24576
	v_mfma_f32_32x32x16_bf16 v[50:65], v[220:223], v[228:231], v[50:65]
	ds_read_b128 v[236:239], v209 offset:20480
	v_mfma_f32_32x32x16_bf16 v[34:49], v[216:219], v[228:231], v[34:49]
	ds_read_b128 v[248:251], v213 offset:28672
	s_waitcnt lgkmcnt(4)
	v_mfma_f32_32x32x16_bf16 v[18:33], v[220:223], v[224:227], v[18:33]
	ds_read_b128 v[244:247], v213 offset:32768
	v_mfma_f32_32x32x16_bf16 v[2:17], v[216:219], v[224:227], v[2:17]
	s_waitcnt lgkmcnt(1)
	v_mfma_f32_32x32x16_bf16 v[82:97], v[240:243], v[252:255], v[82:97]
	ds_read_b128 v[220:223], v208 offset:16384
	s_add_u32 s83, s79, s78
	s_add_u32 s83, s83, 3
	s_and_b32 s83, s83, 15
	v_mfma_f32_32x32x16_bf16 v[66:81], v[236:239], v[252:255], v[66:81]
	ds_read_b128 v[232:235], v212 offset:24576
	s_lshl_b32 s83, s83, 7
	s_add_u32 s70, s66, s83
	v_mfma_f32_32x32x16_bf16 v[50:65], v[240:243], v[248:251], v[50:65]
	ds_read_b128 v[216:219], v208 offset:20480
	s_addc_u32 s71, s67, 0
	s_add_u32 s72, s68, s83
	v_mfma_f32_32x32x16_bf16 v[34:49], v[236:239], v[248:251], v[34:49]
	ds_read_b128 v[228:231], v212 offset:28672
	s_addc_u32 s73, s69, 0
	s_add_u32 s81, s80, 0x6000
	s_add_u32 s82, s80, 0x10000
	s_waitcnt lgkmcnt(4)
	v_mfma_f32_32x32x16_bf16 v[18:33], v[240:243], v[244:247], v[18:33]
	ds_read_b128 v[224:227], v212 offset:32768
	v_mfma_f32_32x32x16_bf16 v[2:17], v[236:239], v[244:247], v[2:17]
	s_waitcnt vmcnt(0) lgkmcnt(0)
	s_barrier
	v_mfma_f32_32x32x16_bf16 v[82:97], v[220:223], v[232:235], v[82:97]
	s_add_u32 m0, s81, 0x0
	ds_read_b128 v[240:243], v211 offset:0
	global_load_lds_dwordx4 v207, s[70:71]
	s_add_u32 m0, s81, 0x1000
	s_nop 0
	global_load_lds_dwordx4 v206, s[70:71]
	v_mfma_f32_32x32x16_bf16 v[66:81], v[216:219], v[232:235], v[66:81]
	s_add_u32 m0, s81, 0x2000
	ds_read_b128 v[252:255], v215 offset:0
	global_load_lds_dwordx4 v205, s[70:71]
	s_add_u32 m0, s81, 0x3000
	s_nop 0
	global_load_lds_dwordx4 v204, s[70:71]
	v_mfma_f32_32x32x16_bf16 v[50:65], v[220:223], v[228:231], v[50:65]
	s_add_u32 m0, s81, 0x4000
	ds_read_b128 v[236:239], v211 offset:4096
	global_load_lds_dwordx4 v203, s[70:71]
	s_add_u32 m0, s81, 0x5000
	s_nop 0
	global_load_lds_dwordx4 v202, s[70:71]
	v_mfma_f32_32x32x16_bf16 v[34:49], v[216:219], v[228:231], v[34:49]
	s_add_u32 m0, s82, 0x0
	ds_read_b128 v[248:251], v215 offset:4096
	global_load_lds_dwordx4 v207, s[72:73]
	s_add_u32 m0, s82, 0x1000
	s_nop 0
	global_load_lds_dwordx4 v206, s[72:73]
	v_mfma_f32_32x32x16_bf16 v[18:33], v[220:223], v[224:227], v[18:33]
	s_add_u32 m0, s82, 0x2000
	ds_read_b128 v[244:247], v215 offset:8192
	global_load_lds_dwordx4 v205, s[72:73]
	s_add_u32 m0, s82, 0x3000
	s_nop 0
	global_load_lds_dwordx4 v204, s[72:73]
	v_mfma_f32_32x32x16_bf16 v[2:17], v[216:219], v[224:227], v[2:17]
	s_add_u32 s78, s78, 2
	s_cmp_lt_u32 s78, 14
	s_cbranch_scc1 .Lgm_ph17_loop
	s_waitcnt lgkmcnt(1)
	v_mfma_f32_32x32x16_bf16 v[82:97], v[240:243], v[252:255], v[82:97]
	ds_read_b128 v[220:223], v210 offset:0
	v_mfma_f32_32x32x16_bf16 v[66:81], v[236:239], v[252:255], v[66:81]
	ds_read_b128 v[232:235], v214 offset:0
	v_mfma_f32_32x32x16_bf16 v[50:65], v[240:243], v[248:251], v[50:65]
	ds_read_b128 v[216:219], v210 offset:4096
	v_mfma_f32_32x32x16_bf16 v[34:49], v[236:239], v[248:251], v[34:49]
	ds_read_b128 v[228:231], v214 offset:4096
	s_waitcnt lgkmcnt(4)
	v_mfma_f32_32x32x16_bf16 v[18:33], v[240:243], v[244:247], v[18:33]
	ds_read_b128 v[224:227], v214 offset:8192
	v_mfma_f32_32x32x16_bf16 v[2:17], v[236:239], v[244:247], v[2:17]
	s_waitcnt lgkmcnt(1)
	v_mfma_f32_32x32x16_bf16 v[82:97], v[220:223], v[232:235], v[82:97]
	ds_read_b128 v[240:243], v209 offset:0
	v_mfma_f32_32x32x16_bf16 v[66:81], v[216:219], v[232:235], v[66:81]
	ds_read_b128 v[252:255], v213 offset:0
	v_mfma_f32_32x32x16_bf16 v[50:65], v[220:223], v[228:231], v[50:65]
	ds_read_b128 v[236:239], v209 offset:4096
	v_mfma_f32_32x32x16_bf16 v[34:49], v[216:219], v[228:231], v[34:49]
	ds_read_b128 v[248:251], v213 offset:4096
	s_waitcnt lgkmcnt(4)
	v_mfma_f32_32x32x16_bf16 v[18:33], v[220:223], v[224:227], v[18:33]
	ds_read_b128 v[244:247], v213 offset:8192
	v_mfma_f32_32x32x16_bf16 v[2:17], v[216:219], v[224:227], v[2:17]
	s_waitcnt lgkmcnt(1)
	v_mfma_f32_32x32x16_bf16 v[82:97], v[240:243], v[252:255], v[82:97]
	ds_read_b128 v[220:223], v208 offset:0
	v_mfma_f32_32x32x16_bf16 v[66:81], v[236:239], v[252:255], v[66:81]
	ds_read_b128 v[232:235], v212 offset:0
	v_mfma_f32_32x32x16_bf16 v[50:65], v[240:243], v[248:251], v[50:65]
	ds_read_b128 v[216:219], v208 offset:4096
	v_mfma_f32_32x32x16_bf16 v[34:49], v[236:239], v[248:251], v[34:49]
	ds_read_b128 v[228:231], v212 offset:4096
	s_waitcnt lgkmcnt(4)
	v_mfma_f32_32x32x16_bf16 v[18:33], v[240:243], v[244:247], v[18:33]
	ds_read_b128 v[224:227], v212 offset:8192
	v_mfma_f32_32x32x16_bf16 v[2:17], v[236:239], v[244:247], v[2:17]
	s_waitcnt vmcnt(0) lgkmcnt(0)
	s_barrier
	v_mfma_f32_32x32x16_bf16 v[82:97], v[220:223], v[232:235], v[82:97]
	ds_read_b128 v[240:243], v211 offset:16384
	v_mfma_f32_32x32x16_bf16 v[66:81], v[216:219], v[232:235], v[66:81]
	ds_read_b128 v[252:255], v215 offset:24576
	v_mfma_f32_32x32x16_bf16 v[50:65], v[220:223], v[228:231], v[50:65]
	ds_read_b128 v[236:239], v211 offset:20480
	v_mfma_f32_32x32x16_bf16 v[34:49], v[216:219], v[228:231], v[34:49]
	ds_read_b128 v[248:251], v215 offset:28672
	v_mfma_f32_32x32x16_bf16 v[18:33], v[220:223], v[224:227], v[18:33]
	ds_read_b128 v[244:247], v215 offset:32768
	v_mfma_f32_32x32x16_bf16 v[2:17], v[216:219], v[224:227], v[2:17]
	s_waitcnt lgkmcnt(1)
	v_mfma_f32_32x32x16_bf16 v[82:97], v[240:243], v[252:255], v[82:97]
	ds_read_b128 v[220:223], v210 offset:16384
	v_mfma_f32_32x32x16_bf16 v[66:81], v[236:239], v[252:255], v[66:81]
	ds_read_b128 v[232:235], v214 offset:24576
	v_mfma_f32_32x32x16_bf16 v[50:65], v[240:243], v[248:251], v[50:65]
	ds_read_b128 v[216:219], v210 offset:20480
	v_mfma_f32_32x32x16_bf16 v[34:49], v[236:239], v[248:251], v[34:49]
	ds_read_b128 v[228:231], v214 offset:28672
	s_waitcnt lgkmcnt(4)
	v_mfma_f32_32x32x16_bf16 v[18:33], v[240:243], v[244:247], v[18:33]
	ds_read_b128 v[224:227], v214 offset:32768
	v_mfma_f32_32x32x16_bf16 v[2:17], v[236:239], v[244:247], v[2:17]
	s_waitcnt lgkmcnt(1)
	v_mfma_f32_32x32x16_bf16 v[82:97], v[220:223], v[232:235], v[82:97]
	ds_read_b128 v[240:243], v209 offset:16384
	v_mfma_f32_32x32x16_bf16 v[66:81], v[216:219], v[232:235], v[66:81]
	ds_read_b128 v[252:255], v213 offset:24576
	v_mfma_f32_32x32x16_bf16 v[50:65], v[220:223], v[228:231], v[50:65]
	ds_read_b128 v[236:239], v209 offset:20480
	v_mfma_f32_32x32x16_bf16 v[34:49], v[216:219], v[228:231], v[34:49]
	ds_read_b128 v[248:251], v213 offset:28672
	s_waitcnt lgkmcnt(4)
	v_mfma_f32_32x32x16_bf16 v[18:33], v[220:223], v[224:227], v[18:33]
	ds_read_b128 v[244:247], v213 offset:32768
	v_mfma_f32_32x32x16_bf16 v[2:17], v[216:219], v[224:227], v[2:17]
	s_waitcnt lgkmcnt(1)
	v_mfma_f32_32x32x16_bf16 v[82:97], v[240:243], v[252:255], v[82:97]
	ds_read_b128 v[220:223], v208 offset:16384
	v_mfma_f32_32x32x16_bf16 v[66:81], v[236:239], v[252:255], v[66:81]
	ds_read_b128 v[232:235], v212 offset:24576
	v_mfma_f32_32x32x16_bf16 v[50:65], v[240:243], v[248:251], v[50:65]
	ds_read_b128 v[216:219], v208 offset:20480
	v_mfma_f32_32x32x16_bf16 v[34:49], v[236:239], v[248:251], v[34:49]
	ds_read_b128 v[228:231], v212 offset:28672
	s_waitcnt lgkmcnt(4)
	v_mfma_f32_32x32x16_bf16 v[18:33], v[240:243], v[244:247], v[18:33]
	ds_read_b128 v[224:227], v212 offset:32768
	v_mfma_f32_32x32x16_bf16 v[2:17], v[236:239], v[244:247], v[2:17]
	s_waitcnt vmcnt(0) lgkmcnt(0)
	s_barrier
	v_mfma_f32_32x32x16_bf16 v[82:97], v[220:223], v[232:235], v[82:97]
	v_mfma_f32_32x32x16_bf16 v[66:81], v[216:219], v[232:235], v[66:81]
	v_mfma_f32_32x32x16_bf16 v[50:65], v[220:223], v[228:231], v[50:65]
	v_mfma_f32_32x32x16_bf16 v[34:49], v[216:219], v[228:231], v[34:49]
	v_mfma_f32_32x32x16_bf16 v[18:33], v[220:223], v[224:227], v[18:33]
	v_mfma_f32_32x32x16_bf16 v[2:17], v[216:219], v[224:227], v[2:17]
	s_nop 7
	s_nop 7
	v_add_u32_e32 v144, v116, v120
	s_nop 4
	v_add_u32_e32 v145, v116, v121
	s_nop 4
	v_add_u32_e32 v147, v116, v122
	s_nop 4
	v_or_b32_e32 v143, s5, v123
	s_nop 4
	v_cmp_lt_i32_e64 s[6:7], s3, v143
	s_nop 4
	v_add_u32_e32 v98, v118, v122
	s_nop 4
	s_waitcnt lgkmcnt(0)
	v_add_u32_e32 v106, s4, v115
	v_ashrrev_i32_e32 v107, 31, v106
	v_lshlrev_b64 v[110:111], 11, v[106:107]
	v_or_b32_e32 v104, v143, v124
	v_lshl_add_u64 v[108:109], s[10:11], 0, v[110:111]
	s_and_saveexec_b64 s[4:5], s[6:7]
	s_xor_b64 s[4:5], exec, s[4:5]
	s_cbranch_execz .LBB0_1996
	v_mul_f32_e32 v98, 0xbfb8aa3b, v82
	v_exp_f32_e32 v144, v98
	v_mul_f32_e32 v98, 0xbfb8aa3b, v83
	v_exp_f32_e32 v145, v98
	s_nop 0
	v_pk_add_f32 v[144:145], v[144:145], 1.0 op_sel_hi:[1,0]
	s_nop 0
	v_div_scale_f32 v98, s[30:31], v145, v145, v83
	v_rcp_f32_e32 v105, v98
	v_div_scale_f32 v107, vcc, v83, v145, v83
	v_fma_f32 v147, -v98, v105, 1.0
	v_fmac_f32_e32 v105, v147, v105
	v_mul_f32_e32 v147, v107, v105
	v_fma_f32 v149, -v98, v147, v107
	v_fmac_f32_e32 v147, v149, v105
	v_fma_f32 v98, -v98, v147, v107
	v_div_scale_f32 v107, s[30:31], v144, v144, v82
	v_rcp_f32_e32 v149, v107
	v_div_fmas_f32 v98, v98, v105, v147
	v_mul_f32_e32 v147, 0xbfb8aa3b, v84
	v_exp_f32_e32 v152, v147
	v_mul_f32_e32 v147, 0xbfb8aa3b, v85
	v_fma_f32 v105, -v107, v149, 1.0
	v_exp_f32_e32 v153, v147
	v_fmac_f32_e32 v149, v105, v149
	v_div_scale_f32 v105, vcc, v82, v144, v82
	v_div_fixup_f32 v98, v98, v145, v83
	v_mul_f32_e32 v145, v105, v149
	v_fma_f32 v147, -v107, v145, v105
	v_fmac_f32_e32 v145, v147, v149
	v_pk_add_f32 v[152:153], v[152:153], 1.0 op_sel_hi:[1,0]
	v_fma_f32 v105, -v107, v145, v105
	v_div_scale_f32 v107, s[30:31], v153, v153, v85
	v_rcp_f32_e32 v147, v107
	v_div_fmas_f32 v105, v105, v149, v145
	v_div_fixup_f32 v105, v105, v144, v82
	v_cvt_pk_bf16_f32 v144, v105, v98
	v_fma_f32 v98, -v107, v147, 1.0
	v_fmac_f32_e32 v147, v98, v147
	v_div_scale_f32 v98, vcc, v85, v153, v85
	v_mul_f32_e32 v105, v98, v147
	v_fma_f32 v145, -v107, v105, v98
	v_fmac_f32_e32 v105, v145, v147
	v_fma_f32 v98, -v107, v105, v98
	v_div_scale_f32 v107, s[30:31], v152, v152, v84
	v_rcp_f32_e32 v145, v107
	v_div_fmas_f32 v98, v98, v147, v105
	v_div_fixup_f32 v98, v98, v153, v85
	v_fma_f32 v105, -v107, v145, 1.0
	v_fmac_f32_e32 v145, v105, v145
	v_div_scale_f32 v105, vcc, v84, v152, v84
	v_mul_f32_e32 v147, v105, v145
	v_fma_f32 v149, -v107, v147, v105
	v_fmac_f32_e32 v147, v149, v145
	v_fma_f32 v105, -v107, v147, v105
	v_div_fmas_f32 v105, v105, v145, v147
	v_div_fixup_f32 v105, v105, v152, v84
	v_cvt_pk_bf16_f32 v145, v105, v98
	v_mov_b32_e32 v105, v99
	v_lshl_add_u64 v[152:153], v[104:105], 1, v[108:109]
	global_store_dwordx2 v[152:153], v[144:145], off offset:-2048

.LBB0_2331:
	s_ashr_i32 s10, s2, 31
	s_lshr_b32 s10, s10, 26
	s_add_i32 s10, s2, s10
	s_ashr_i32 s30, s10, 6
	s_and_b32 s10, s10, 0x3ffffc0
	s_sub_i32 s28, s2, s10
	s_mulk_i32 s28, 0xc0
	v_add_u32_e32 v2, s28, v108
	s_lshr_b32 s10, s28, 6
	s_lshl_b32 s29, s30, 7
	v_ashrrev_i32_e32 v3, 31, v2
	s_add_i32 s10, s10, s30
	v_lshlrev_b64 v[2:3], 11, v[2:3]
	v_or_b32_e32 v4, s29, v108
	s_lshl_b32 s30, s10, 6
	s_lshl_b32 s10, s10, 7
	v_ashrrev_i32_e32 v5, 31, v4
	v_lshl_add_u64 v[104:105], v[100:101], 0, v[2:3]
	s_and_b32 s10, s10, 0x780
	v_readfirstlane_b32 s31, v109
	v_lshlrev_b64 v[4:5], 11, v[4:5]
	v_lshl_add_u64 v[2:3], v[104:105], 0, s[10:11]
	s_mov_b32 m0, s31
	v_readfirstlane_b32 s31, v127
	v_lshl_add_u64 v[106:107], v[102:103], 0, v[4:5]
	s_waitcnt vmcnt(0)
	s_barrier
	s_load_dwordx2 s[66:67], s[0:1], 0x118
	s_load_dwordx2 s[68:69], s[0:1], 0xd0
	v_and_b32_e32 v201, 0x3ff, v0
	v_readfirstlane_b32 s80, v0
	v_and_b32_e32 v200, 31, v201
	v_bfe_u32 v214, v201, 1, 3
	v_bfe_u32 v213, v201, 5, 1
	v_xor_b32_e32 v214, v214, v213
	v_lshlrev_b32_e32 v214, 4, v214
	s_and_b32 s80, s80, 0x3ff
	s_lshr_b32 s83, s80, 6
	s_lshl_b32 s80, s80, 4
	s_lshr_b32 s84, s83, 1
	s_and_b32 s83, s83, 1
	s_mul_i32 s84, s84, 0x3000
	s_lshl_b32 s83, s83, 13
	s_add_u32 s83, s83, 0xc000
	v_lshlrev_b32_e32 v200, 7, v200
	v_or_b32_e32 v200, v200, v214
	v_add_u32_e32 v215, s84, v200
	v_add_u32_e32 v211, s83, v200
	v_xor_b32_e32 v214, 0x20, v215
	v_xor_b32_e32 v210, 0x20, v211
	v_xor_b32_e32 v213, 0x40, v215
	v_xor_b32_e32 v209, 0x40, v211
	v_xor_b32_e32 v212, 0x60, v215
	v_xor_b32_e32 v208, 0x60, v211
	v_bfe_u32 v200, v201, 4, 3
	v_and_b32_e32 v206, 7, v201
	v_xor_b32_e32 v200, v200, v206
	v_lshlrev_b32_e32 v200, 4, v200
	v_lshrrev_b32_e32 v206, 3, v201
	v_lshl_or_b32 v207, v206, 11, v200
	v_add_u32_e32 v206, 0x10000, v207
	v_add_u32_e32 v205, 0x20000, v207
	v_add_u32_e32 v204, 0x30000, v207
	v_add_u32_e32 v203, 0x40000, v207
	v_add_u32_e32 v202, 0x50000, v207
	s_lshr_b32 s83, s2, 6
	s_and_b32 s84, s2, 63
	s_mov_b32 s79, 0
	s_mul_i32 s84, s84, 0x60000
	s_lshl_b32 s83, s83, 18
	s_add_u32 s83, s83, 0x200000
	s_waitcnt lgkmcnt(0)
	s_add_u32 s66, s66, s84
	s_addc_u32 s67, s67, 0
	s_add_u32 s68, s68, s83
	s_addc_u32 s69, s69, 0
	s_add_u32 s83, s79, 0
	s_and_b32 s83, s83, 15
	s_lshl_b32 s83, s83, 7
	s_add_u32 s70, s66, s83
	s_addc_u32 s71, s67, 0
	s_add_u32 s72, s68, s83
	s_addc_u32 s73, s69, 0
	s_add_u32 s81, s80, 0x0
	s_add_u32 s82, s80, 0xc000
	s_add_u32 m0, s81, 0x0
	s_nop 0
	global_load_lds_dwordx4 v207, s[70:71]
	s_add_u32 m0, s81, 0x1000
	s_nop 0
	global_load_lds_dwordx4 v206, s[70:71]
	s_add_u32 m0, s81, 0x2000
	s_nop 0
	global_load_lds_dwordx4 v205, s[70:71]
	s_add_u32 m0, s81, 0x3000
	s_nop 0
	global_load_lds_dwordx4 v204, s[70:71]
	s_add_u32 m0, s81, 0x4000
	s_nop 0
	global_load_lds_dwordx4 v203, s[70:71]
	s_add_u32 m0, s81, 0x5000
	s_nop 0
	global_load_lds_dwordx4 v202, s[70:71]
	s_add_u32 m0, s82, 0x0
	s_nop 0
	global_load_lds_dwordx4 v207, s[72:73]
	s_add_u32 m0, s82, 0x1000
	s_nop 0
	global_load_lds_dwordx4 v206, s[72:73]
	s_add_u32 m0, s82, 0x2000
	s_nop 0
	global_load_lds_dwordx4 v205, s[72:73]
	s_add_u32 m0, s82, 0x3000
	s_nop 0
	global_load_lds_dwordx4 v204, s[72:73]
	s_add_u32 s83, s79, 1
	s_and_b32 s83, s83, 15
	s_lshl_b32 s83, s83, 7
	s_add_u32 s70, s66, s83
	s_addc_u32 s71, s67, 0
	s_add_u32 s72, s68, s83
	s_addc_u32 s73, s69, 0
	s_add_u32 s81, s80, 0x6000
	s_add_u32 s82, s80, 0x10000
	s_add_u32 m0, s81, 0x0
	s_nop 0
	global_load_lds_dwordx4 v207, s[70:71]
	s_add_u32 m0, s81, 0x1000
	s_nop 0
	global_load_lds_dwordx4 v206, s[70:71]
	s_add_u32 m0, s81, 0x2000
	s_nop 0
	global_load_lds_dwordx4 v205, s[70:71]
	s_add_u32 m0, s81, 0x3000
	s_nop 0
	global_load_lds_dwordx4 v204, s[70:71]
	s_add_u32 m0, s81, 0x4000
	s_nop 0
	global_load_lds_dwordx4 v203, s[70:71]
	s_add_u32 m0, s81, 0x5000
	s_nop 0
	global_load_lds_dwordx4 v202, s[70:71]
	s_add_u32 m0, s82, 0x0
	s_nop 0
	global_load_lds_dwordx4 v207, s[72:73]
	s_add_u32 m0, s82, 0x1000
	s_nop 0
	global_load_lds_dwordx4 v206, s[72:73]
	s_add_u32 m0, s82, 0x2000
	s_nop 0
	global_load_lds_dwordx4 v205, s[72:73]
	s_add_u32 m0, s82, 0x3000
	s_nop 0
	global_load_lds_dwordx4 v204, s[72:73]
	v_mov_b32_e32 v2, 0
	v_mov_b32_e32 v3, 0
	v_mov_b32_e32 v4, 0
	v_mov_b32_e32 v5, 0
	v_mov_b32_e32 v6, 0
	v_mov_b32_e32 v7, 0
	v_mov_b32_e32 v8, 0
	v_mov_b32_e32 v9, 0
	v_mov_b32_e32 v10, 0
	v_mov_b32_e32 v11, 0
	v_mov_b32_e32 v12, 0
	v_mov_b32_e32 v13, 0
	v_mov_b32_e32 v14, 0
	v_mov_b32_e32 v15, 0
	v_mov_b32_e32 v16, 0
	v_mov_b32_e32 v17, 0
	v_mov_b32_e32 v18, 0
	v_mov_b32_e32 v19, 0
	v_mov_b32_e32 v20, 0
	v_mov_b32_e32 v21, 0
	v_mov_b32_e32 v22, 0
	v_mov_b32_e32 v23, 0
	v_mov_b32_e32 v24, 0
	v_mov_b32_e32 v25, 0
	v_mov_b32_e32 v26, 0
	v_mov_b32_e32 v27, 0
	v_mov_b32_e32 v28, 0
	v_mov_b32_e32 v29, 0
	v_mov_b32_e32 v30, 0
	v_mov_b32_e32 v31, 0
	v_mov_b32_e32 v32, 0
	v_mov_b32_e32 v33, 0
	v_mov_b32_e32 v34, 0
	v_mov_b32_e32 v35, 0
	v_mov_b32_e32 v36, 0
	v_mov_b32_e32 v37, 0
	v_mov_b32_e32 v38, 0
	v_mov_b32_e32 v39, 0
	v_mov_b32_e32 v40, 0
	v_mov_b32_e32 v41, 0
	v_mov_b32_e32 v42, 0
	v_mov_b32_e32 v43, 0
	v_mov_b32_e32 v44, 0
	v_mov_b32_e32 v45, 0
	v_mov_b32_e32 v46, 0
	v_mov_b32_e32 v47, 0
	v_mov_b32_e32 v48, 0
	v_mov_b32_e32 v49, 0
	v_mov_b32_e32 v50, 0
	v_mov_b32_e32 v51, 0
	v_mov_b32_e32 v52, 0
	v_mov_b32_e32 v53, 0
	v_mov_b32_e32 v54, 0
	v_mov_b32_e32 v55, 0
	v_mov_b32_e32 v56, 0
	v_mov_b32_e32 v57, 0
	v_mov_b32_e32 v58, 0
	v_mov_b32_e32 v59, 0
	v_mov_b32_e32 v60, 0
	v_mov_b32_e32 v61, 0
	v_mov_b32_e32 v62, 0
	v_mov_b32_e32 v63, 0
	v_mov_b32_e32 v64, 0
	v_mov_b32_e32 v65, 0
	v_mov_b32_e32 v66, 0
	v_mov_b32_e32 v67, 0
	v_mov_b32_e32 v68, 0
	v_mov_b32_e32 v69, 0
	v_mov_b32_e32 v70, 0
	v_mov_b32_e32 v71, 0
	v_mov_b32_e32 v72, 0
	v_mov_b32_e32 v73, 0
	v_mov_b32_e32 v74, 0
	v_mov_b32_e32 v75, 0
	v_mov_b32_e32 v76, 0
	v_mov_b32_e32 v77, 0
	v_mov_b32_e32 v78, 0
	v_mov_b32_e32 v79, 0
	v_mov_b32_e32 v80, 0
	v_mov_b32_e32 v81, 0
	v_mov_b32_e32 v82, 0
	v_mov_b32_e32 v83, 0
	v_mov_b32_e32 v84, 0
	v_mov_b32_e32 v85, 0
	v_mov_b32_e32 v86, 0
	v_mov_b32_e32 v87, 0
	v_mov_b32_e32 v88, 0
	v_mov_b32_e32 v89, 0
	v_mov_b32_e32 v90, 0
	v_mov_b32_e32 v91, 0
	v_mov_b32_e32 v92, 0
	v_mov_b32_e32 v93, 0
	v_mov_b32_e32 v94, 0
	v_mov_b32_e32 v95, 0
	v_mov_b32_e32 v96, 0
	v_mov_b32_e32 v97, 0
	s_waitcnt vmcnt(10)
	s_barrier
	ds_read_b128 v[240:243], v211 offset:0
	ds_read_b128 v[252:255], v215 offset:0
	ds_read_b128 v[236:239], v211 offset:4096
	ds_read_b128 v[248:251], v215 offset:4096
	ds_read_b128 v[244:247], v215 offset:8192
	s_mov_b32 s78, 0
.Lgm_ph20_loop:
	s_waitcnt lgkmcnt(1)
	v_mfma_f32_32x32x16_bf16 v[82:97], v[240:243], v[252:255], v[82:97]
	ds_read_b128 v[220:223], v210 offset:0
	v_mfma_f32_32x32x16_bf16 v[66:81], v[236:239], v[252:255], v[66:81]
	ds_read_b128 v[232:235], v214 offset:0
	v_mfma_f32_32x32x16_bf16 v[50:65], v[240:243], v[248:251], v[50:65]
	ds_read_b128 v[216:219], v210 offset:4096
	v_mfma_f32_32x32x16_bf16 v[34:49], v[236:239], v[248:251], v[34:49]
	ds_read_b128 v[228:231], v214 offset:4096
	s_waitcnt lgkmcnt(4)
	v_mfma_f32_32x32x16_bf16 v[18:33], v[240:243], v[244:247], v[18:33]
	ds_read_b128 v[224:227], v214 offset:8192
	v_mfma_f32_32x32x16_bf16 v[2:17], v[236:239], v[244:247], v[2:17]
	s_waitcnt lgkmcnt(1)
	v_mfma_f32_32x32x16_bf16 v[82:97], v[220:223], v[232:235], v[82:97]
	ds_read_b128 v[240:243], v209 offset:0
	v_mfma_f32_32x32x16_bf16 v[66:81], v[216:219], v[232:235], v[66:81]
	ds_read_b128 v[252:255], v213 offset:0
	v_mfma_f32_32x32x16_bf16 v[50:65], v[220:223], v[228:231], v[50:65]
	ds_read_b128 v[236:239], v209 offset:4096
	v_mfma_f32_32x32x16_bf16 v[34:49], v[216:219], v[228:231], v[34:49]
	ds_read_b128 v[248:251], v213 offset:4096
	s_waitcnt lgkmcnt(4)
	v_mfma_f32_32x32x16_bf16 v[18:33], v[220:223], v[224:227], v[18:33]
	ds_read_b128 v[244:247], v213 offset:8192
	v_mfma_f32_32x32x16_bf16 v[2:17], v[216:219], v[224:227], v[2:17]
	s_waitcnt lgkmcnt(1)
	v_mfma_f32_32x32x16_bf16 v[82:97], v[240:243], v[252:255], v[82:97]
	ds_read_b128 v[220:223], v208 offset:0
	s_add_u32 s83, s79, s78
	s_add_u32 s83, s83, 2
	s_and_b32 s83, s83, 15
	v_mfma_f32_32x32x16_bf16 v[66:81], v[236:239], v[252:255], v[66:81]
	ds_read_b128 v[232:235], v212 offset:0
	s_lshl_b32 s83, s83, 7
	s_add_u32 s70, s66, s83
	v_mfma_f32_32x32x16_bf16 v[50:65], v[240:243], v[248:251], v[50:65]
	ds_read_b128 v[216:219], v208 offset:4096
	s_addc_u32 s71, s67, 0
	s_add_u32 s72, s68, s83
	v_mfma_f32_32x32x16_bf16 v[34:49], v[236:239], v[248:251], v[34:49]
	ds_read_b128 v[228:231], v212 offset:4096
	s_addc_u32 s73, s69, 0
	s_add_u32 s81, s80, 0x0
	s_add_u32 s82, s80, 0xc000
	s_waitcnt lgkmcnt(4)
	v_mfma_f32_32x32x16_bf16 v[18:33], v[240:243], v[244:247], v[18:33]
	ds_read_b128 v[224:227], v212 offset:8192
	v_mfma_f32_32x32x16_bf16 v[2:17], v[236:239], v[244:247], v[2:17]
	s_waitcnt vmcnt(0) lgkmcnt(0)
	s_barrier
	v_mfma_f32_32x32x16_bf16 v[82:97], v[220:223], v[232:235], v[82:97]
	s_add_u32 m0, s81, 0x0
	ds_read_b128 v[240:243], v211 offset:16384
	global_load_lds_dwordx4 v207, s[70:71]
	s_add_u32 m0, s81, 0x1000
	s_nop 0
	global_load_lds_dwordx4 v206, s[70:71]
	v_mfma_f32_32x32x16_bf16 v[66:81], v[216:219], v[232:235], v[66:81]
	s_add_u32 m0, s81, 0x2000
	ds_read_b128 v[252:255], v215 offset:24576
	global_load_lds_dwordx4 v205, s[70:71]
	s_add_u32 m0, s81, 0x3000
	s_nop 0
	global_load_lds_dwordx4 v204, s[70:71]
	v_mfma_f32_32x32x16_bf16 v[50:65], v[220:223], v[228:231], v[50:65]
	s_add_u32 m0, s81, 0x4000
	ds_read_b128 v[236:239], v211 offset:20480
	global_load_lds_dwordx4 v203, s[70:71]
	s_add_u32 m0, s81, 0x5000
	s_nop 0
	global_load_lds_dwordx4 v202, s[70:71]
	v_mfma_f32_32x32x16_bf16 v[34:49], v[216:219], v[228:231], v[34:49]
	s_add_u32 m0, s82, 0x0
	ds_read_b128 v[248:251], v215 offset:28672
	global_load_lds_dwordx4 v207, s[72:73]
	s_add_u32 m0, s82, 0x1000
	s_nop 0
	global_load_lds_dwordx4 v206, s[72:73]
	v_mfma_f32_32x32x16_bf16 v[18:33], v[220:223], v[224:227], v[18:33]
	s_add_u32 m0, s82, 0x2000
	ds_read_b128 v[244:247], v215 offset:32768
	global_load_lds_dwordx4 v205, s[72:73]
	s_add_u32 m0, s82, 0x3000
	s_nop 0
	global_load_lds_dwordx4 v204, s[72:73]
	v_mfma_f32_32x32x16_bf16 v[2:17], v[216:219], v[224:227], v[2:17]
	s_waitcnt lgkmcnt(1)
	v_mfma_f32_32x32x16_bf16 v[82:97], v[240:243], v[252:255], v[82:97]
	ds_read_b128 v[220:223], v210 offset:16384
	v_mfma_f32_32x32x16_bf16 v[66:81], v[236:239], v[252:255], v[66:81]
	ds_read_b128 v[232:235], v214 offset:24576
	v_mfma_f32_32x32x16_bf16 v[50:65], v[240:243], v[248:251], v[50:65]
	ds_read_b128 v[216:219], v210 offset:20480
	v_mfma_f32_32x32x16_bf16 v[34:49], v[236:239], v[248:251], v[34:49]
	ds_read_b128 v[228:231], v214 offset:28672
	s_waitcnt lgkmcnt(4)
	v_mfma_f32_32x32x16_bf16 v[18:33], v[240:243], v[244:247], v[18:33]
	ds_read_b128 v[224:227], v214 offset:32768
	v_mfma_f32_32x32x16_bf16 v[2:17], v[236:239], v[244:247], v[2:17]
	s_waitcnt lgkmcnt(1)
	v_mfma_f32_32x32x16_bf16 v[82:97], v[220:223], v[232:235], v[82:97]
	ds_read_b128 v[240:243], v209 offset:16384
	v_mfma_f32_32x32x16_bf16 v[66:81], v[216:219], v[232:235], v[66:81]
	ds_read_b128 v[252:255], v213 offset:24576
	v_mfma_f32_32x32x16_bf16 v[50:65], v[220:223], v[228:231], v[50:65]
	ds_read_b128 v[236:239], v209 offset:20480
	v_mfma_f32_32x32x16_bf16 v[34:49], v[216:219], v[228:231], v[34:49]
	ds_read_b128 v[248:251], v213 offset:28672
	s_waitcnt lgkmcnt(4)
	v_mfma_f32_32x32x16_bf16 v[18:33], v[220:223], v[224:227], v[18:33]
	ds_read_b128 v[244:247], v213 offset:32768
	v_mfma_f32_32x32x16_bf16 v[2:17], v[216:219], v[224:227], v[2:17]
	s_waitcnt lgkmcnt(1)
	v_mfma_f32_32x32x16_bf16 v[82:97], v[240:243], v[252:255], v[82:97]
	ds_read_b128 v[220:223], v208 offset:16384
	s_add_u32 s83, s79, s78
	s_add_u32 s83, s83, 3
	s_and_b32 s83, s83, 15
	v_mfma_f32_32x32x16_bf16 v[66:81], v[236:239], v[252:255], v[66:81]
	ds_read_b128 v[232:235], v212 offset:24576
	s_lshl_b32 s83, s83, 7
	s_add_u32 s70, s66, s83
	v_mfma_f32_32x32x16_bf16 v[50:65], v[240:243], v[248:251], v[50:65]
	ds_read_b128 v[216:219], v208 offset:20480
	s_addc_u32 s71, s67, 0
	s_add_u32 s72, s68, s83
	v_mfma_f32_32x32x16_bf16 v[34:49], v[236:239], v[248:251], v[34:49]
	ds_read_b128 v[228:231], v212 offset:28672
	s_addc_u32 s73, s69, 0
	s_add_u32 s81, s80, 0x6000
	s_add_u32 s82, s80, 0x10000
	s_waitcnt lgkmcnt(4)
	v_mfma_f32_32x32x16_bf16 v[18:33], v[240:243], v[244:247], v[18:33]
	ds_read_b128 v[224:227], v212 offset:32768
	v_mfma_f32_32x32x16_bf16 v[2:17], v[236:239], v[244:247], v[2:17]
	s_waitcnt vmcnt(0) lgkmcnt(0)
	s_barrier
	v_mfma_f32_32x32x16_bf16 v[82:97], v[220:223], v[232:235], v[82:97]
	s_add_u32 m0, s81, 0x0
	ds_read_b128 v[240:243], v211 offset:0
	global_load_lds_dwordx4 v207, s[70:71]
	s_add_u32 m0, s81, 0x1000
	s_nop 0
	global_load_lds_dwordx4 v206, s[70:71]
	v_mfma_f32_32x32x16_bf16 v[66:81], v[216:219], v[232:235], v[66:81]
	s_add_u32 m0, s81, 0x2000
	ds_read_b128 v[252:255], v215 offset:0
	global_load_lds_dwordx4 v205, s[70:71]
	s_add_u32 m0, s81, 0x3000
	s_nop 0
	global_load_lds_dwordx4 v204, s[70:71]
	v_mfma_f32_32x32x16_bf16 v[50:65], v[220:223], v[228:231], v[50:65]
	s_add_u32 m0, s81, 0x4000
	ds_read_b128 v[236:239], v211 offset:4096
	global_load_lds_dwordx4 v203, s[70:71]
	s_add_u32 m0, s81, 0x5000
	s_nop 0
	global_load_lds_dwordx4 v202, s[70:71]
	v_mfma_f32_32x32x16_bf16 v[34:49], v[216:219], v[228:231], v[34:49]
	s_add_u32 m0, s82, 0x0
	ds_read_b128 v[248:251], v215 offset:4096
	global_load_lds_dwordx4 v207, s[72:73]
	s_add_u32 m0, s82, 0x1000
	s_nop 0
	global_load_lds_dwordx4 v206, s[72:73]
	v_mfma_f32_32x32x16_bf16 v[18:33], v[220:223], v[224:227], v[18:33]
	s_add_u32 m0, s82, 0x2000
	ds_read_b128 v[244:247], v215 offset:8192
	global_load_lds_dwordx4 v205, s[72:73]
	s_add_u32 m0, s82, 0x3000
	s_nop 0
	global_load_lds_dwordx4 v204, s[72:73]
	v_mfma_f32_32x32x16_bf16 v[2:17], v[216:219], v[224:227], v[2:17]
	s_add_u32 s78, s78, 2
	s_cmp_lt_u32 s78, 14
	s_cbranch_scc1 .Lgm_ph20_loop
	s_waitcnt lgkmcnt(1)
	v_mfma_f32_32x32x16_bf16 v[82:97], v[240:243], v[252:255], v[82:97]
	ds_read_b128 v[220:223], v210 offset:0
	v_mfma_f32_32x32x16_bf16 v[66:81], v[236:239], v[252:255], v[66:81]
	ds_read_b128 v[232:235], v214 offset:0
	v_mfma_f32_32x32x16_bf16 v[50:65], v[240:243], v[248:251], v[50:65]
	ds_read_b128 v[216:219], v210 offset:4096
	v_mfma_f32_32x32x16_bf16 v[34:49], v[236:239], v[248:251], v[34:49]
	ds_read_b128 v[228:231], v214 offset:4096
	s_waitcnt lgkmcnt(4)
	v_mfma_f32_32x32x16_bf16 v[18:33], v[240:243], v[244:247], v[18:33]
	ds_read_b128 v[224:227], v214 offset:8192
	v_mfma_f32_32x32x16_bf16 v[2:17], v[236:239], v[244:247], v[2:17]
	s_waitcnt lgkmcnt(1)
	v_mfma_f32_32x32x16_bf16 v[82:97], v[220:223], v[232:235], v[82:97]
	ds_read_b128 v[240:243], v209 offset:0
	v_mfma_f32_32x32x16_bf16 v[66:81], v[216:219], v[232:235], v[66:81]
	ds_read_b128 v[252:255], v213 offset:0
	v_mfma_f32_32x32x16_bf16 v[50:65], v[220:223], v[228:231], v[50:65]
	ds_read_b128 v[236:239], v209 offset:4096
	v_mfma_f32_32x32x16_bf16 v[34:49], v[216:219], v[228:231], v[34:49]
	ds_read_b128 v[248:251], v213 offset:4096
	s_waitcnt lgkmcnt(4)
	v_mfma_f32_32x32x16_bf16 v[18:33], v[220:223], v[224:227], v[18:33]
	ds_read_b128 v[244:247], v213 offset:8192
	v_mfma_f32_32x32x16_bf16 v[2:17], v[216:219], v[224:227], v[2:17]
	s_waitcnt lgkmcnt(1)
	v_mfma_f32_32x32x16_bf16 v[82:97], v[240:243], v[252:255], v[82:97]
	ds_read_b128 v[220:223], v208 offset:0
	v_mfma_f32_32x32x16_bf16 v[66:81], v[236:239], v[252:255], v[66:81]
	ds_read_b128 v[232:235], v212 offset:0
	v_mfma_f32_32x32x16_bf16 v[50:65], v[240:243], v[248:251], v[50:65]
	ds_read_b128 v[216:219], v208 offset:4096
	v_mfma_f32_32x32x16_bf16 v[34:49], v[236:239], v[248:251], v[34:49]
	ds_read_b128 v[228:231], v212 offset:4096
	s_waitcnt lgkmcnt(4)
	v_mfma_f32_32x32x16_bf16 v[18:33], v[240:243], v[244:247], v[18:33]
	ds_read_b128 v[224:227], v212 offset:8192
	v_mfma_f32_32x32x16_bf16 v[2:17], v[236:239], v[244:247], v[2:17]
	s_waitcnt vmcnt(0) lgkmcnt(0)
	s_barrier
	v_mfma_f32_32x32x16_bf16 v[82:97], v[220:223], v[232:235], v[82:97]
	ds_read_b128 v[240:243], v211 offset:16384
	v_mfma_f32_32x32x16_bf16 v[66:81], v[216:219], v[232:235], v[66:81]
	ds_read_b128 v[252:255], v215 offset:24576
	v_mfma_f32_32x32x16_bf16 v[50:65], v[220:223], v[228:231], v[50:65]
	ds_read_b128 v[236:239], v211 offset:20480
	v_mfma_f32_32x32x16_bf16 v[34:49], v[216:219], v[228:231], v[34:49]
	ds_read_b128 v[248:251], v215 offset:28672
	v_mfma_f32_32x32x16_bf16 v[18:33], v[220:223], v[224:227], v[18:33]
	ds_read_b128 v[244:247], v215 offset:32768
	v_mfma_f32_32x32x16_bf16 v[2:17], v[216:219], v[224:227], v[2:17]
	s_waitcnt lgkmcnt(1)
	v_mfma_f32_32x32x16_bf16 v[82:97], v[240:243], v[252:255], v[82:97]
	ds_read_b128 v[220:223], v210 offset:16384
	v_mfma_f32_32x32x16_bf16 v[66:81], v[236:239], v[252:255], v[66:81]
	ds_read_b128 v[232:235], v214 offset:24576
	v_mfma_f32_32x32x16_bf16 v[50:65], v[240:243], v[248:251], v[50:65]
	ds_read_b128 v[216:219], v210 offset:20480
	v_mfma_f32_32x32x16_bf16 v[34:49], v[236:239], v[248:251], v[34:49]
	ds_read_b128 v[228:231], v214 offset:28672
	s_waitcnt lgkmcnt(4)
	v_mfma_f32_32x32x16_bf16 v[18:33], v[240:243], v[244:247], v[18:33]
	ds_read_b128 v[224:227], v214 offset:32768
	v_mfma_f32_32x32x16_bf16 v[2:17], v[236:239], v[244:247], v[2:17]
	s_waitcnt lgkmcnt(1)
	v_mfma_f32_32x32x16_bf16 v[82:97], v[220:223], v[232:235], v[82:97]
	ds_read_b128 v[240:243], v209 offset:16384
	v_mfma_f32_32x32x16_bf16 v[66:81], v[216:219], v[232:235], v[66:81]
	ds_read_b128 v[252:255], v213 offset:24576
	v_mfma_f32_32x32x16_bf16 v[50:65], v[220:223], v[228:231], v[50:65]
	ds_read_b128 v[236:239], v209 offset:20480
	v_mfma_f32_32x32x16_bf16 v[34:49], v[216:219], v[228:231], v[34:49]
	ds_read_b128 v[248:251], v213 offset:28672
	s_waitcnt lgkmcnt(4)
	v_mfma_f32_32x32x16_bf16 v[18:33], v[220:223], v[224:227], v[18:33]
	ds_read_b128 v[244:247], v213 offset:32768
	v_mfma_f32_32x32x16_bf16 v[2:17], v[216:219], v[224:227], v[2:17]
	s_waitcnt lgkmcnt(1)
	v_mfma_f32_32x32x16_bf16 v[82:97], v[240:243], v[252:255], v[82:97]
	ds_read_b128 v[220:223], v208 offset:16384
	v_mfma_f32_32x32x16_bf16 v[66:81], v[236:239], v[252:255], v[66:81]
	ds_read_b128 v[232:235], v212 offset:24576
	v_mfma_f32_32x32x16_bf16 v[50:65], v[240:243], v[248:251], v[50:65]
	ds_read_b128 v[216:219], v208 offset:20480
	v_mfma_f32_32x32x16_bf16 v[34:49], v[236:239], v[248:251], v[34:49]
	ds_read_b128 v[228:231], v212 offset:28672
	s_waitcnt lgkmcnt(4)
	v_mfma_f32_32x32x16_bf16 v[18:33], v[240:243], v[244:247], v[18:33]
	ds_read_b128 v[224:227], v212 offset:32768
	v_mfma_f32_32x32x16_bf16 v[2:17], v[236:239], v[244:247], v[2:17]
	s_waitcnt vmcnt(0) lgkmcnt(0)
	s_barrier
	v_mfma_f32_32x32x16_bf16 v[82:97], v[220:223], v[232:235], v[82:97]
	v_mfma_f32_32x32x16_bf16 v[66:81], v[216:219], v[232:235], v[66:81]
	v_mfma_f32_32x32x16_bf16 v[50:65], v[220:223], v[228:231], v[50:65]
	v_mfma_f32_32x32x16_bf16 v[34:49], v[216:219], v[228:231], v[34:49]
	v_mfma_f32_32x32x16_bf16 v[18:33], v[220:223], v[224:227], v[18:33]
	v_mfma_f32_32x32x16_bf16 v[2:17], v[216:219], v[224:227], v[2:17]
	s_nop 7
	s_nop 7
	s_waitcnt lgkmcnt(0)
	s_nop 10
	ds_write_b128 v145, v[82:85]
	ds_write_b128 v145, v[86:89] offset:32
	ds_write_b128 v145, v[90:93] offset:64
	ds_write_b128 v145, v[94:97] offset:96
	ds_write_b128 v145, v[66:69] offset:128
	ds_write_b128 v145, v[70:73] offset:160
	ds_write_b128 v145, v[74:77] offset:192
	ds_write_b128 v145, v[78:81] offset:224
	s_waitcnt lgkmcnt(0)
	v_add_u32_e32 v104, s28, v111
	v_or_b32_e32 v244, s29, v119
	v_lshlrev_b32_e32 v242, 2, v244
	v_add_u32_e32 v242, s3, v242
	v_lshlrev_b32_e32 v243, 1, v244
	v_mov_b32_e32 v240, v104
	v_add_u32_e32 v241, 0xfffff000, v240
	v_lshrrev_b32_e32 v241, 11, v241
	v_mad_u32_u24 v241, v241, s26, s26
	v_lshlrev_b32_e32 v241, 2, v241
	v_or_b32_e32 v232, v240, v1
	v_or_b32_e32 v233, v240, v120
	v_or_b32_e32 v234, v240, v121
	v_or_b32_e32 v235, v240, v122
	v_or_b32_e32 v236, v240, v123
	v_or_b32_e32 v237, v240, v124
	v_or_b32_e32 v238, v240, v125
	v_or_b32_e32 v239, v240, v126
	v_cmp_lt_i32_e64 s[82:83], s27, v232
	v_cmp_lt_i32_e64 s[84:85], s27, v233
	v_cmp_lt_i32_e64 s[86:87], s27, v234
	v_cmp_lt_i32_e64 s[88:89], s27, v235
	v_cmp_lt_i32_e64 s[90:91], s27, v236
	v_cmp_lt_i32_e64 s[92:93], s27, v237
	v_cmp_lt_i32_e64 s[94:95], s27, v238
	v_cmp_lt_i32_e64 s[96:97], s27, v239
	s_waitcnt lgkmcnt(0)
	v_cndmask_b32_e64 v200, 0, v241, s[82:83]
	v_cndmask_b32_e64 v204, 0, v241, s[84:85]
	v_cndmask_b32_e64 v208, 0, v241, s[86:87]
	v_cndmask_b32_e64 v212, 0, v241, s[88:89]
	v_cndmask_b32_e64 v216, 0, v241, s[90:91]
	v_cndmask_b32_e64 v220, 0, v241, s[92:93]
	v_cndmask_b32_e64 v224, 0, v241, s[94:95]
	v_cndmask_b32_e64 v228, 0, v241, s[96:97]
	v_add_u32_e32 v200, v200, v242
	v_add_u32_e32 v204, v204, v242
	v_add_u32_e32 v208, v208, v242
	v_add_u32_e32 v212, v212, v242
	v_add_u32_e32 v216, v216, v242
	v_add_u32_e32 v220, v220, v242
	v_add_u32_e32 v224, v224, v242
	v_add_u32_e32 v228, v228, v242
	ds_read_b128 v[82:85], v147
	global_load_dwordx4 v[200:203], v200, s[6:7]
	ds_read_b128 v[86:89], v147 offset:1088
	global_load_dwordx4 v[204:207], v204, s[6:7]
	ds_read_b128 v[90:93], v147 offset:2176
	global_load_dwordx4 v[208:211], v208, s[6:7]
	ds_read_b128 v[94:97], v147 offset:3264
	global_load_dwordx4 v[212:215], v212, s[6:7]
	ds_read_b128 v[66:69], v147 offset:4352
	global_load_dwordx4 v[216:219], v216, s[6:7]
	ds_read_b128 v[70:73], v147 offset:5440
	global_load_dwordx4 v[220:223], v220, s[6:7]
	ds_read_b128 v[74:77], v147 offset:6528
	global_load_dwordx4 v[224:227], v224, s[6:7]
	ds_read_b128 v[78:81], v147 offset:7616
	global_load_dwordx4 v[228:231], v228, s[6:7]
	v_lshl_add_u32 v232, v232, 11, v243
	v_lshl_add_u32 v233, v233, 11, v243
	v_lshl_add_u32 v234, v234, 11, v243
	v_lshl_add_u32 v235, v235, 11, v243
	v_lshl_add_u32 v236, v236, 11, v243
	v_lshl_add_u32 v237, v237, 11, v243
	v_lshl_add_u32 v238, v238, 11, v243
	v_lshl_add_u32 v239, v239, 11, v243
	s_waitcnt vmcnt(7) lgkmcnt(7)
	v_mul_f32_e32 v82, v82, v200
	v_mul_f32_e32 v83, v83, v201
	v_mul_f32_e32 v84, v84, v202
	v_mul_f32_e32 v85, v85, v203
	v_cvt_pk_bf16_f32 v82, v82, v83
	v_cvt_pk_bf16_f32 v83, v84, v85
	global_store_dwordx2 v232, v[82:83], s[4:5]
	s_waitcnt vmcnt(7) lgkmcnt(6)
	v_mul_f32_e32 v86, v86, v204
	v_mul_f32_e32 v87, v87, v205
	v_mul_f32_e32 v88, v88, v206
	v_mul_f32_e32 v89, v89, v207
	v_cvt_pk_bf16_f32 v86, v86, v87
	v_cvt_pk_bf16_f32 v87, v88, v89
	global_store_dwordx2 v233, v[86:87], s[4:5]
	s_waitcnt vmcnt(7) lgkmcnt(5)
	v_mul_f32_e32 v90, v90, v208
	v_mul_f32_e32 v91, v91, v209
	v_mul_f32_e32 v92, v92, v210
	v_mul_f32_e32 v93, v93, v211
	v_cvt_pk_bf16_f32 v90, v90, v91
	v_cvt_pk_bf16_f32 v91, v92, v93
	global_store_dwordx2 v234, v[90:91], s[4:5]
	s_waitcnt vmcnt(7) lgkmcnt(4)
	v_mul_f32_e32 v94, v94, v212
	v_mul_f32_e32 v95, v95, v213
	v_mul_f32_e32 v96, v96, v214
	v_mul_f32_e32 v97, v97, v215
	v_cvt_pk_bf16_f32 v94, v94, v95
	v_cvt_pk_bf16_f32 v95, v96, v97
	global_store_dwordx2 v235, v[94:95], s[4:5]
	s_waitcnt vmcnt(7) lgkmcnt(3)
	v_mul_f32_e32 v66, v66, v216
	v_mul_f32_e32 v67, v67, v217
	v_mul_f32_e32 v68, v68, v218
	v_mul_f32_e32 v69, v69, v219
	v_cvt_pk_bf16_f32 v66, v66, v67
	v_cvt_pk_bf16_f32 v67, v68, v69
	global_store_dwordx2 v236, v[66:67], s[4:5]
	s_waitcnt vmcnt(7) lgkmcnt(2)
	v_mul_f32_e32 v70, v70, v220
	v_mul_f32_e32 v71, v71, v221
	v_mul_f32_e32 v72, v72, v222
	v_mul_f32_e32 v73, v73, v223
	v_cvt_pk_bf16_f32 v70, v70, v71
	v_cvt_pk_bf16_f32 v71, v72, v73
	global_store_dwordx2 v237, v[70:71], s[4:5]
	s_waitcnt vmcnt(7) lgkmcnt(1)
	v_mul_f32_e32 v74, v74, v224
	v_mul_f32_e32 v75, v75, v225
	v_mul_f32_e32 v76, v76, v226
	v_mul_f32_e32 v77, v77, v227
	v_cvt_pk_bf16_f32 v74, v74, v75
	v_cvt_pk_bf16_f32 v75, v76, v77
	global_store_dwordx2 v238, v[74:75], s[4:5]
	s_waitcnt vmcnt(7) lgkmcnt(0)
	v_mul_f32_e32 v78, v78, v228
	v_mul_f32_e32 v79, v79, v229
	v_mul_f32_e32 v80, v80, v230
	v_mul_f32_e32 v81, v81, v231
	v_cvt_pk_bf16_f32 v78, v78, v79
	v_cvt_pk_bf16_f32 v79, v80, v81
	global_store_dwordx2 v239, v[78:79], s[4:5]
	ds_write_b128 v145, v[50:53]
	ds_write_b128 v145, v[54:57] offset:32
	ds_write_b128 v145, v[58:61] offset:64
	ds_write_b128 v145, v[62:65] offset:96
	ds_write_b128 v145, v[34:37] offset:128
	ds_write_b128 v145, v[38:41] offset:160
	ds_write_b128 v145, v[42:45] offset:192
	ds_write_b128 v145, v[46:49] offset:224
	v_add_u32_e32 v240, 0x20, v104
	v_add_u32_e32 v241, 0xfffff000, v240
	v_lshrrev_b32_e32 v241, 11, v241
	v_mad_u32_u24 v241, v241, s26, s26
	v_lshlrev_b32_e32 v241, 2, v241
	v_or_b32_e32 v232, v240, v1
	v_or_b32_e32 v233, v240, v120
	v_or_b32_e32 v234, v240, v121
	v_or_b32_e32 v235, v240, v122
	v_or_b32_e32 v236, v240, v123
	v_or_b32_e32 v237, v240, v124
	v_or_b32_e32 v238, v240, v125
	v_or_b32_e32 v239, v240, v126
	v_cmp_lt_i32_e64 s[82:83], s27, v232
	v_cmp_lt_i32_e64 s[84:85], s27, v233
	v_cmp_lt_i32_e64 s[86:87], s27, v234
	v_cmp_lt_i32_e64 s[88:89], s27, v235
	v_cmp_lt_i32_e64 s[90:91], s27, v236
	v_cmp_lt_i32_e64 s[92:93], s27, v237
	v_cmp_lt_i32_e64 s[94:95], s27, v238
	v_cmp_lt_i32_e64 s[96:97], s27, v239
	s_waitcnt lgkmcnt(0)
	v_cndmask_b32_e64 v200, 0, v241, s[82:83]
	v_cndmask_b32_e64 v204, 0, v241, s[84:85]
	v_cndmask_b32_e64 v208, 0, v241, s[86:87]
	v_cndmask_b32_e64 v212, 0, v241, s[88:89]
	v_cndmask_b32_e64 v216, 0, v241, s[90:91]
	v_cndmask_b32_e64 v220, 0, v241, s[92:93]
	v_cndmask_b32_e64 v224, 0, v241, s[94:95]
	v_cndmask_b32_e64 v228, 0, v241, s[96:97]
	v_add_u32_e32 v200, v200, v242
	v_add_u32_e32 v204, v204, v242
	v_add_u32_e32 v208, v208, v242
	v_add_u32_e32 v212, v212, v242
	v_add_u32_e32 v216, v216, v242
	v_add_u32_e32 v220, v220, v242
	v_add_u32_e32 v224, v224, v242
	v_add_u32_e32 v228, v228, v242
	ds_read_b128 v[50:53], v147
	global_load_dwordx4 v[200:203], v200, s[6:7]
	ds_read_b128 v[54:57], v147 offset:1088
	global_load_dwordx4 v[204:207], v204, s[6:7]
	ds_read_b128 v[58:61], v147 offset:2176
	global_load_dwordx4 v[208:211], v208, s[6:7]
	ds_read_b128 v[62:65], v147 offset:3264
	global_load_dwordx4 v[212:215], v212, s[6:7]
	ds_read_b128 v[34:37], v147 offset:4352
	global_load_dwordx4 v[216:219], v216, s[6:7]
	ds_read_b128 v[38:41], v147 offset:5440
	global_load_dwordx4 v[220:223], v220, s[6:7]
	ds_read_b128 v[42:45], v147 offset:6528
	global_load_dwordx4 v[224:227], v224, s[6:7]
	ds_read_b128 v[46:49], v147 offset:7616
	global_load_dwordx4 v[228:231], v228, s[6:7]
	v_lshl_add_u32 v232, v232, 11, v243
	v_lshl_add_u32 v233, v233, 11, v243
	v_lshl_add_u32 v234, v234, 11, v243
	v_lshl_add_u32 v235, v235, 11, v243
	v_lshl_add_u32 v236, v236, 11, v243
	v_lshl_add_u32 v237, v237, 11, v243
	v_lshl_add_u32 v238, v238, 11, v243
	v_lshl_add_u32 v239, v239, 11, v243
	s_waitcnt vmcnt(7) lgkmcnt(7)
	v_mul_f32_e32 v50, v50, v200
	v_mul_f32_e32 v51, v51, v201
	v_mul_f32_e32 v52, v52, v202
	v_mul_f32_e32 v53, v53, v203
	v_cvt_pk_bf16_f32 v50, v50, v51
	v_cvt_pk_bf16_f32 v51, v52, v53
	global_store_dwordx2 v232, v[50:51], s[4:5]
	s_waitcnt vmcnt(7) lgkmcnt(6)
	v_mul_f32_e32 v54, v54, v204
	v_mul_f32_e32 v55, v55, v205
	v_mul_f32_e32 v56, v56, v206
	v_mul_f32_e32 v57, v57, v207
	v_cvt_pk_bf16_f32 v54, v54, v55
	v_cvt_pk_bf16_f32 v55, v56, v57
	global_store_dwordx2 v233, v[54:55], s[4:5]
	s_waitcnt vmcnt(7) lgkmcnt(5)
	v_mul_f32_e32 v58, v58, v208
	v_mul_f32_e32 v59, v59, v209
	v_mul_f32_e32 v60, v60, v210
	v_mul_f32_e32 v61, v61, v211
	v_cvt_pk_bf16_f32 v58, v58, v59
	v_cvt_pk_bf16_f32 v59, v60, v61
	global_store_dwordx2 v234, v[58:59], s[4:5]
	s_waitcnt vmcnt(7) lgkmcnt(4)
	v_mul_f32_e32 v62, v62, v212
	v_mul_f32_e32 v63, v63, v213
	v_mul_f32_e32 v64, v64, v214
	v_mul_f32_e32 v65, v65, v215
	v_cvt_pk_bf16_f32 v62, v62, v63
	v_cvt_pk_bf16_f32 v63, v64, v65
	global_store_dwordx2 v235, v[62:63], s[4:5]
	s_waitcnt vmcnt(7) lgkmcnt(3)
	v_mul_f32_e32 v34, v34, v216
	v_mul_f32_e32 v35, v35, v217
	v_mul_f32_e32 v36, v36, v218
	v_mul_f32_e32 v37, v37, v219
	v_cvt_pk_bf16_f32 v34, v34, v35
	v_cvt_pk_bf16_f32 v35, v36, v37
	global_store_dwordx2 v236, v[34:35], s[4:5]
	s_waitcnt vmcnt(7) lgkmcnt(2)
	v_mul_f32_e32 v38, v38, v220
	v_mul_f32_e32 v39, v39, v221
	v_mul_f32_e32 v40, v40, v222
	v_mul_f32_e32 v41, v41, v223
	v_cvt_pk_bf16_f32 v38, v38, v39
	v_cvt_pk_bf16_f32 v39, v40, v41
	global_store_dwordx2 v237, v[38:39], s[4:5]
	s_waitcnt vmcnt(7) lgkmcnt(1)
	v_mul_f32_e32 v42, v42, v224
	v_mul_f32_e32 v43, v43, v225
	v_mul_f32_e32 v44, v44, v226
	v_mul_f32_e32 v45, v45, v227
	v_cvt_pk_bf16_f32 v42, v42, v43
	v_cvt_pk_bf16_f32 v43, v44, v45
	global_store_dwordx2 v238, v[42:43], s[4:5]
	s_waitcnt vmcnt(7) lgkmcnt(0)
	v_mul_f32_e32 v46, v46, v228
	v_mul_f32_e32 v47, v47, v229
	v_mul_f32_e32 v48, v48, v230
	v_mul_f32_e32 v49, v49, v231
	v_cvt_pk_bf16_f32 v46, v46, v47
	v_cvt_pk_bf16_f32 v47, v48, v49
	global_store_dwordx2 v239, v[46:47], s[4:5]
	ds_write_b128 v145, v[18:21]
	ds_write_b128 v145, v[22:25] offset:32
	ds_write_b128 v145, v[26:29] offset:64
	ds_write_b128 v145, v[30:33] offset:96
	ds_write_b128 v145, v[2:5] offset:128
	ds_write_b128 v145, v[6:9] offset:160
	ds_write_b128 v145, v[10:13] offset:192
	ds_write_b128 v145, v[14:17] offset:224
	v_add_u32_e32 v240, 0x40, v104
	v_add_u32_e32 v241, 0xfffff000, v240
	v_lshrrev_b32_e32 v241, 11, v241
	v_mad_u32_u24 v241, v241, s26, s26
	v_lshlrev_b32_e32 v241, 2, v241
	v_or_b32_e32 v232, v240, v1
	v_or_b32_e32 v233, v240, v120
	v_or_b32_e32 v234, v240, v121
	v_or_b32_e32 v235, v240, v122
	v_or_b32_e32 v236, v240, v123
	v_or_b32_e32 v237, v240, v124
	v_or_b32_e32 v238, v240, v125
	v_or_b32_e32 v239, v240, v126
	v_cmp_lt_i32_e64 s[82:83], s27, v232
	v_cmp_lt_i32_e64 s[84:85], s27, v233
	v_cmp_lt_i32_e64 s[86:87], s27, v234
	v_cmp_lt_i32_e64 s[88:89], s27, v235
	v_cmp_lt_i32_e64 s[90:91], s27, v236
	v_cmp_lt_i32_e64 s[92:93], s27, v237
	v_cmp_lt_i32_e64 s[94:95], s27, v238
	v_cmp_lt_i32_e64 s[96:97], s27, v239
	s_waitcnt lgkmcnt(0)
	v_cndmask_b32_e64 v200, 0, v241, s[82:83]
	v_cndmask_b32_e64 v204, 0, v241, s[84:85]
	v_cndmask_b32_e64 v208, 0, v241, s[86:87]
	v_cndmask_b32_e64 v212, 0, v241, s[88:89]
	v_cndmask_b32_e64 v216, 0, v241, s[90:91]
	v_cndmask_b32_e64 v220, 0, v241, s[92:93]
	v_cndmask_b32_e64 v224, 0, v241, s[94:95]
	v_cndmask_b32_e64 v228, 0, v241, s[96:97]
	v_add_u32_e32 v200, v200, v242
	v_add_u32_e32 v204, v204, v242
	v_add_u32_e32 v208, v208, v242
	v_add_u32_e32 v212, v212, v242
	v_add_u32_e32 v216, v216, v242
	v_add_u32_e32 v220, v220, v242
	v_add_u32_e32 v224, v224, v242
	v_add_u32_e32 v228, v228, v242
	ds_read_b128 v[18:21], v147
	global_load_dwordx4 v[200:203], v200, s[6:7]
	ds_read_b128 v[22:25], v147 offset:1088
	global_load_dwordx4 v[204:207], v204, s[6:7]
	ds_read_b128 v[26:29], v147 offset:2176
	global_load_dwordx4 v[208:211], v208, s[6:7]
	ds_read_b128 v[30:33], v147 offset:3264
	global_load_dwordx4 v[212:215], v212, s[6:7]
	ds_read_b128 v[2:5], v147 offset:4352
	global_load_dwordx4 v[216:219], v216, s[6:7]
	ds_read_b128 v[6:9], v147 offset:5440
	global_load_dwordx4 v[220:223], v220, s[6:7]
	ds_read_b128 v[10:13], v147 offset:6528
	global_load_dwordx4 v[224:227], v224, s[6:7]
	ds_read_b128 v[14:17], v147 offset:7616
	global_load_dwordx4 v[228:231], v228, s[6:7]
	v_lshl_add_u32 v232, v232, 11, v243
	v_lshl_add_u32 v233, v233, 11, v243
	v_lshl_add_u32 v234, v234, 11, v243
	v_lshl_add_u32 v235, v235, 11, v243
	v_lshl_add_u32 v236, v236, 11, v243
	v_lshl_add_u32 v237, v237, 11, v243
	v_lshl_add_u32 v238, v238, 11, v243
	v_lshl_add_u32 v239, v239, 11, v243
	s_waitcnt vmcnt(7) lgkmcnt(7)
	v_mul_f32_e32 v18, v18, v200
	v_mul_f32_e32 v19, v19, v201
	v_mul_f32_e32 v20, v20, v202
	v_mul_f32_e32 v21, v21, v203
	v_cvt_pk_bf16_f32 v18, v18, v19
	v_cvt_pk_bf16_f32 v19, v20, v21
	global_store_dwordx2 v232, v[18:19], s[4:5]
	s_waitcnt vmcnt(7) lgkmcnt(6)
	v_mul_f32_e32 v22, v22, v204
	v_mul_f32_e32 v23, v23, v205
	v_mul_f32_e32 v24, v24, v206
	v_mul_f32_e32 v25, v25, v207
	v_cvt_pk_bf16_f32 v22, v22, v23
	v_cvt_pk_bf16_f32 v23, v24, v25
	global_store_dwordx2 v233, v[22:23], s[4:5]
	s_waitcnt vmcnt(7) lgkmcnt(5)
	v_mul_f32_e32 v26, v26, v208
	v_mul_f32_e32 v27, v27, v209
	v_mul_f32_e32 v28, v28, v210
	v_mul_f32_e32 v29, v29, v211
	v_cvt_pk_bf16_f32 v26, v26, v27
	v_cvt_pk_bf16_f32 v27, v28, v29
	global_store_dwordx2 v234, v[26:27], s[4:5]
	s_waitcnt vmcnt(7) lgkmcnt(4)
	v_mul_f32_e32 v30, v30, v212
	v_mul_f32_e32 v31, v31, v213
	v_mul_f32_e32 v32, v32, v214
	v_mul_f32_e32 v33, v33, v215
	v_cvt_pk_bf16_f32 v30, v30, v31
	v_cvt_pk_bf16_f32 v31, v32, v33
	global_store_dwordx2 v235, v[30:31], s[4:5]
	s_waitcnt vmcnt(7) lgkmcnt(3)
	v_mul_f32_e32 v2, v2, v216
	v_mul_f32_e32 v3, v3, v217
	v_mul_f32_e32 v4, v4, v218
	v_mul_f32_e32 v5, v5, v219
	v_cvt_pk_bf16_f32 v2, v2, v3
	v_cvt_pk_bf16_f32 v3, v4, v5
	global_store_dwordx2 v236, v[2:3], s[4:5]
	s_waitcnt vmcnt(7) lgkmcnt(2)
	v_mul_f32_e32 v6, v6, v220
	v_mul_f32_e32 v7, v7, v221
	v_mul_f32_e32 v8, v8, v222
	v_mul_f32_e32 v9, v9, v223
	v_cvt_pk_bf16_f32 v6, v6, v7
	v_cvt_pk_bf16_f32 v7, v8, v9
	global_store_dwordx2 v237, v[6:7], s[4:5]
	s_waitcnt vmcnt(7) lgkmcnt(1)
	v_mul_f32_e32 v10, v10, v224
	v_mul_f32_e32 v11, v11, v225
	v_mul_f32_e32 v12, v12, v226
	v_mul_f32_e32 v13, v13, v227
	v_cvt_pk_bf16_f32 v10, v10, v11
	v_cvt_pk_bf16_f32 v11, v12, v13
	global_store_dwordx2 v238, v[10:11], s[4:5]
	s_waitcnt vmcnt(7) lgkmcnt(0)
	v_mul_f32_e32 v14, v14, v228
	v_mul_f32_e32 v15, v15, v229
	v_mul_f32_e32 v16, v16, v230
	v_mul_f32_e32 v17, v17, v231
	v_cvt_pk_bf16_f32 v14, v14, v15
	v_cvt_pk_bf16_f32 v15, v16, v17
	global_store_dwordx2 v239, v[14:15], s[4:5]
	s_waitcnt lgkmcnt(0)
	s_load_dword s10, s[8:9], 0x0
	s_waitcnt lgkmcnt(0)
	s_add_i32 s2, s10, s2
	s_cmpk_lt_i32 s2, 0x200
	s_cbranch_scc1 .LBB0_2331

.LBB0_2382:
	s_or_b64 exec, exec, s[8:9]
	v_mov_b32_e32 v3, 0x2000
	v_mov_b32_e32 v5, 1
	s_waitcnt vmcnt(0)
	global_atomic_add v3, v5, s[4:5] offset:1024
	buffer_inv sc1
	s_waitcnt vmcnt(0)

.LBB0_2447:
	s_or_b64 exec, exec, s[8:9]
	v_mov_b32_e32 v1, 0x2000
	v_mov_b32_e32 v2, 1
	s_waitcnt vmcnt(0)
	global_atomic_add v1, v2, s[4:5] offset:1024
	buffer_inv sc1
	s_waitcnt vmcnt(0)
